# opt19: hand-written residual (ResNorm) epilogue with packed f32 math + row-swap reductions + branch-free ss store (replaces opt5/opt17 there); opt18 natten; opt17 on phase 7
# speedup vs baseline: 1.0021x; 1.0021x over previous
.LBB0_389:
	v_lshl_add_u32 v150, s48, 8, v131
	v_ashrrev_i32_e32 v151, 31, v150
	v_lshl_or_b32 v148, s0, 8, v153
	v_lshlrev_b64 v[160:161], 11, v[150:151]
	v_ashrrev_i32_e32 v149, 31, v148
	v_lshl_add_u64 v[160:161], s[14:15], 0, v[160:161]
	v_lshl_add_u64 v[164:165], v[148:149], 1, v[160:161]
	v_mov_b32_e32 v232, v164
	v_mov_b32_e32 v233, v165
	global_load_dwordx4 v[188:191], v[232:233], off
	global_load_dwordx4 v[192:195], v[232:233], off offset:256
	s_mov_b64 s[100:101], 0x8000
	v_lshl_add_u64 v[230:231], v[232:233], 0, s[100:101]
	global_load_dwordx4 v[196:199], v[230:231], off
	global_load_dwordx4 v[200:203], v[230:231], off offset:256
	s_mov_b64 s[100:101], 0x10000
	v_lshl_add_u64 v[230:231], v[232:233], 0, s[100:101]
	global_load_dwordx4 v[204:207], v[230:231], off
	global_load_dwordx4 v[208:211], v[230:231], off offset:256
	s_mov_b64 s[100:101], 0x18000
	v_lshl_add_u64 v[230:231], v[232:233], 0, s[100:101]
	global_load_dwordx4 v[212:215], v[230:231], off
	global_load_dwordx4 v[216:219], v[230:231], off offset:256
	s_lshl_b32 s48, s0, 2
	s_ashr_i32 s49, s48, 31
	v_lshlrev_b64 v[234:235], 6, v[150:151]
	v_lshl_add_u64 v[234:235], s[18:19], 0, v[234:235]
	v_lshl_add_u64 v[234:235], s[48:49], 2, v[234:235]
	s_lshl_b32 s100, s64, 2
	s_mov_b32 s101, 0
	v_lshl_add_u64 v[234:235], v[234:235], 0, s[100:101]
	s_mov_b64 s[100:101], 0x2000
	v_lshl_add_u64 v[236:237], v[234:235], 0, s[100:101]
	s_waitcnt vmcnt(7)
	v_lshlrev_b32_e32 v166, 16, v188
	v_and_b32_e32 v167, 0xffff0000, v188
	v_lshlrev_b32_e32 v168, 16, v189
	v_and_b32_e32 v169, 0xffff0000, v189
	v_lshlrev_b32_e32 v170, 16, v190
	v_and_b32_e32 v171, 0xffff0000, v190
	v_lshlrev_b32_e32 v172, 16, v191
	v_and_b32_e32 v173, 0xffff0000, v191
	v_pk_add_f32 v[124:125], v[124:125], v[166:167]
	v_pk_add_f32 v[126:127], v[126:127], v[168:169]
	v_pk_add_f32 v[120:121], v[120:121], v[170:171]
	v_pk_add_f32 v[122:123], v[122:123], v[172:173]
	v_cvt_pk_bf16_f32 v174, v124, v125
	v_cvt_pk_bf16_f32 v175, v126, v127
	v_cvt_pk_bf16_f32 v176, v120, v121
	v_cvt_pk_bf16_f32 v177, v122, v123
	v_pk_mul_f32 v[182:183], v[124:125], v[124:125]
	v_pk_fma_f32 v[182:183], v[126:127], v[126:127], v[182:183]
	v_pk_fma_f32 v[182:183], v[120:121], v[120:121], v[182:183]
	v_pk_fma_f32 v[182:183], v[122:123], v[122:123], v[182:183]
	global_store_dwordx4 v[232:233], v[174:177], off
	s_waitcnt vmcnt(7)
	v_lshlrev_b32_e32 v166, 16, v192
	v_and_b32_e32 v167, 0xffff0000, v192
	v_lshlrev_b32_e32 v168, 16, v193
	v_and_b32_e32 v169, 0xffff0000, v193
	v_lshlrev_b32_e32 v170, 16, v194
	v_and_b32_e32 v171, 0xffff0000, v194
	v_lshlrev_b32_e32 v172, 16, v195
	v_and_b32_e32 v173, 0xffff0000, v195
	v_pk_add_f32 v[116:117], v[116:117], v[166:167]
	v_pk_add_f32 v[118:119], v[118:119], v[168:169]
	v_pk_add_f32 v[112:113], v[112:113], v[170:171]
	v_pk_add_f32 v[114:115], v[114:115], v[172:173]
	v_cvt_pk_bf16_f32 v178, v116, v117
	v_cvt_pk_bf16_f32 v179, v118, v119
	v_cvt_pk_bf16_f32 v180, v112, v113
	v_cvt_pk_bf16_f32 v181, v114, v115
	v_pk_fma_f32 v[182:183], v[116:117], v[116:117], v[182:183]
	v_pk_fma_f32 v[182:183], v[118:119], v[118:119], v[182:183]
	v_pk_fma_f32 v[182:183], v[112:113], v[112:113], v[182:183]
	v_pk_fma_f32 v[182:183], v[114:115], v[114:115], v[182:183]
	global_store_dwordx4 v[232:233], v[178:181], off offset:256
	v_add_f32_e32 v184, v182, v183
	v_mov_b32_e32 v185, v184
	s_nop 1
	v_permlane16_swap_b32_e32 v185, v184
	v_add_f32_e32 v184, v184, v185
	v_mov_b32_e32 v185, v184
	s_nop 1
	v_permlane32_swap_b32_e32 v185, v184
	v_add_f32_e32 v184, v184, v185
	s_and_saveexec_b64 s[50:51], s[4:5]
	global_store_dword v[234:235], v184, off
	s_or_b64 exec, exec, s[50:51]
	s_mov_b64 s[100:101], 0x40000
	v_lshl_add_u64 v[230:231], v[232:233], 0, s[100:101]
	global_load_dwordx4 v[188:191], v[230:231], off
	global_load_dwordx4 v[192:195], v[230:231], off offset:256
	s_mov_b64 s[100:101], 0x8000
	v_lshl_add_u64 v[186:187], v[232:233], 0, s[100:101]
	s_waitcnt vmcnt(10)
	v_lshlrev_b32_e32 v166, 16, v196
	v_and_b32_e32 v167, 0xffff0000, v196
	v_lshlrev_b32_e32 v168, 16, v197
	v_and_b32_e32 v169, 0xffff0000, v197
	v_lshlrev_b32_e32 v170, 16, v198
	v_and_b32_e32 v171, 0xffff0000, v198
	v_lshlrev_b32_e32 v172, 16, v199
	v_and_b32_e32 v173, 0xffff0000, v199
	v_pk_add_f32 v[108:109], v[108:109], v[166:167]
	v_pk_add_f32 v[110:111], v[110:111], v[168:169]
	v_pk_add_f32 v[104:105], v[104:105], v[170:171]
	v_pk_add_f32 v[106:107], v[106:107], v[172:173]
	v_cvt_pk_bf16_f32 v174, v108, v109
	v_cvt_pk_bf16_f32 v175, v110, v111
	v_cvt_pk_bf16_f32 v176, v104, v105
	v_cvt_pk_bf16_f32 v177, v106, v107
	v_pk_mul_f32 v[182:183], v[108:109], v[108:109]
	v_pk_fma_f32 v[182:183], v[110:111], v[110:111], v[182:183]
	v_pk_fma_f32 v[182:183], v[104:105], v[104:105], v[182:183]
	v_pk_fma_f32 v[182:183], v[106:107], v[106:107], v[182:183]
	global_store_dwordx4 v[186:187], v[174:177], off
	s_waitcnt vmcnt(10)
	v_lshlrev_b32_e32 v166, 16, v200
	v_and_b32_e32 v167, 0xffff0000, v200
	v_lshlrev_b32_e32 v168, 16, v201
	v_and_b32_e32 v169, 0xffff0000, v201
	v_lshlrev_b32_e32 v170, 16, v202
	v_and_b32_e32 v171, 0xffff0000, v202
	v_lshlrev_b32_e32 v172, 16, v203
	v_and_b32_e32 v173, 0xffff0000, v203
	v_pk_add_f32 v[100:101], v[100:101], v[166:167]
	v_pk_add_f32 v[102:103], v[102:103], v[168:169]
	v_pk_add_f32 v[96:97], v[96:97], v[170:171]
	v_pk_add_f32 v[98:99], v[98:99], v[172:173]
	v_cvt_pk_bf16_f32 v178, v100, v101
	v_cvt_pk_bf16_f32 v179, v102, v103
	v_cvt_pk_bf16_f32 v180, v96, v97
	v_cvt_pk_bf16_f32 v181, v98, v99
	v_pk_fma_f32 v[182:183], v[100:101], v[100:101], v[182:183]
	v_pk_fma_f32 v[182:183], v[102:103], v[102:103], v[182:183]
	v_pk_fma_f32 v[182:183], v[96:97], v[96:97], v[182:183]
	v_pk_fma_f32 v[182:183], v[98:99], v[98:99], v[182:183]
	global_store_dwordx4 v[186:187], v[178:181], off offset:256
	v_add_f32_e32 v184, v182, v183
	v_mov_b32_e32 v185, v184
	s_nop 1
	v_permlane16_swap_b32_e32 v185, v184
	v_add_f32_e32 v184, v184, v185
	v_mov_b32_e32 v185, v184
	s_nop 1
	v_permlane32_swap_b32_e32 v185, v184
	v_add_f32_e32 v184, v184, v185
	s_and_saveexec_b64 s[50:51], s[4:5]
	global_store_dword v[234:235], v184, off offset:1024
	s_or_b64 exec, exec, s[50:51]
	s_mov_b64 s[100:101], 0x48000
	v_lshl_add_u64 v[230:231], v[232:233], 0, s[100:101]
	global_load_dwordx4 v[196:199], v[230:231], off
	global_load_dwordx4 v[200:203], v[230:231], off offset:256
	s_mov_b64 s[100:101], 0x10000
	v_lshl_add_u64 v[186:187], v[232:233], 0, s[100:101]
	s_waitcnt vmcnt(13)
	v_lshlrev_b32_e32 v166, 16, v204
	v_and_b32_e32 v167, 0xffff0000, v204
	v_lshlrev_b32_e32 v168, 16, v205
	v_and_b32_e32 v169, 0xffff0000, v205
	v_lshlrev_b32_e32 v170, 16, v206
	v_and_b32_e32 v171, 0xffff0000, v206
	v_lshlrev_b32_e32 v172, 16, v207
	v_and_b32_e32 v173, 0xffff0000, v207
	v_pk_add_f32 v[92:93], v[92:93], v[166:167]
	v_pk_add_f32 v[94:95], v[94:95], v[168:169]
	v_pk_add_f32 v[88:89], v[88:89], v[170:171]
	v_pk_add_f32 v[90:91], v[90:91], v[172:173]
	v_cvt_pk_bf16_f32 v174, v92, v93
	v_cvt_pk_bf16_f32 v175, v94, v95
	v_cvt_pk_bf16_f32 v176, v88, v89
	v_cvt_pk_bf16_f32 v177, v90, v91
	v_pk_mul_f32 v[182:183], v[92:93], v[92:93]
	v_pk_fma_f32 v[182:183], v[94:95], v[94:95], v[182:183]
	v_pk_fma_f32 v[182:183], v[88:89], v[88:89], v[182:183]
	v_pk_fma_f32 v[182:183], v[90:91], v[90:91], v[182:183]
	global_store_dwordx4 v[186:187], v[174:177], off
	s_waitcnt vmcnt(13)
	v_lshlrev_b32_e32 v166, 16, v208
	v_and_b32_e32 v167, 0xffff0000, v208
	v_lshlrev_b32_e32 v168, 16, v209
	v_and_b32_e32 v169, 0xffff0000, v209
	v_lshlrev_b32_e32 v170, 16, v210
	v_and_b32_e32 v171, 0xffff0000, v210
	v_lshlrev_b32_e32 v172, 16, v211
	v_and_b32_e32 v173, 0xffff0000, v211
	v_pk_add_f32 v[84:85], v[84:85], v[166:167]
	v_pk_add_f32 v[86:87], v[86:87], v[168:169]
	v_pk_add_f32 v[80:81], v[80:81], v[170:171]
	v_pk_add_f32 v[82:83], v[82:83], v[172:173]
	v_cvt_pk_bf16_f32 v178, v84, v85
	v_cvt_pk_bf16_f32 v179, v86, v87
	v_cvt_pk_bf16_f32 v180, v80, v81
	v_cvt_pk_bf16_f32 v181, v82, v83
	v_pk_fma_f32 v[182:183], v[84:85], v[84:85], v[182:183]
	v_pk_fma_f32 v[182:183], v[86:87], v[86:87], v[182:183]
	v_pk_fma_f32 v[182:183], v[80:81], v[80:81], v[182:183]
	v_pk_fma_f32 v[182:183], v[82:83], v[82:83], v[182:183]
	global_store_dwordx4 v[186:187], v[178:181], off offset:256
	v_add_f32_e32 v184, v182, v183
	v_mov_b32_e32 v185, v184
	s_nop 1
	v_permlane16_swap_b32_e32 v185, v184
	v_add_f32_e32 v184, v184, v185
	v_mov_b32_e32 v185, v184
	s_nop 1
	v_permlane32_swap_b32_e32 v185, v184
	v_add_f32_e32 v184, v184, v185
	s_and_saveexec_b64 s[50:51], s[4:5]
	global_store_dword v[234:235], v184, off offset:2048
	s_or_b64 exec, exec, s[50:51]
	s_mov_b64 s[100:101], 0x50000
	v_lshl_add_u64 v[230:231], v[232:233], 0, s[100:101]
	global_load_dwordx4 v[204:207], v[230:231], off
	global_load_dwordx4 v[208:211], v[230:231], off offset:256
	s_mov_b64 s[100:101], 0x18000
	v_lshl_add_u64 v[186:187], v[232:233], 0, s[100:101]
	s_waitcnt vmcnt(16)
	v_lshlrev_b32_e32 v166, 16, v212
	v_and_b32_e32 v167, 0xffff0000, v212
	v_lshlrev_b32_e32 v168, 16, v213
	v_and_b32_e32 v169, 0xffff0000, v213
	v_lshlrev_b32_e32 v170, 16, v214
	v_and_b32_e32 v171, 0xffff0000, v214
	v_lshlrev_b32_e32 v172, 16, v215
	v_and_b32_e32 v173, 0xffff0000, v215
	v_pk_add_f32 v[76:77], v[76:77], v[166:167]
	v_pk_add_f32 v[78:79], v[78:79], v[168:169]
	v_pk_add_f32 v[72:73], v[72:73], v[170:171]
	v_pk_add_f32 v[74:75], v[74:75], v[172:173]
	v_cvt_pk_bf16_f32 v174, v76, v77
	v_cvt_pk_bf16_f32 v175, v78, v79
	v_cvt_pk_bf16_f32 v176, v72, v73
	v_cvt_pk_bf16_f32 v177, v74, v75
	v_pk_mul_f32 v[182:183], v[76:77], v[76:77]
	v_pk_fma_f32 v[182:183], v[78:79], v[78:79], v[182:183]
	v_pk_fma_f32 v[182:183], v[72:73], v[72:73], v[182:183]
	v_pk_fma_f32 v[182:183], v[74:75], v[74:75], v[182:183]
	global_store_dwordx4 v[186:187], v[174:177], off
	s_waitcnt vmcnt(16)
	v_lshlrev_b32_e32 v166, 16, v216
	v_and_b32_e32 v167, 0xffff0000, v216
	v_lshlrev_b32_e32 v168, 16, v217
	v_and_b32_e32 v169, 0xffff0000, v217
	v_lshlrev_b32_e32 v170, 16, v218
	v_and_b32_e32 v171, 0xffff0000, v218
	v_lshlrev_b32_e32 v172, 16, v219
	v_and_b32_e32 v173, 0xffff0000, v219
	v_pk_add_f32 v[68:69], v[68:69], v[166:167]
	v_pk_add_f32 v[70:71], v[70:71], v[168:169]
	v_pk_add_f32 v[64:65], v[64:65], v[170:171]
	v_pk_add_f32 v[66:67], v[66:67], v[172:173]
	v_cvt_pk_bf16_f32 v178, v68, v69
	v_cvt_pk_bf16_f32 v179, v70, v71
	v_cvt_pk_bf16_f32 v180, v64, v65
	v_cvt_pk_bf16_f32 v181, v66, v67
	v_pk_fma_f32 v[182:183], v[68:69], v[68:69], v[182:183]
	v_pk_fma_f32 v[182:183], v[70:71], v[70:71], v[182:183]
	v_pk_fma_f32 v[182:183], v[64:65], v[64:65], v[182:183]
	v_pk_fma_f32 v[182:183], v[66:67], v[66:67], v[182:183]
	global_store_dwordx4 v[186:187], v[178:181], off offset:256
	v_add_f32_e32 v184, v182, v183
	v_mov_b32_e32 v185, v184
	s_nop 1
	v_permlane16_swap_b32_e32 v185, v184
	v_add_f32_e32 v184, v184, v185
	v_mov_b32_e32 v185, v184
	s_nop 1
	v_permlane32_swap_b32_e32 v185, v184
	v_add_f32_e32 v184, v184, v185
	s_and_saveexec_b64 s[50:51], s[4:5]
	global_store_dword v[234:235], v184, off offset:3072
	s_or_b64 exec, exec, s[50:51]
	s_mov_b64 s[100:101], 0x58000
	v_lshl_add_u64 v[230:231], v[232:233], 0, s[100:101]
	global_load_dwordx4 v[212:215], v[230:231], off
	global_load_dwordx4 v[216:219], v[230:231], off offset:256
	s_mov_b64 s[100:101], 0x40000
	v_lshl_add_u64 v[186:187], v[232:233], 0, s[100:101]
	s_waitcnt vmcnt(16)
	v_lshlrev_b32_e32 v166, 16, v188
	v_and_b32_e32 v167, 0xffff0000, v188
	v_lshlrev_b32_e32 v168, 16, v189
	v_and_b32_e32 v169, 0xffff0000, v189
	v_lshlrev_b32_e32 v170, 16, v190
	v_and_b32_e32 v171, 0xffff0000, v190
	v_lshlrev_b32_e32 v172, 16, v191
	v_and_b32_e32 v173, 0xffff0000, v191
	v_pk_add_f32 v[60:61], v[60:61], v[166:167]
	v_pk_add_f32 v[62:63], v[62:63], v[168:169]
	v_pk_add_f32 v[56:57], v[56:57], v[170:171]
	v_pk_add_f32 v[58:59], v[58:59], v[172:173]
	v_cvt_pk_bf16_f32 v174, v60, v61
	v_cvt_pk_bf16_f32 v175, v62, v63
	v_cvt_pk_bf16_f32 v176, v56, v57
	v_cvt_pk_bf16_f32 v177, v58, v59
	v_pk_mul_f32 v[182:183], v[60:61], v[60:61]
	v_pk_fma_f32 v[182:183], v[62:63], v[62:63], v[182:183]
	v_pk_fma_f32 v[182:183], v[56:57], v[56:57], v[182:183]
	v_pk_fma_f32 v[182:183], v[58:59], v[58:59], v[182:183]
	global_store_dwordx4 v[186:187], v[174:177], off
	s_waitcnt vmcnt(16)
	v_lshlrev_b32_e32 v166, 16, v192
	v_and_b32_e32 v167, 0xffff0000, v192
	v_lshlrev_b32_e32 v168, 16, v193
	v_and_b32_e32 v169, 0xffff0000, v193
	v_lshlrev_b32_e32 v170, 16, v194
	v_and_b32_e32 v171, 0xffff0000, v194
	v_lshlrev_b32_e32 v172, 16, v195
	v_and_b32_e32 v173, 0xffff0000, v195
	v_pk_add_f32 v[52:53], v[52:53], v[166:167]
	v_pk_add_f32 v[54:55], v[54:55], v[168:169]
	v_pk_add_f32 v[48:49], v[48:49], v[170:171]
	v_pk_add_f32 v[50:51], v[50:51], v[172:173]
	v_cvt_pk_bf16_f32 v178, v52, v53
	v_cvt_pk_bf16_f32 v179, v54, v55
	v_cvt_pk_bf16_f32 v180, v48, v49
	v_cvt_pk_bf16_f32 v181, v50, v51
	v_pk_fma_f32 v[182:183], v[52:53], v[52:53], v[182:183]
	v_pk_fma_f32 v[182:183], v[54:55], v[54:55], v[182:183]
	v_pk_fma_f32 v[182:183], v[48:49], v[48:49], v[182:183]
	v_pk_fma_f32 v[182:183], v[50:51], v[50:51], v[182:183]
	global_store_dwordx4 v[186:187], v[178:181], off offset:256
	v_add_f32_e32 v184, v182, v183
	v_mov_b32_e32 v185, v184
	s_nop 1
	v_permlane16_swap_b32_e32 v185, v184
	v_add_f32_e32 v184, v184, v185
	v_mov_b32_e32 v185, v184
	s_nop 1
	v_permlane32_swap_b32_e32 v185, v184
	v_add_f32_e32 v184, v184, v185
	s_and_saveexec_b64 s[50:51], s[4:5]
	global_store_dword v[236:237], v184, off
	s_or_b64 exec, exec, s[50:51]
	s_mov_b64 s[100:101], 0x48000
	v_lshl_add_u64 v[186:187], v[232:233], 0, s[100:101]
	s_waitcnt vmcnt(14)
	v_lshlrev_b32_e32 v166, 16, v196
	v_and_b32_e32 v167, 0xffff0000, v196
	v_lshlrev_b32_e32 v168, 16, v197
	v_and_b32_e32 v169, 0xffff0000, v197
	v_lshlrev_b32_e32 v170, 16, v198
	v_and_b32_e32 v171, 0xffff0000, v198
	v_lshlrev_b32_e32 v172, 16, v199
	v_and_b32_e32 v173, 0xffff0000, v199
	v_pk_add_f32 v[44:45], v[44:45], v[166:167]
	v_pk_add_f32 v[46:47], v[46:47], v[168:169]
	v_pk_add_f32 v[40:41], v[40:41], v[170:171]
	v_pk_add_f32 v[42:43], v[42:43], v[172:173]
	v_cvt_pk_bf16_f32 v174, v44, v45
	v_cvt_pk_bf16_f32 v175, v46, v47
	v_cvt_pk_bf16_f32 v176, v40, v41
	v_cvt_pk_bf16_f32 v177, v42, v43
	v_pk_mul_f32 v[182:183], v[44:45], v[44:45]
	v_pk_fma_f32 v[182:183], v[46:47], v[46:47], v[182:183]
	v_pk_fma_f32 v[182:183], v[40:41], v[40:41], v[182:183]
	v_pk_fma_f32 v[182:183], v[42:43], v[42:43], v[182:183]
	global_store_dwordx4 v[186:187], v[174:177], off
	s_waitcnt vmcnt(14)
	v_lshlrev_b32_e32 v166, 16, v200
	v_and_b32_e32 v167, 0xffff0000, v200
	v_lshlrev_b32_e32 v168, 16, v201
	v_and_b32_e32 v169, 0xffff0000, v201
	v_lshlrev_b32_e32 v170, 16, v202
	v_and_b32_e32 v171, 0xffff0000, v202
	v_lshlrev_b32_e32 v172, 16, v203
	v_and_b32_e32 v173, 0xffff0000, v203
	v_pk_add_f32 v[36:37], v[36:37], v[166:167]
	v_pk_add_f32 v[38:39], v[38:39], v[168:169]
	v_pk_add_f32 v[32:33], v[32:33], v[170:171]
	v_pk_add_f32 v[34:35], v[34:35], v[172:173]
	v_cvt_pk_bf16_f32 v178, v36, v37
	v_cvt_pk_bf16_f32 v179, v38, v39
	v_cvt_pk_bf16_f32 v180, v32, v33
	v_cvt_pk_bf16_f32 v181, v34, v35
	v_pk_fma_f32 v[182:183], v[36:37], v[36:37], v[182:183]
	v_pk_fma_f32 v[182:183], v[38:39], v[38:39], v[182:183]
	v_pk_fma_f32 v[182:183], v[32:33], v[32:33], v[182:183]
	v_pk_fma_f32 v[182:183], v[34:35], v[34:35], v[182:183]
	global_store_dwordx4 v[186:187], v[178:181], off offset:256
	v_add_f32_e32 v184, v182, v183
	v_mov_b32_e32 v185, v184
	s_nop 1
	v_permlane16_swap_b32_e32 v185, v184
	v_add_f32_e32 v184, v184, v185
	v_mov_b32_e32 v185, v184
	s_nop 1
	v_permlane32_swap_b32_e32 v185, v184
	v_add_f32_e32 v184, v184, v185
	s_and_saveexec_b64 s[50:51], s[4:5]
	global_store_dword v[236:237], v184, off offset:1024
	s_or_b64 exec, exec, s[50:51]
	s_mov_b64 s[100:101], 0x50000
	v_lshl_add_u64 v[186:187], v[232:233], 0, s[100:101]
	s_waitcnt vmcnt(12)
	v_lshlrev_b32_e32 v166, 16, v204
	v_and_b32_e32 v167, 0xffff0000, v204
	v_lshlrev_b32_e32 v168, 16, v205
	v_and_b32_e32 v169, 0xffff0000, v205
	v_lshlrev_b32_e32 v170, 16, v206
	v_and_b32_e32 v171, 0xffff0000, v206
	v_lshlrev_b32_e32 v172, 16, v207
	v_and_b32_e32 v173, 0xffff0000, v207
	v_pk_add_f32 v[28:29], v[28:29], v[166:167]
	v_pk_add_f32 v[30:31], v[30:31], v[168:169]
	v_pk_add_f32 v[24:25], v[24:25], v[170:171]
	v_pk_add_f32 v[26:27], v[26:27], v[172:173]
	v_cvt_pk_bf16_f32 v174, v28, v29
	v_cvt_pk_bf16_f32 v175, v30, v31
	v_cvt_pk_bf16_f32 v176, v24, v25
	v_cvt_pk_bf16_f32 v177, v26, v27
	v_pk_mul_f32 v[182:183], v[28:29], v[28:29]
	v_pk_fma_f32 v[182:183], v[30:31], v[30:31], v[182:183]
	v_pk_fma_f32 v[182:183], v[24:25], v[24:25], v[182:183]
	v_pk_fma_f32 v[182:183], v[26:27], v[26:27], v[182:183]
	global_store_dwordx4 v[186:187], v[174:177], off
	s_waitcnt vmcnt(12)
	v_lshlrev_b32_e32 v166, 16, v208
	v_and_b32_e32 v167, 0xffff0000, v208
	v_lshlrev_b32_e32 v168, 16, v209
	v_and_b32_e32 v169, 0xffff0000, v209
	v_lshlrev_b32_e32 v170, 16, v210
	v_and_b32_e32 v171, 0xffff0000, v210
	v_lshlrev_b32_e32 v172, 16, v211
	v_and_b32_e32 v173, 0xffff0000, v211
	v_pk_add_f32 v[20:21], v[20:21], v[166:167]
	v_pk_add_f32 v[22:23], v[22:23], v[168:169]
	v_pk_add_f32 v[16:17], v[16:17], v[170:171]
	v_pk_add_f32 v[18:19], v[18:19], v[172:173]
	v_cvt_pk_bf16_f32 v178, v20, v21
	v_cvt_pk_bf16_f32 v179, v22, v23
	v_cvt_pk_bf16_f32 v180, v16, v17
	v_cvt_pk_bf16_f32 v181, v18, v19
	v_pk_fma_f32 v[182:183], v[20:21], v[20:21], v[182:183]
	v_pk_fma_f32 v[182:183], v[22:23], v[22:23], v[182:183]
	v_pk_fma_f32 v[182:183], v[16:17], v[16:17], v[182:183]
	v_pk_fma_f32 v[182:183], v[18:19], v[18:19], v[182:183]
	global_store_dwordx4 v[186:187], v[178:181], off offset:256
	v_add_f32_e32 v184, v182, v183
	v_mov_b32_e32 v185, v184
	s_nop 1
	v_permlane16_swap_b32_e32 v185, v184
	v_add_f32_e32 v184, v184, v185
	v_mov_b32_e32 v185, v184
	s_nop 1
	v_permlane32_swap_b32_e32 v185, v184
	v_add_f32_e32 v184, v184, v185
	s_and_saveexec_b64 s[50:51], s[4:5]
	global_store_dword v[236:237], v184, off offset:2048
	s_or_b64 exec, exec, s[50:51]
	s_mov_b64 s[100:101], 0x58000
	v_lshl_add_u64 v[186:187], v[232:233], 0, s[100:101]
	s_waitcnt vmcnt(10)
	v_lshlrev_b32_e32 v166, 16, v212
	v_and_b32_e32 v167, 0xffff0000, v212
	v_lshlrev_b32_e32 v168, 16, v213
	v_and_b32_e32 v169, 0xffff0000, v213
	v_lshlrev_b32_e32 v170, 16, v214
	v_and_b32_e32 v171, 0xffff0000, v214
	v_lshlrev_b32_e32 v172, 16, v215
	v_and_b32_e32 v173, 0xffff0000, v215
	v_pk_add_f32 v[12:13], v[12:13], v[166:167]
	v_pk_add_f32 v[14:15], v[14:15], v[168:169]
	v_pk_add_f32 v[8:9], v[8:9], v[170:171]
	v_pk_add_f32 v[10:11], v[10:11], v[172:173]
	v_cvt_pk_bf16_f32 v174, v12, v13
	v_cvt_pk_bf16_f32 v175, v14, v15
	v_cvt_pk_bf16_f32 v176, v8, v9
	v_cvt_pk_bf16_f32 v177, v10, v11
	v_pk_mul_f32 v[182:183], v[12:13], v[12:13]
	v_pk_fma_f32 v[182:183], v[14:15], v[14:15], v[182:183]
	v_pk_fma_f32 v[182:183], v[8:9], v[8:9], v[182:183]
	v_pk_fma_f32 v[182:183], v[10:11], v[10:11], v[182:183]
	global_store_dwordx4 v[186:187], v[174:177], off
	s_waitcnt vmcnt(10)
	v_lshlrev_b32_e32 v166, 16, v216
	v_and_b32_e32 v167, 0xffff0000, v216
	v_lshlrev_b32_e32 v168, 16, v217
	v_and_b32_e32 v169, 0xffff0000, v217
	v_lshlrev_b32_e32 v170, 16, v218
	v_and_b32_e32 v171, 0xffff0000, v218
	v_lshlrev_b32_e32 v172, 16, v219
	v_and_b32_e32 v173, 0xffff0000, v219
	v_pk_add_f32 v[4:5], v[4:5], v[166:167]
	v_pk_add_f32 v[6:7], v[6:7], v[168:169]
	v_pk_add_f32 v[0:1], v[0:1], v[170:171]
	v_pk_add_f32 v[2:3], v[2:3], v[172:173]
	v_cvt_pk_bf16_f32 v178, v4, v5
	v_cvt_pk_bf16_f32 v179, v6, v7
	v_cvt_pk_bf16_f32 v180, v0, v1
	v_cvt_pk_bf16_f32 v181, v2, v3
	v_pk_fma_f32 v[182:183], v[4:5], v[4:5], v[182:183]
	v_pk_fma_f32 v[182:183], v[6:7], v[6:7], v[182:183]
	v_pk_fma_f32 v[182:183], v[0:1], v[0:1], v[182:183]
	v_pk_fma_f32 v[182:183], v[2:3], v[2:3], v[182:183]
	global_store_dwordx4 v[186:187], v[178:181], off offset:256
	v_add_f32_e32 v184, v182, v183
	v_mov_b32_e32 v185, v184
	s_nop 1
	v_permlane16_swap_b32_e32 v185, v184
	v_add_f32_e32 v184, v184, v185
	v_mov_b32_e32 v185, v184
	s_nop 1
	v_permlane32_swap_b32_e32 v185, v184
	v_add_f32_e32 v184, v184, v185
	s_and_saveexec_b64 s[50:51], s[4:5]
	global_store_dword v[236:237], v184, off offset:3072
	s_or_b64 exec, exec, s[50:51]
	s_andn2_b64 vcc, exec, s[6:7]
	s_mov_b64 s[6:7], -1
	s_cbranch_vccnz .LBB0_378
	s_andn2_b64 vcc, exec, s[8:9]
	s_cbranch_vccnz .LBB0_377
	s_nop 0
	s_branch .LBB0_377

.LBB0_565:
	v_lshl_add_u32 v150, s12, 8, v131
	v_ashrrev_i32_e32 v151, 31, v150
	v_lshl_or_b32 v148, s8, 8, v153
	v_lshlrev_b64 v[160:161], 11, v[150:151]
	v_ashrrev_i32_e32 v149, 31, v148
	v_lshl_add_u64 v[160:161], s[14:15], 0, v[160:161]
	v_lshl_add_u64 v[164:165], v[148:149], 1, v[160:161]
	v_mov_b32_e32 v232, v164
	v_mov_b32_e32 v233, v165
	global_load_dwordx4 v[188:191], v[232:233], off
	global_load_dwordx4 v[192:195], v[232:233], off offset:256
	s_mov_b64 s[100:101], 0x8000
	v_lshl_add_u64 v[230:231], v[232:233], 0, s[100:101]
	global_load_dwordx4 v[196:199], v[230:231], off
	global_load_dwordx4 v[200:203], v[230:231], off offset:256
	s_mov_b64 s[100:101], 0x10000
	v_lshl_add_u64 v[230:231], v[232:233], 0, s[100:101]
	global_load_dwordx4 v[204:207], v[230:231], off
	global_load_dwordx4 v[208:211], v[230:231], off offset:256
	s_mov_b64 s[100:101], 0x18000
	v_lshl_add_u64 v[230:231], v[232:233], 0, s[100:101]
	global_load_dwordx4 v[212:215], v[230:231], off
	global_load_dwordx4 v[216:219], v[230:231], off offset:256
	s_lshl_b32 s40, s8, 2
	s_ashr_i32 s41, s40, 31
	v_lshlrev_b64 v[234:235], 6, v[150:151]
	v_lshl_add_u64 v[234:235], s[18:19], 0, v[234:235]
	v_lshl_add_u64 v[234:235], s[40:41], 2, v[234:235]
	s_lshl_b32 s100, s56, 2
	s_mov_b32 s101, 0
	v_lshl_add_u64 v[234:235], v[234:235], 0, s[100:101]
	s_mov_b64 s[100:101], 0x2000
	v_lshl_add_u64 v[236:237], v[234:235], 0, s[100:101]
	s_waitcnt vmcnt(7)
	v_lshlrev_b32_e32 v166, 16, v188
	v_and_b32_e32 v167, 0xffff0000, v188
	v_lshlrev_b32_e32 v168, 16, v189
	v_and_b32_e32 v169, 0xffff0000, v189
	v_lshlrev_b32_e32 v170, 16, v190
	v_and_b32_e32 v171, 0xffff0000, v190
	v_lshlrev_b32_e32 v172, 16, v191
	v_and_b32_e32 v173, 0xffff0000, v191
	v_pk_add_f32 v[124:125], v[124:125], v[166:167]
	v_pk_add_f32 v[126:127], v[126:127], v[168:169]
	v_pk_add_f32 v[120:121], v[120:121], v[170:171]
	v_pk_add_f32 v[122:123], v[122:123], v[172:173]
	v_cvt_pk_bf16_f32 v174, v124, v125
	v_cvt_pk_bf16_f32 v175, v126, v127
	v_cvt_pk_bf16_f32 v176, v120, v121
	v_cvt_pk_bf16_f32 v177, v122, v123
	v_pk_mul_f32 v[182:183], v[124:125], v[124:125]
	v_pk_fma_f32 v[182:183], v[126:127], v[126:127], v[182:183]
	v_pk_fma_f32 v[182:183], v[120:121], v[120:121], v[182:183]
	v_pk_fma_f32 v[182:183], v[122:123], v[122:123], v[182:183]
	global_store_dwordx4 v[232:233], v[174:177], off
	s_waitcnt vmcnt(7)
	v_lshlrev_b32_e32 v166, 16, v192
	v_and_b32_e32 v167, 0xffff0000, v192
	v_lshlrev_b32_e32 v168, 16, v193
	v_and_b32_e32 v169, 0xffff0000, v193
	v_lshlrev_b32_e32 v170, 16, v194
	v_and_b32_e32 v171, 0xffff0000, v194
	v_lshlrev_b32_e32 v172, 16, v195
	v_and_b32_e32 v173, 0xffff0000, v195
	v_pk_add_f32 v[116:117], v[116:117], v[166:167]
	v_pk_add_f32 v[118:119], v[118:119], v[168:169]
	v_pk_add_f32 v[112:113], v[112:113], v[170:171]
	v_pk_add_f32 v[114:115], v[114:115], v[172:173]
	v_cvt_pk_bf16_f32 v178, v116, v117
	v_cvt_pk_bf16_f32 v179, v118, v119
	v_cvt_pk_bf16_f32 v180, v112, v113
	v_cvt_pk_bf16_f32 v181, v114, v115
	v_pk_fma_f32 v[182:183], v[116:117], v[116:117], v[182:183]
	v_pk_fma_f32 v[182:183], v[118:119], v[118:119], v[182:183]
	v_pk_fma_f32 v[182:183], v[112:113], v[112:113], v[182:183]
	v_pk_fma_f32 v[182:183], v[114:115], v[114:115], v[182:183]
	global_store_dwordx4 v[232:233], v[178:181], off offset:256
	v_add_f32_e32 v184, v182, v183
	v_mov_b32_e32 v185, v184
	s_nop 1
	v_permlane16_swap_b32_e32 v185, v184
	v_add_f32_e32 v184, v184, v185
	v_mov_b32_e32 v185, v184
	s_nop 1
	v_permlane32_swap_b32_e32 v185, v184
	v_add_f32_e32 v184, v184, v185
	s_and_saveexec_b64 s[42:43], s[4:5]
	global_store_dword v[234:235], v184, off
	s_or_b64 exec, exec, s[42:43]
	s_mov_b64 s[100:101], 0x40000
	v_lshl_add_u64 v[230:231], v[232:233], 0, s[100:101]
	global_load_dwordx4 v[188:191], v[230:231], off
	global_load_dwordx4 v[192:195], v[230:231], off offset:256
	s_mov_b64 s[100:101], 0x8000
	v_lshl_add_u64 v[186:187], v[232:233], 0, s[100:101]
	s_waitcnt vmcnt(10)
	v_lshlrev_b32_e32 v166, 16, v196
	v_and_b32_e32 v167, 0xffff0000, v196
	v_lshlrev_b32_e32 v168, 16, v197
	v_and_b32_e32 v169, 0xffff0000, v197
	v_lshlrev_b32_e32 v170, 16, v198
	v_and_b32_e32 v171, 0xffff0000, v198
	v_lshlrev_b32_e32 v172, 16, v199
	v_and_b32_e32 v173, 0xffff0000, v199
	v_pk_add_f32 v[108:109], v[108:109], v[166:167]
	v_pk_add_f32 v[110:111], v[110:111], v[168:169]
	v_pk_add_f32 v[104:105], v[104:105], v[170:171]
	v_pk_add_f32 v[106:107], v[106:107], v[172:173]
	v_cvt_pk_bf16_f32 v174, v108, v109
	v_cvt_pk_bf16_f32 v175, v110, v111
	v_cvt_pk_bf16_f32 v176, v104, v105
	v_cvt_pk_bf16_f32 v177, v106, v107
	v_pk_mul_f32 v[182:183], v[108:109], v[108:109]
	v_pk_fma_f32 v[182:183], v[110:111], v[110:111], v[182:183]
	v_pk_fma_f32 v[182:183], v[104:105], v[104:105], v[182:183]
	v_pk_fma_f32 v[182:183], v[106:107], v[106:107], v[182:183]
	global_store_dwordx4 v[186:187], v[174:177], off
	s_waitcnt vmcnt(10)
	v_lshlrev_b32_e32 v166, 16, v200
	v_and_b32_e32 v167, 0xffff0000, v200
	v_lshlrev_b32_e32 v168, 16, v201
	v_and_b32_e32 v169, 0xffff0000, v201
	v_lshlrev_b32_e32 v170, 16, v202
	v_and_b32_e32 v171, 0xffff0000, v202
	v_lshlrev_b32_e32 v172, 16, v203
	v_and_b32_e32 v173, 0xffff0000, v203
	v_pk_add_f32 v[100:101], v[100:101], v[166:167]
	v_pk_add_f32 v[102:103], v[102:103], v[168:169]
	v_pk_add_f32 v[96:97], v[96:97], v[170:171]
	v_pk_add_f32 v[98:99], v[98:99], v[172:173]
	v_cvt_pk_bf16_f32 v178, v100, v101
	v_cvt_pk_bf16_f32 v179, v102, v103
	v_cvt_pk_bf16_f32 v180, v96, v97
	v_cvt_pk_bf16_f32 v181, v98, v99
	v_pk_fma_f32 v[182:183], v[100:101], v[100:101], v[182:183]
	v_pk_fma_f32 v[182:183], v[102:103], v[102:103], v[182:183]
	v_pk_fma_f32 v[182:183], v[96:97], v[96:97], v[182:183]
	v_pk_fma_f32 v[182:183], v[98:99], v[98:99], v[182:183]
	global_store_dwordx4 v[186:187], v[178:181], off offset:256
	v_add_f32_e32 v184, v182, v183
	v_mov_b32_e32 v185, v184
	s_nop 1
	v_permlane16_swap_b32_e32 v185, v184
	v_add_f32_e32 v184, v184, v185
	v_mov_b32_e32 v185, v184
	s_nop 1
	v_permlane32_swap_b32_e32 v185, v184
	v_add_f32_e32 v184, v184, v185
	s_and_saveexec_b64 s[42:43], s[4:5]
	global_store_dword v[234:235], v184, off offset:1024
	s_or_b64 exec, exec, s[42:43]
	s_mov_b64 s[100:101], 0x48000
	v_lshl_add_u64 v[230:231], v[232:233], 0, s[100:101]
	global_load_dwordx4 v[196:199], v[230:231], off
	global_load_dwordx4 v[200:203], v[230:231], off offset:256
	s_mov_b64 s[100:101], 0x10000
	v_lshl_add_u64 v[186:187], v[232:233], 0, s[100:101]
	s_waitcnt vmcnt(13)
	v_lshlrev_b32_e32 v166, 16, v204
	v_and_b32_e32 v167, 0xffff0000, v204
	v_lshlrev_b32_e32 v168, 16, v205
	v_and_b32_e32 v169, 0xffff0000, v205
	v_lshlrev_b32_e32 v170, 16, v206
	v_and_b32_e32 v171, 0xffff0000, v206
	v_lshlrev_b32_e32 v172, 16, v207
	v_and_b32_e32 v173, 0xffff0000, v207
	v_pk_add_f32 v[92:93], v[92:93], v[166:167]
	v_pk_add_f32 v[94:95], v[94:95], v[168:169]
	v_pk_add_f32 v[88:89], v[88:89], v[170:171]
	v_pk_add_f32 v[90:91], v[90:91], v[172:173]
	v_cvt_pk_bf16_f32 v174, v92, v93
	v_cvt_pk_bf16_f32 v175, v94, v95
	v_cvt_pk_bf16_f32 v176, v88, v89
	v_cvt_pk_bf16_f32 v177, v90, v91
	v_pk_mul_f32 v[182:183], v[92:93], v[92:93]
	v_pk_fma_f32 v[182:183], v[94:95], v[94:95], v[182:183]
	v_pk_fma_f32 v[182:183], v[88:89], v[88:89], v[182:183]
	v_pk_fma_f32 v[182:183], v[90:91], v[90:91], v[182:183]
	global_store_dwordx4 v[186:187], v[174:177], off
	s_waitcnt vmcnt(13)
	v_lshlrev_b32_e32 v166, 16, v208
	v_and_b32_e32 v167, 0xffff0000, v208
	v_lshlrev_b32_e32 v168, 16, v209
	v_and_b32_e32 v169, 0xffff0000, v209
	v_lshlrev_b32_e32 v170, 16, v210
	v_and_b32_e32 v171, 0xffff0000, v210
	v_lshlrev_b32_e32 v172, 16, v211
	v_and_b32_e32 v173, 0xffff0000, v211
	v_pk_add_f32 v[84:85], v[84:85], v[166:167]
	v_pk_add_f32 v[86:87], v[86:87], v[168:169]
	v_pk_add_f32 v[80:81], v[80:81], v[170:171]
	v_pk_add_f32 v[82:83], v[82:83], v[172:173]
	v_cvt_pk_bf16_f32 v178, v84, v85
	v_cvt_pk_bf16_f32 v179, v86, v87
	v_cvt_pk_bf16_f32 v180, v80, v81
	v_cvt_pk_bf16_f32 v181, v82, v83
	v_pk_fma_f32 v[182:183], v[84:85], v[84:85], v[182:183]
	v_pk_fma_f32 v[182:183], v[86:87], v[86:87], v[182:183]
	v_pk_fma_f32 v[182:183], v[80:81], v[80:81], v[182:183]
	v_pk_fma_f32 v[182:183], v[82:83], v[82:83], v[182:183]
	global_store_dwordx4 v[186:187], v[178:181], off offset:256
	v_add_f32_e32 v184, v182, v183
	v_mov_b32_e32 v185, v184
	s_nop 1
	v_permlane16_swap_b32_e32 v185, v184
	v_add_f32_e32 v184, v184, v185
	v_mov_b32_e32 v185, v184
	s_nop 1
	v_permlane32_swap_b32_e32 v185, v184
	v_add_f32_e32 v184, v184, v185
	s_and_saveexec_b64 s[42:43], s[4:5]
	global_store_dword v[234:235], v184, off offset:2048
	s_or_b64 exec, exec, s[42:43]
	s_mov_b64 s[100:101], 0x50000
	v_lshl_add_u64 v[230:231], v[232:233], 0, s[100:101]
	global_load_dwordx4 v[204:207], v[230:231], off
	global_load_dwordx4 v[208:211], v[230:231], off offset:256
	s_mov_b64 s[100:101], 0x18000
	v_lshl_add_u64 v[186:187], v[232:233], 0, s[100:101]
	s_waitcnt vmcnt(16)
	v_lshlrev_b32_e32 v166, 16, v212
	v_and_b32_e32 v167, 0xffff0000, v212
	v_lshlrev_b32_e32 v168, 16, v213
	v_and_b32_e32 v169, 0xffff0000, v213
	v_lshlrev_b32_e32 v170, 16, v214
	v_and_b32_e32 v171, 0xffff0000, v214
	v_lshlrev_b32_e32 v172, 16, v215
	v_and_b32_e32 v173, 0xffff0000, v215
	v_pk_add_f32 v[76:77], v[76:77], v[166:167]
	v_pk_add_f32 v[78:79], v[78:79], v[168:169]
	v_pk_add_f32 v[72:73], v[72:73], v[170:171]
	v_pk_add_f32 v[74:75], v[74:75], v[172:173]
	v_cvt_pk_bf16_f32 v174, v76, v77
	v_cvt_pk_bf16_f32 v175, v78, v79
	v_cvt_pk_bf16_f32 v176, v72, v73
	v_cvt_pk_bf16_f32 v177, v74, v75
	v_pk_mul_f32 v[182:183], v[76:77], v[76:77]
	v_pk_fma_f32 v[182:183], v[78:79], v[78:79], v[182:183]
	v_pk_fma_f32 v[182:183], v[72:73], v[72:73], v[182:183]
	v_pk_fma_f32 v[182:183], v[74:75], v[74:75], v[182:183]
	global_store_dwordx4 v[186:187], v[174:177], off
	s_waitcnt vmcnt(16)
	v_lshlrev_b32_e32 v166, 16, v216
	v_and_b32_e32 v167, 0xffff0000, v216
	v_lshlrev_b32_e32 v168, 16, v217
	v_and_b32_e32 v169, 0xffff0000, v217
	v_lshlrev_b32_e32 v170, 16, v218
	v_and_b32_e32 v171, 0xffff0000, v218
	v_lshlrev_b32_e32 v172, 16, v219
	v_and_b32_e32 v173, 0xffff0000, v219
	v_pk_add_f32 v[68:69], v[68:69], v[166:167]
	v_pk_add_f32 v[70:71], v[70:71], v[168:169]
	v_pk_add_f32 v[64:65], v[64:65], v[170:171]
	v_pk_add_f32 v[66:67], v[66:67], v[172:173]
	v_cvt_pk_bf16_f32 v178, v68, v69
	v_cvt_pk_bf16_f32 v179, v70, v71
	v_cvt_pk_bf16_f32 v180, v64, v65
	v_cvt_pk_bf16_f32 v181, v66, v67
	v_pk_fma_f32 v[182:183], v[68:69], v[68:69], v[182:183]
	v_pk_fma_f32 v[182:183], v[70:71], v[70:71], v[182:183]
	v_pk_fma_f32 v[182:183], v[64:65], v[64:65], v[182:183]
	v_pk_fma_f32 v[182:183], v[66:67], v[66:67], v[182:183]
	global_store_dwordx4 v[186:187], v[178:181], off offset:256
	v_add_f32_e32 v184, v182, v183
	v_mov_b32_e32 v185, v184
	s_nop 1
	v_permlane16_swap_b32_e32 v185, v184
	v_add_f32_e32 v184, v184, v185
	v_mov_b32_e32 v185, v184
	s_nop 1
	v_permlane32_swap_b32_e32 v185, v184
	v_add_f32_e32 v184, v184, v185
	s_and_saveexec_b64 s[42:43], s[4:5]
	global_store_dword v[234:235], v184, off offset:3072
	s_or_b64 exec, exec, s[42:43]
	s_mov_b64 s[100:101], 0x58000
	v_lshl_add_u64 v[230:231], v[232:233], 0, s[100:101]
	global_load_dwordx4 v[212:215], v[230:231], off
	global_load_dwordx4 v[216:219], v[230:231], off offset:256
	s_mov_b64 s[100:101], 0x40000
	v_lshl_add_u64 v[186:187], v[232:233], 0, s[100:101]
	s_waitcnt vmcnt(16)
	v_lshlrev_b32_e32 v166, 16, v188
	v_and_b32_e32 v167, 0xffff0000, v188
	v_lshlrev_b32_e32 v168, 16, v189
	v_and_b32_e32 v169, 0xffff0000, v189
	v_lshlrev_b32_e32 v170, 16, v190
	v_and_b32_e32 v171, 0xffff0000, v190
	v_lshlrev_b32_e32 v172, 16, v191
	v_and_b32_e32 v173, 0xffff0000, v191
	v_pk_add_f32 v[60:61], v[60:61], v[166:167]
	v_pk_add_f32 v[62:63], v[62:63], v[168:169]
	v_pk_add_f32 v[56:57], v[56:57], v[170:171]
	v_pk_add_f32 v[58:59], v[58:59], v[172:173]
	v_cvt_pk_bf16_f32 v174, v60, v61
	v_cvt_pk_bf16_f32 v175, v62, v63
	v_cvt_pk_bf16_f32 v176, v56, v57
	v_cvt_pk_bf16_f32 v177, v58, v59
	v_pk_mul_f32 v[182:183], v[60:61], v[60:61]
	v_pk_fma_f32 v[182:183], v[62:63], v[62:63], v[182:183]
	v_pk_fma_f32 v[182:183], v[56:57], v[56:57], v[182:183]
	v_pk_fma_f32 v[182:183], v[58:59], v[58:59], v[182:183]
	global_store_dwordx4 v[186:187], v[174:177], off
	s_waitcnt vmcnt(16)
	v_lshlrev_b32_e32 v166, 16, v192
	v_and_b32_e32 v167, 0xffff0000, v192
	v_lshlrev_b32_e32 v168, 16, v193
	v_and_b32_e32 v169, 0xffff0000, v193
	v_lshlrev_b32_e32 v170, 16, v194
	v_and_b32_e32 v171, 0xffff0000, v194
	v_lshlrev_b32_e32 v172, 16, v195
	v_and_b32_e32 v173, 0xffff0000, v195
	v_pk_add_f32 v[52:53], v[52:53], v[166:167]
	v_pk_add_f32 v[54:55], v[54:55], v[168:169]
	v_pk_add_f32 v[48:49], v[48:49], v[170:171]
	v_pk_add_f32 v[50:51], v[50:51], v[172:173]
	v_cvt_pk_bf16_f32 v178, v52, v53
	v_cvt_pk_bf16_f32 v179, v54, v55
	v_cvt_pk_bf16_f32 v180, v48, v49
	v_cvt_pk_bf16_f32 v181, v50, v51
	v_pk_fma_f32 v[182:183], v[52:53], v[52:53], v[182:183]
	v_pk_fma_f32 v[182:183], v[54:55], v[54:55], v[182:183]
	v_pk_fma_f32 v[182:183], v[48:49], v[48:49], v[182:183]
	v_pk_fma_f32 v[182:183], v[50:51], v[50:51], v[182:183]
	global_store_dwordx4 v[186:187], v[178:181], off offset:256
	v_add_f32_e32 v184, v182, v183
	v_mov_b32_e32 v185, v184
	s_nop 1
	v_permlane16_swap_b32_e32 v185, v184
	v_add_f32_e32 v184, v184, v185
	v_mov_b32_e32 v185, v184
	s_nop 1
	v_permlane32_swap_b32_e32 v185, v184
	v_add_f32_e32 v184, v184, v185
	s_and_saveexec_b64 s[42:43], s[4:5]
	global_store_dword v[236:237], v184, off
	s_or_b64 exec, exec, s[42:43]
	s_mov_b64 s[100:101], 0x48000
	v_lshl_add_u64 v[186:187], v[232:233], 0, s[100:101]
	s_waitcnt vmcnt(14)
	v_lshlrev_b32_e32 v166, 16, v196
	v_and_b32_e32 v167, 0xffff0000, v196
	v_lshlrev_b32_e32 v168, 16, v197
	v_and_b32_e32 v169, 0xffff0000, v197
	v_lshlrev_b32_e32 v170, 16, v198
	v_and_b32_e32 v171, 0xffff0000, v198
	v_lshlrev_b32_e32 v172, 16, v199
	v_and_b32_e32 v173, 0xffff0000, v199
	v_pk_add_f32 v[44:45], v[44:45], v[166:167]
	v_pk_add_f32 v[46:47], v[46:47], v[168:169]
	v_pk_add_f32 v[40:41], v[40:41], v[170:171]
	v_pk_add_f32 v[42:43], v[42:43], v[172:173]
	v_cvt_pk_bf16_f32 v174, v44, v45
	v_cvt_pk_bf16_f32 v175, v46, v47
	v_cvt_pk_bf16_f32 v176, v40, v41
	v_cvt_pk_bf16_f32 v177, v42, v43
	v_pk_mul_f32 v[182:183], v[44:45], v[44:45]
	v_pk_fma_f32 v[182:183], v[46:47], v[46:47], v[182:183]
	v_pk_fma_f32 v[182:183], v[40:41], v[40:41], v[182:183]
	v_pk_fma_f32 v[182:183], v[42:43], v[42:43], v[182:183]
	global_store_dwordx4 v[186:187], v[174:177], off
	s_waitcnt vmcnt(14)
	v_lshlrev_b32_e32 v166, 16, v200
	v_and_b32_e32 v167, 0xffff0000, v200
	v_lshlrev_b32_e32 v168, 16, v201
	v_and_b32_e32 v169, 0xffff0000, v201
	v_lshlrev_b32_e32 v170, 16, v202
	v_and_b32_e32 v171, 0xffff0000, v202
	v_lshlrev_b32_e32 v172, 16, v203
	v_and_b32_e32 v173, 0xffff0000, v203
	v_pk_add_f32 v[36:37], v[36:37], v[166:167]
	v_pk_add_f32 v[38:39], v[38:39], v[168:169]
	v_pk_add_f32 v[32:33], v[32:33], v[170:171]
	v_pk_add_f32 v[34:35], v[34:35], v[172:173]
	v_cvt_pk_bf16_f32 v178, v36, v37
	v_cvt_pk_bf16_f32 v179, v38, v39
	v_cvt_pk_bf16_f32 v180, v32, v33
	v_cvt_pk_bf16_f32 v181, v34, v35
	v_pk_fma_f32 v[182:183], v[36:37], v[36:37], v[182:183]
	v_pk_fma_f32 v[182:183], v[38:39], v[38:39], v[182:183]
	v_pk_fma_f32 v[182:183], v[32:33], v[32:33], v[182:183]
	v_pk_fma_f32 v[182:183], v[34:35], v[34:35], v[182:183]
	global_store_dwordx4 v[186:187], v[178:181], off offset:256
	v_add_f32_e32 v184, v182, v183
	v_mov_b32_e32 v185, v184
	s_nop 1
	v_permlane16_swap_b32_e32 v185, v184
	v_add_f32_e32 v184, v184, v185
	v_mov_b32_e32 v185, v184
	s_nop 1
	v_permlane32_swap_b32_e32 v185, v184
	v_add_f32_e32 v184, v184, v185
	s_and_saveexec_b64 s[42:43], s[4:5]
	global_store_dword v[236:237], v184, off offset:1024
	s_or_b64 exec, exec, s[42:43]
	s_mov_b64 s[100:101], 0x50000
	v_lshl_add_u64 v[186:187], v[232:233], 0, s[100:101]
	s_waitcnt vmcnt(12)
	v_lshlrev_b32_e32 v166, 16, v204
	v_and_b32_e32 v167, 0xffff0000, v204
	v_lshlrev_b32_e32 v168, 16, v205
	v_and_b32_e32 v169, 0xffff0000, v205
	v_lshlrev_b32_e32 v170, 16, v206
	v_and_b32_e32 v171, 0xffff0000, v206
	v_lshlrev_b32_e32 v172, 16, v207
	v_and_b32_e32 v173, 0xffff0000, v207
	v_pk_add_f32 v[28:29], v[28:29], v[166:167]
	v_pk_add_f32 v[30:31], v[30:31], v[168:169]
	v_pk_add_f32 v[24:25], v[24:25], v[170:171]
	v_pk_add_f32 v[26:27], v[26:27], v[172:173]
	v_cvt_pk_bf16_f32 v174, v28, v29
	v_cvt_pk_bf16_f32 v175, v30, v31
	v_cvt_pk_bf16_f32 v176, v24, v25
	v_cvt_pk_bf16_f32 v177, v26, v27
	v_pk_mul_f32 v[182:183], v[28:29], v[28:29]
	v_pk_fma_f32 v[182:183], v[30:31], v[30:31], v[182:183]
	v_pk_fma_f32 v[182:183], v[24:25], v[24:25], v[182:183]
	v_pk_fma_f32 v[182:183], v[26:27], v[26:27], v[182:183]
	global_store_dwordx4 v[186:187], v[174:177], off
	s_waitcnt vmcnt(12)
	v_lshlrev_b32_e32 v166, 16, v208
	v_and_b32_e32 v167, 0xffff0000, v208
	v_lshlrev_b32_e32 v168, 16, v209
	v_and_b32_e32 v169, 0xffff0000, v209
	v_lshlrev_b32_e32 v170, 16, v210
	v_and_b32_e32 v171, 0xffff0000, v210
	v_lshlrev_b32_e32 v172, 16, v211
	v_and_b32_e32 v173, 0xffff0000, v211
	v_pk_add_f32 v[20:21], v[20:21], v[166:167]
	v_pk_add_f32 v[22:23], v[22:23], v[168:169]
	v_pk_add_f32 v[16:17], v[16:17], v[170:171]
	v_pk_add_f32 v[18:19], v[18:19], v[172:173]
	v_cvt_pk_bf16_f32 v178, v20, v21
	v_cvt_pk_bf16_f32 v179, v22, v23
	v_cvt_pk_bf16_f32 v180, v16, v17
	v_cvt_pk_bf16_f32 v181, v18, v19
	v_pk_fma_f32 v[182:183], v[20:21], v[20:21], v[182:183]
	v_pk_fma_f32 v[182:183], v[22:23], v[22:23], v[182:183]
	v_pk_fma_f32 v[182:183], v[16:17], v[16:17], v[182:183]
	v_pk_fma_f32 v[182:183], v[18:19], v[18:19], v[182:183]
	global_store_dwordx4 v[186:187], v[178:181], off offset:256
	v_add_f32_e32 v184, v182, v183
	v_mov_b32_e32 v185, v184
	s_nop 1
	v_permlane16_swap_b32_e32 v185, v184
	v_add_f32_e32 v184, v184, v185
	v_mov_b32_e32 v185, v184
	s_nop 1
	v_permlane32_swap_b32_e32 v185, v184
	v_add_f32_e32 v184, v184, v185
	s_and_saveexec_b64 s[42:43], s[4:5]
	global_store_dword v[236:237], v184, off offset:2048
	s_or_b64 exec, exec, s[42:43]
	s_mov_b64 s[100:101], 0x58000
	v_lshl_add_u64 v[186:187], v[232:233], 0, s[100:101]
	s_waitcnt vmcnt(10)
	v_lshlrev_b32_e32 v166, 16, v212
	v_and_b32_e32 v167, 0xffff0000, v212
	v_lshlrev_b32_e32 v168, 16, v213
	v_and_b32_e32 v169, 0xffff0000, v213
	v_lshlrev_b32_e32 v170, 16, v214
	v_and_b32_e32 v171, 0xffff0000, v214
	v_lshlrev_b32_e32 v172, 16, v215
	v_and_b32_e32 v173, 0xffff0000, v215
	v_pk_add_f32 v[12:13], v[12:13], v[166:167]
	v_pk_add_f32 v[14:15], v[14:15], v[168:169]
	v_pk_add_f32 v[8:9], v[8:9], v[170:171]
	v_pk_add_f32 v[10:11], v[10:11], v[172:173]
	v_cvt_pk_bf16_f32 v174, v12, v13
	v_cvt_pk_bf16_f32 v175, v14, v15
	v_cvt_pk_bf16_f32 v176, v8, v9
	v_cvt_pk_bf16_f32 v177, v10, v11
	v_pk_mul_f32 v[182:183], v[12:13], v[12:13]
	v_pk_fma_f32 v[182:183], v[14:15], v[14:15], v[182:183]
	v_pk_fma_f32 v[182:183], v[8:9], v[8:9], v[182:183]
	v_pk_fma_f32 v[182:183], v[10:11], v[10:11], v[182:183]
	global_store_dwordx4 v[186:187], v[174:177], off
	s_waitcnt vmcnt(10)
	v_lshlrev_b32_e32 v166, 16, v216
	v_and_b32_e32 v167, 0xffff0000, v216
	v_lshlrev_b32_e32 v168, 16, v217
	v_and_b32_e32 v169, 0xffff0000, v217
	v_lshlrev_b32_e32 v170, 16, v218
	v_and_b32_e32 v171, 0xffff0000, v218
	v_lshlrev_b32_e32 v172, 16, v219
	v_and_b32_e32 v173, 0xffff0000, v219
	v_pk_add_f32 v[4:5], v[4:5], v[166:167]
	v_pk_add_f32 v[6:7], v[6:7], v[168:169]
	v_pk_add_f32 v[0:1], v[0:1], v[170:171]
	v_pk_add_f32 v[2:3], v[2:3], v[172:173]
	v_cvt_pk_bf16_f32 v178, v4, v5
	v_cvt_pk_bf16_f32 v179, v6, v7
	v_cvt_pk_bf16_f32 v180, v0, v1
	v_cvt_pk_bf16_f32 v181, v2, v3
	v_pk_fma_f32 v[182:183], v[4:5], v[4:5], v[182:183]
	v_pk_fma_f32 v[182:183], v[6:7], v[6:7], v[182:183]
	v_pk_fma_f32 v[182:183], v[0:1], v[0:1], v[182:183]
	v_pk_fma_f32 v[182:183], v[2:3], v[2:3], v[182:183]
	global_store_dwordx4 v[186:187], v[178:181], off offset:256
	v_add_f32_e32 v184, v182, v183
	v_mov_b32_e32 v185, v184
	s_nop 1
	v_permlane16_swap_b32_e32 v185, v184
	v_add_f32_e32 v184, v184, v185
	v_mov_b32_e32 v185, v184
	s_nop 1
	v_permlane32_swap_b32_e32 v185, v184
	v_add_f32_e32 v184, v184, v185
	s_and_saveexec_b64 s[42:43], s[4:5]
	global_store_dword v[236:237], v184, off offset:3072
	s_or_b64 exec, exec, s[42:43]
	s_and_b64 vcc, exec, s[6:7]
	s_mov_b64 s[6:7], -1
	s_cbranch_vccnz .LBB0_550
	s_andn2_b64 vcc, exec, s[10:11]
	s_cbranch_vccnz .LBB0_549
	s_nop 0
	s_branch .LBB0_549

.LBB0_972:
	v_lshl_add_u32 v150, s38, 8, v131
	v_ashrrev_i32_e32 v151, 31, v150
	v_lshl_or_b32 v148, s0, 8, v153
	v_lshlrev_b64 v[160:161], 11, v[150:151]
	v_ashrrev_i32_e32 v149, 31, v148
	v_lshl_add_u64 v[160:161], s[14:15], 0, v[160:161]
	v_lshl_add_u64 v[164:165], v[148:149], 1, v[160:161]
	v_mov_b32_e32 v232, v164
	v_mov_b32_e32 v233, v165
	global_load_dwordx4 v[188:191], v[232:233], off
	global_load_dwordx4 v[192:195], v[232:233], off offset:256
	s_mov_b64 s[100:101], 0x8000
	v_lshl_add_u64 v[230:231], v[232:233], 0, s[100:101]
	global_load_dwordx4 v[196:199], v[230:231], off
	global_load_dwordx4 v[200:203], v[230:231], off offset:256
	s_mov_b64 s[100:101], 0x10000
	v_lshl_add_u64 v[230:231], v[232:233], 0, s[100:101]
	global_load_dwordx4 v[204:207], v[230:231], off
	global_load_dwordx4 v[208:211], v[230:231], off offset:256
	s_mov_b64 s[100:101], 0x18000
	v_lshl_add_u64 v[230:231], v[232:233], 0, s[100:101]
	global_load_dwordx4 v[212:215], v[230:231], off
	global_load_dwordx4 v[216:219], v[230:231], off offset:256
	s_lshl_b32 s38, s0, 2
	s_ashr_i32 s39, s38, 31
	v_lshlrev_b64 v[234:235], 6, v[150:151]
	v_lshl_add_u64 v[234:235], s[18:19], 0, v[234:235]
	v_lshl_add_u64 v[234:235], s[38:39], 2, v[234:235]
	s_lshl_b32 s100, s56, 2
	s_mov_b32 s101, 0
	v_lshl_add_u64 v[234:235], v[234:235], 0, s[100:101]
	s_mov_b64 s[100:101], 0x2000
	v_lshl_add_u64 v[236:237], v[234:235], 0, s[100:101]
	s_waitcnt vmcnt(7)
	v_lshlrev_b32_e32 v166, 16, v188
	v_and_b32_e32 v167, 0xffff0000, v188
	v_lshlrev_b32_e32 v168, 16, v189
	v_and_b32_e32 v169, 0xffff0000, v189
	v_lshlrev_b32_e32 v170, 16, v190
	v_and_b32_e32 v171, 0xffff0000, v190
	v_lshlrev_b32_e32 v172, 16, v191
	v_and_b32_e32 v173, 0xffff0000, v191
	v_pk_add_f32 v[124:125], v[124:125], v[166:167]
	v_pk_add_f32 v[126:127], v[126:127], v[168:169]
	v_pk_add_f32 v[120:121], v[120:121], v[170:171]
	v_pk_add_f32 v[122:123], v[122:123], v[172:173]
	v_cvt_pk_bf16_f32 v174, v124, v125
	v_cvt_pk_bf16_f32 v175, v126, v127
	v_cvt_pk_bf16_f32 v176, v120, v121
	v_cvt_pk_bf16_f32 v177, v122, v123
	v_pk_mul_f32 v[182:183], v[124:125], v[124:125]
	v_pk_fma_f32 v[182:183], v[126:127], v[126:127], v[182:183]
	v_pk_fma_f32 v[182:183], v[120:121], v[120:121], v[182:183]
	v_pk_fma_f32 v[182:183], v[122:123], v[122:123], v[182:183]
	global_store_dwordx4 v[232:233], v[174:177], off
	s_waitcnt vmcnt(7)
	v_lshlrev_b32_e32 v166, 16, v192
	v_and_b32_e32 v167, 0xffff0000, v192
	v_lshlrev_b32_e32 v168, 16, v193
	v_and_b32_e32 v169, 0xffff0000, v193
	v_lshlrev_b32_e32 v170, 16, v194
	v_and_b32_e32 v171, 0xffff0000, v194
	v_lshlrev_b32_e32 v172, 16, v195
	v_and_b32_e32 v173, 0xffff0000, v195
	v_pk_add_f32 v[116:117], v[116:117], v[166:167]
	v_pk_add_f32 v[118:119], v[118:119], v[168:169]
	v_pk_add_f32 v[112:113], v[112:113], v[170:171]
	v_pk_add_f32 v[114:115], v[114:115], v[172:173]
	v_cvt_pk_bf16_f32 v178, v116, v117
	v_cvt_pk_bf16_f32 v179, v118, v119
	v_cvt_pk_bf16_f32 v180, v112, v113
	v_cvt_pk_bf16_f32 v181, v114, v115
	v_pk_fma_f32 v[182:183], v[116:117], v[116:117], v[182:183]
	v_pk_fma_f32 v[182:183], v[118:119], v[118:119], v[182:183]
	v_pk_fma_f32 v[182:183], v[112:113], v[112:113], v[182:183]
	v_pk_fma_f32 v[182:183], v[114:115], v[114:115], v[182:183]
	global_store_dwordx4 v[232:233], v[178:181], off offset:256
	v_add_f32_e32 v184, v182, v183
	v_mov_b32_e32 v185, v184
	s_nop 1
	v_permlane16_swap_b32_e32 v185, v184
	v_add_f32_e32 v184, v184, v185
	v_mov_b32_e32 v185, v184
	s_nop 1
	v_permlane32_swap_b32_e32 v185, v184
	v_add_f32_e32 v184, v184, v185
	s_and_saveexec_b64 s[40:41], s[4:5]
	global_store_dword v[234:235], v184, off
	s_or_b64 exec, exec, s[40:41]
	s_mov_b64 s[100:101], 0x40000
	v_lshl_add_u64 v[230:231], v[232:233], 0, s[100:101]
	global_load_dwordx4 v[188:191], v[230:231], off
	global_load_dwordx4 v[192:195], v[230:231], off offset:256
	s_mov_b64 s[100:101], 0x8000
	v_lshl_add_u64 v[186:187], v[232:233], 0, s[100:101]
	s_waitcnt vmcnt(10)
	v_lshlrev_b32_e32 v166, 16, v196
	v_and_b32_e32 v167, 0xffff0000, v196
	v_lshlrev_b32_e32 v168, 16, v197
	v_and_b32_e32 v169, 0xffff0000, v197
	v_lshlrev_b32_e32 v170, 16, v198
	v_and_b32_e32 v171, 0xffff0000, v198
	v_lshlrev_b32_e32 v172, 16, v199
	v_and_b32_e32 v173, 0xffff0000, v199
	v_pk_add_f32 v[108:109], v[108:109], v[166:167]
	v_pk_add_f32 v[110:111], v[110:111], v[168:169]
	v_pk_add_f32 v[104:105], v[104:105], v[170:171]
	v_pk_add_f32 v[106:107], v[106:107], v[172:173]
	v_cvt_pk_bf16_f32 v174, v108, v109
	v_cvt_pk_bf16_f32 v175, v110, v111
	v_cvt_pk_bf16_f32 v176, v104, v105
	v_cvt_pk_bf16_f32 v177, v106, v107
	v_pk_mul_f32 v[182:183], v[108:109], v[108:109]
	v_pk_fma_f32 v[182:183], v[110:111], v[110:111], v[182:183]
	v_pk_fma_f32 v[182:183], v[104:105], v[104:105], v[182:183]
	v_pk_fma_f32 v[182:183], v[106:107], v[106:107], v[182:183]
	global_store_dwordx4 v[186:187], v[174:177], off
	s_waitcnt vmcnt(10)
	v_lshlrev_b32_e32 v166, 16, v200
	v_and_b32_e32 v167, 0xffff0000, v200
	v_lshlrev_b32_e32 v168, 16, v201
	v_and_b32_e32 v169, 0xffff0000, v201
	v_lshlrev_b32_e32 v170, 16, v202
	v_and_b32_e32 v171, 0xffff0000, v202
	v_lshlrev_b32_e32 v172, 16, v203
	v_and_b32_e32 v173, 0xffff0000, v203
	v_pk_add_f32 v[100:101], v[100:101], v[166:167]
	v_pk_add_f32 v[102:103], v[102:103], v[168:169]
	v_pk_add_f32 v[96:97], v[96:97], v[170:171]
	v_pk_add_f32 v[98:99], v[98:99], v[172:173]
	v_cvt_pk_bf16_f32 v178, v100, v101
	v_cvt_pk_bf16_f32 v179, v102, v103
	v_cvt_pk_bf16_f32 v180, v96, v97
	v_cvt_pk_bf16_f32 v181, v98, v99
	v_pk_fma_f32 v[182:183], v[100:101], v[100:101], v[182:183]
	v_pk_fma_f32 v[182:183], v[102:103], v[102:103], v[182:183]
	v_pk_fma_f32 v[182:183], v[96:97], v[96:97], v[182:183]
	v_pk_fma_f32 v[182:183], v[98:99], v[98:99], v[182:183]
	global_store_dwordx4 v[186:187], v[178:181], off offset:256
	v_add_f32_e32 v184, v182, v183
	v_mov_b32_e32 v185, v184
	s_nop 1
	v_permlane16_swap_b32_e32 v185, v184
	v_add_f32_e32 v184, v184, v185
	v_mov_b32_e32 v185, v184
	s_nop 1
	v_permlane32_swap_b32_e32 v185, v184
	v_add_f32_e32 v184, v184, v185
	s_and_saveexec_b64 s[40:41], s[4:5]
	global_store_dword v[234:235], v184, off offset:1024
	s_or_b64 exec, exec, s[40:41]
	s_mov_b64 s[100:101], 0x48000
	v_lshl_add_u64 v[230:231], v[232:233], 0, s[100:101]
	global_load_dwordx4 v[196:199], v[230:231], off
	global_load_dwordx4 v[200:203], v[230:231], off offset:256
	s_mov_b64 s[100:101], 0x10000
	v_lshl_add_u64 v[186:187], v[232:233], 0, s[100:101]
	s_waitcnt vmcnt(13)
	v_lshlrev_b32_e32 v166, 16, v204
	v_and_b32_e32 v167, 0xffff0000, v204
	v_lshlrev_b32_e32 v168, 16, v205
	v_and_b32_e32 v169, 0xffff0000, v205
	v_lshlrev_b32_e32 v170, 16, v206
	v_and_b32_e32 v171, 0xffff0000, v206
	v_lshlrev_b32_e32 v172, 16, v207
	v_and_b32_e32 v173, 0xffff0000, v207
	v_pk_add_f32 v[92:93], v[92:93], v[166:167]
	v_pk_add_f32 v[94:95], v[94:95], v[168:169]
	v_pk_add_f32 v[88:89], v[88:89], v[170:171]
	v_pk_add_f32 v[90:91], v[90:91], v[172:173]
	v_cvt_pk_bf16_f32 v174, v92, v93
	v_cvt_pk_bf16_f32 v175, v94, v95
	v_cvt_pk_bf16_f32 v176, v88, v89
	v_cvt_pk_bf16_f32 v177, v90, v91
	v_pk_mul_f32 v[182:183], v[92:93], v[92:93]
	v_pk_fma_f32 v[182:183], v[94:95], v[94:95], v[182:183]
	v_pk_fma_f32 v[182:183], v[88:89], v[88:89], v[182:183]
	v_pk_fma_f32 v[182:183], v[90:91], v[90:91], v[182:183]
	global_store_dwordx4 v[186:187], v[174:177], off
	s_waitcnt vmcnt(13)
	v_lshlrev_b32_e32 v166, 16, v208
	v_and_b32_e32 v167, 0xffff0000, v208
	v_lshlrev_b32_e32 v168, 16, v209
	v_and_b32_e32 v169, 0xffff0000, v209
	v_lshlrev_b32_e32 v170, 16, v210
	v_and_b32_e32 v171, 0xffff0000, v210
	v_lshlrev_b32_e32 v172, 16, v211
	v_and_b32_e32 v173, 0xffff0000, v211
	v_pk_add_f32 v[84:85], v[84:85], v[166:167]
	v_pk_add_f32 v[86:87], v[86:87], v[168:169]
	v_pk_add_f32 v[80:81], v[80:81], v[170:171]
	v_pk_add_f32 v[82:83], v[82:83], v[172:173]
	v_cvt_pk_bf16_f32 v178, v84, v85
	v_cvt_pk_bf16_f32 v179, v86, v87
	v_cvt_pk_bf16_f32 v180, v80, v81
	v_cvt_pk_bf16_f32 v181, v82, v83
	v_pk_fma_f32 v[182:183], v[84:85], v[84:85], v[182:183]
	v_pk_fma_f32 v[182:183], v[86:87], v[86:87], v[182:183]
	v_pk_fma_f32 v[182:183], v[80:81], v[80:81], v[182:183]
	v_pk_fma_f32 v[182:183], v[82:83], v[82:83], v[182:183]
	global_store_dwordx4 v[186:187], v[178:181], off offset:256
	v_add_f32_e32 v184, v182, v183
	v_mov_b32_e32 v185, v184
	s_nop 1
	v_permlane16_swap_b32_e32 v185, v184
	v_add_f32_e32 v184, v184, v185
	v_mov_b32_e32 v185, v184
	s_nop 1
	v_permlane32_swap_b32_e32 v185, v184
	v_add_f32_e32 v184, v184, v185
	s_and_saveexec_b64 s[40:41], s[4:5]
	global_store_dword v[234:235], v184, off offset:2048
	s_or_b64 exec, exec, s[40:41]
	s_mov_b64 s[100:101], 0x50000
	v_lshl_add_u64 v[230:231], v[232:233], 0, s[100:101]
	global_load_dwordx4 v[204:207], v[230:231], off
	global_load_dwordx4 v[208:211], v[230:231], off offset:256
	s_mov_b64 s[100:101], 0x18000
	v_lshl_add_u64 v[186:187], v[232:233], 0, s[100:101]
	s_waitcnt vmcnt(16)
	v_lshlrev_b32_e32 v166, 16, v212
	v_and_b32_e32 v167, 0xffff0000, v212
	v_lshlrev_b32_e32 v168, 16, v213
	v_and_b32_e32 v169, 0xffff0000, v213
	v_lshlrev_b32_e32 v170, 16, v214
	v_and_b32_e32 v171, 0xffff0000, v214
	v_lshlrev_b32_e32 v172, 16, v215
	v_and_b32_e32 v173, 0xffff0000, v215
	v_pk_add_f32 v[76:77], v[76:77], v[166:167]
	v_pk_add_f32 v[78:79], v[78:79], v[168:169]
	v_pk_add_f32 v[72:73], v[72:73], v[170:171]
	v_pk_add_f32 v[74:75], v[74:75], v[172:173]
	v_cvt_pk_bf16_f32 v174, v76, v77
	v_cvt_pk_bf16_f32 v175, v78, v79
	v_cvt_pk_bf16_f32 v176, v72, v73
	v_cvt_pk_bf16_f32 v177, v74, v75
	v_pk_mul_f32 v[182:183], v[76:77], v[76:77]
	v_pk_fma_f32 v[182:183], v[78:79], v[78:79], v[182:183]
	v_pk_fma_f32 v[182:183], v[72:73], v[72:73], v[182:183]
	v_pk_fma_f32 v[182:183], v[74:75], v[74:75], v[182:183]
	global_store_dwordx4 v[186:187], v[174:177], off
	s_waitcnt vmcnt(16)
	v_lshlrev_b32_e32 v166, 16, v216
	v_and_b32_e32 v167, 0xffff0000, v216
	v_lshlrev_b32_e32 v168, 16, v217
	v_and_b32_e32 v169, 0xffff0000, v217
	v_lshlrev_b32_e32 v170, 16, v218
	v_and_b32_e32 v171, 0xffff0000, v218
	v_lshlrev_b32_e32 v172, 16, v219
	v_and_b32_e32 v173, 0xffff0000, v219
	v_pk_add_f32 v[68:69], v[68:69], v[166:167]
	v_pk_add_f32 v[70:71], v[70:71], v[168:169]
	v_pk_add_f32 v[64:65], v[64:65], v[170:171]
	v_pk_add_f32 v[66:67], v[66:67], v[172:173]
	v_cvt_pk_bf16_f32 v178, v68, v69
	v_cvt_pk_bf16_f32 v179, v70, v71
	v_cvt_pk_bf16_f32 v180, v64, v65
	v_cvt_pk_bf16_f32 v181, v66, v67
	v_pk_fma_f32 v[182:183], v[68:69], v[68:69], v[182:183]
	v_pk_fma_f32 v[182:183], v[70:71], v[70:71], v[182:183]
	v_pk_fma_f32 v[182:183], v[64:65], v[64:65], v[182:183]
	v_pk_fma_f32 v[182:183], v[66:67], v[66:67], v[182:183]
	global_store_dwordx4 v[186:187], v[178:181], off offset:256
	v_add_f32_e32 v184, v182, v183
	v_mov_b32_e32 v185, v184
	s_nop 1
	v_permlane16_swap_b32_e32 v185, v184
	v_add_f32_e32 v184, v184, v185
	v_mov_b32_e32 v185, v184
	s_nop 1
	v_permlane32_swap_b32_e32 v185, v184
	v_add_f32_e32 v184, v184, v185
	s_and_saveexec_b64 s[40:41], s[4:5]
	global_store_dword v[234:235], v184, off offset:3072
	s_or_b64 exec, exec, s[40:41]
	s_mov_b64 s[100:101], 0x58000
	v_lshl_add_u64 v[230:231], v[232:233], 0, s[100:101]
	global_load_dwordx4 v[212:215], v[230:231], off
	global_load_dwordx4 v[216:219], v[230:231], off offset:256
	s_mov_b64 s[100:101], 0x40000
	v_lshl_add_u64 v[186:187], v[232:233], 0, s[100:101]
	s_waitcnt vmcnt(16)
	v_lshlrev_b32_e32 v166, 16, v188
	v_and_b32_e32 v167, 0xffff0000, v188
	v_lshlrev_b32_e32 v168, 16, v189
	v_and_b32_e32 v169, 0xffff0000, v189
	v_lshlrev_b32_e32 v170, 16, v190
	v_and_b32_e32 v171, 0xffff0000, v190
	v_lshlrev_b32_e32 v172, 16, v191
	v_and_b32_e32 v173, 0xffff0000, v191
	v_pk_add_f32 v[60:61], v[60:61], v[166:167]
	v_pk_add_f32 v[62:63], v[62:63], v[168:169]
	v_pk_add_f32 v[56:57], v[56:57], v[170:171]
	v_pk_add_f32 v[58:59], v[58:59], v[172:173]
	v_cvt_pk_bf16_f32 v174, v60, v61
	v_cvt_pk_bf16_f32 v175, v62, v63
	v_cvt_pk_bf16_f32 v176, v56, v57
	v_cvt_pk_bf16_f32 v177, v58, v59
	v_pk_mul_f32 v[182:183], v[60:61], v[60:61]
	v_pk_fma_f32 v[182:183], v[62:63], v[62:63], v[182:183]
	v_pk_fma_f32 v[182:183], v[56:57], v[56:57], v[182:183]
	v_pk_fma_f32 v[182:183], v[58:59], v[58:59], v[182:183]
	global_store_dwordx4 v[186:187], v[174:177], off
	s_waitcnt vmcnt(16)
	v_lshlrev_b32_e32 v166, 16, v192
	v_and_b32_e32 v167, 0xffff0000, v192
	v_lshlrev_b32_e32 v168, 16, v193
	v_and_b32_e32 v169, 0xffff0000, v193
	v_lshlrev_b32_e32 v170, 16, v194
	v_and_b32_e32 v171, 0xffff0000, v194
	v_lshlrev_b32_e32 v172, 16, v195
	v_and_b32_e32 v173, 0xffff0000, v195
	v_pk_add_f32 v[52:53], v[52:53], v[166:167]
	v_pk_add_f32 v[54:55], v[54:55], v[168:169]
	v_pk_add_f32 v[48:49], v[48:49], v[170:171]
	v_pk_add_f32 v[50:51], v[50:51], v[172:173]
	v_cvt_pk_bf16_f32 v178, v52, v53
	v_cvt_pk_bf16_f32 v179, v54, v55
	v_cvt_pk_bf16_f32 v180, v48, v49
	v_cvt_pk_bf16_f32 v181, v50, v51
	v_pk_fma_f32 v[182:183], v[52:53], v[52:53], v[182:183]
	v_pk_fma_f32 v[182:183], v[54:55], v[54:55], v[182:183]
	v_pk_fma_f32 v[182:183], v[48:49], v[48:49], v[182:183]
	v_pk_fma_f32 v[182:183], v[50:51], v[50:51], v[182:183]
	global_store_dwordx4 v[186:187], v[178:181], off offset:256
	v_add_f32_e32 v184, v182, v183
	v_mov_b32_e32 v185, v184
	s_nop 1
	v_permlane16_swap_b32_e32 v185, v184
	v_add_f32_e32 v184, v184, v185
	v_mov_b32_e32 v185, v184
	s_nop 1
	v_permlane32_swap_b32_e32 v185, v184
	v_add_f32_e32 v184, v184, v185
	s_and_saveexec_b64 s[40:41], s[4:5]
	global_store_dword v[236:237], v184, off
	s_or_b64 exec, exec, s[40:41]
	s_mov_b64 s[100:101], 0x48000
	v_lshl_add_u64 v[186:187], v[232:233], 0, s[100:101]
	s_waitcnt vmcnt(14)
	v_lshlrev_b32_e32 v166, 16, v196
	v_and_b32_e32 v167, 0xffff0000, v196
	v_lshlrev_b32_e32 v168, 16, v197
	v_and_b32_e32 v169, 0xffff0000, v197
	v_lshlrev_b32_e32 v170, 16, v198
	v_and_b32_e32 v171, 0xffff0000, v198
	v_lshlrev_b32_e32 v172, 16, v199
	v_and_b32_e32 v173, 0xffff0000, v199
	v_pk_add_f32 v[44:45], v[44:45], v[166:167]
	v_pk_add_f32 v[46:47], v[46:47], v[168:169]
	v_pk_add_f32 v[40:41], v[40:41], v[170:171]
	v_pk_add_f32 v[42:43], v[42:43], v[172:173]
	v_cvt_pk_bf16_f32 v174, v44, v45
	v_cvt_pk_bf16_f32 v175, v46, v47
	v_cvt_pk_bf16_f32 v176, v40, v41
	v_cvt_pk_bf16_f32 v177, v42, v43
	v_pk_mul_f32 v[182:183], v[44:45], v[44:45]
	v_pk_fma_f32 v[182:183], v[46:47], v[46:47], v[182:183]
	v_pk_fma_f32 v[182:183], v[40:41], v[40:41], v[182:183]
	v_pk_fma_f32 v[182:183], v[42:43], v[42:43], v[182:183]
	global_store_dwordx4 v[186:187], v[174:177], off
	s_waitcnt vmcnt(14)
	v_lshlrev_b32_e32 v166, 16, v200
	v_and_b32_e32 v167, 0xffff0000, v200
	v_lshlrev_b32_e32 v168, 16, v201
	v_and_b32_e32 v169, 0xffff0000, v201
	v_lshlrev_b32_e32 v170, 16, v202
	v_and_b32_e32 v171, 0xffff0000, v202
	v_lshlrev_b32_e32 v172, 16, v203
	v_and_b32_e32 v173, 0xffff0000, v203
	v_pk_add_f32 v[36:37], v[36:37], v[166:167]
	v_pk_add_f32 v[38:39], v[38:39], v[168:169]
	v_pk_add_f32 v[32:33], v[32:33], v[170:171]
	v_pk_add_f32 v[34:35], v[34:35], v[172:173]
	v_cvt_pk_bf16_f32 v178, v36, v37
	v_cvt_pk_bf16_f32 v179, v38, v39
	v_cvt_pk_bf16_f32 v180, v32, v33
	v_cvt_pk_bf16_f32 v181, v34, v35
	v_pk_fma_f32 v[182:183], v[36:37], v[36:37], v[182:183]
	v_pk_fma_f32 v[182:183], v[38:39], v[38:39], v[182:183]
	v_pk_fma_f32 v[182:183], v[32:33], v[32:33], v[182:183]
	v_pk_fma_f32 v[182:183], v[34:35], v[34:35], v[182:183]
	global_store_dwordx4 v[186:187], v[178:181], off offset:256
	v_add_f32_e32 v184, v182, v183
	v_mov_b32_e32 v185, v184
	s_nop 1
	v_permlane16_swap_b32_e32 v185, v184
	v_add_f32_e32 v184, v184, v185
	v_mov_b32_e32 v185, v184
	s_nop 1
	v_permlane32_swap_b32_e32 v185, v184
	v_add_f32_e32 v184, v184, v185
	s_and_saveexec_b64 s[40:41], s[4:5]
	global_store_dword v[236:237], v184, off offset:1024
	s_or_b64 exec, exec, s[40:41]
	s_mov_b64 s[100:101], 0x50000
	v_lshl_add_u64 v[186:187], v[232:233], 0, s[100:101]
	s_waitcnt vmcnt(12)
	v_lshlrev_b32_e32 v166, 16, v204
	v_and_b32_e32 v167, 0xffff0000, v204
	v_lshlrev_b32_e32 v168, 16, v205
	v_and_b32_e32 v169, 0xffff0000, v205
	v_lshlrev_b32_e32 v170, 16, v206
	v_and_b32_e32 v171, 0xffff0000, v206
	v_lshlrev_b32_e32 v172, 16, v207
	v_and_b32_e32 v173, 0xffff0000, v207
	v_pk_add_f32 v[28:29], v[28:29], v[166:167]
	v_pk_add_f32 v[30:31], v[30:31], v[168:169]
	v_pk_add_f32 v[24:25], v[24:25], v[170:171]
	v_pk_add_f32 v[26:27], v[26:27], v[172:173]
	v_cvt_pk_bf16_f32 v174, v28, v29
	v_cvt_pk_bf16_f32 v175, v30, v31
	v_cvt_pk_bf16_f32 v176, v24, v25
	v_cvt_pk_bf16_f32 v177, v26, v27
	v_pk_mul_f32 v[182:183], v[28:29], v[28:29]
	v_pk_fma_f32 v[182:183], v[30:31], v[30:31], v[182:183]
	v_pk_fma_f32 v[182:183], v[24:25], v[24:25], v[182:183]
	v_pk_fma_f32 v[182:183], v[26:27], v[26:27], v[182:183]
	global_store_dwordx4 v[186:187], v[174:177], off
	s_waitcnt vmcnt(12)
	v_lshlrev_b32_e32 v166, 16, v208
	v_and_b32_e32 v167, 0xffff0000, v208
	v_lshlrev_b32_e32 v168, 16, v209
	v_and_b32_e32 v169, 0xffff0000, v209
	v_lshlrev_b32_e32 v170, 16, v210
	v_and_b32_e32 v171, 0xffff0000, v210
	v_lshlrev_b32_e32 v172, 16, v211
	v_and_b32_e32 v173, 0xffff0000, v211
	v_pk_add_f32 v[20:21], v[20:21], v[166:167]
	v_pk_add_f32 v[22:23], v[22:23], v[168:169]
	v_pk_add_f32 v[16:17], v[16:17], v[170:171]
	v_pk_add_f32 v[18:19], v[18:19], v[172:173]
	v_cvt_pk_bf16_f32 v178, v20, v21
	v_cvt_pk_bf16_f32 v179, v22, v23
	v_cvt_pk_bf16_f32 v180, v16, v17
	v_cvt_pk_bf16_f32 v181, v18, v19
	v_pk_fma_f32 v[182:183], v[20:21], v[20:21], v[182:183]
	v_pk_fma_f32 v[182:183], v[22:23], v[22:23], v[182:183]
	v_pk_fma_f32 v[182:183], v[16:17], v[16:17], v[182:183]
	v_pk_fma_f32 v[182:183], v[18:19], v[18:19], v[182:183]
	global_store_dwordx4 v[186:187], v[178:181], off offset:256
	v_add_f32_e32 v184, v182, v183
	v_mov_b32_e32 v185, v184
	s_nop 1
	v_permlane16_swap_b32_e32 v185, v184
	v_add_f32_e32 v184, v184, v185
	v_mov_b32_e32 v185, v184
	s_nop 1
	v_permlane32_swap_b32_e32 v185, v184
	v_add_f32_e32 v184, v184, v185
	s_and_saveexec_b64 s[40:41], s[4:5]
	global_store_dword v[236:237], v184, off offset:2048
	s_or_b64 exec, exec, s[40:41]
	s_mov_b64 s[100:101], 0x58000
	v_lshl_add_u64 v[186:187], v[232:233], 0, s[100:101]
	s_waitcnt vmcnt(10)
	v_lshlrev_b32_e32 v166, 16, v212
	v_and_b32_e32 v167, 0xffff0000, v212
	v_lshlrev_b32_e32 v168, 16, v213
	v_and_b32_e32 v169, 0xffff0000, v213
	v_lshlrev_b32_e32 v170, 16, v214
	v_and_b32_e32 v171, 0xffff0000, v214
	v_lshlrev_b32_e32 v172, 16, v215
	v_and_b32_e32 v173, 0xffff0000, v215
	v_pk_add_f32 v[12:13], v[12:13], v[166:167]
	v_pk_add_f32 v[14:15], v[14:15], v[168:169]
	v_pk_add_f32 v[8:9], v[8:9], v[170:171]
	v_pk_add_f32 v[10:11], v[10:11], v[172:173]
	v_cvt_pk_bf16_f32 v174, v12, v13
	v_cvt_pk_bf16_f32 v175, v14, v15
	v_cvt_pk_bf16_f32 v176, v8, v9
	v_cvt_pk_bf16_f32 v177, v10, v11
	v_pk_mul_f32 v[182:183], v[12:13], v[12:13]
	v_pk_fma_f32 v[182:183], v[14:15], v[14:15], v[182:183]
	v_pk_fma_f32 v[182:183], v[8:9], v[8:9], v[182:183]
	v_pk_fma_f32 v[182:183], v[10:11], v[10:11], v[182:183]
	global_store_dwordx4 v[186:187], v[174:177], off
	s_waitcnt vmcnt(10)
	v_lshlrev_b32_e32 v166, 16, v216
	v_and_b32_e32 v167, 0xffff0000, v216
	v_lshlrev_b32_e32 v168, 16, v217
	v_and_b32_e32 v169, 0xffff0000, v217
	v_lshlrev_b32_e32 v170, 16, v218
	v_and_b32_e32 v171, 0xffff0000, v218
	v_lshlrev_b32_e32 v172, 16, v219
	v_and_b32_e32 v173, 0xffff0000, v219
	v_pk_add_f32 v[4:5], v[4:5], v[166:167]
	v_pk_add_f32 v[6:7], v[6:7], v[168:169]
	v_pk_add_f32 v[0:1], v[0:1], v[170:171]
	v_pk_add_f32 v[2:3], v[2:3], v[172:173]
	v_cvt_pk_bf16_f32 v178, v4, v5
	v_cvt_pk_bf16_f32 v179, v6, v7
	v_cvt_pk_bf16_f32 v180, v0, v1
	v_cvt_pk_bf16_f32 v181, v2, v3
	v_pk_fma_f32 v[182:183], v[4:5], v[4:5], v[182:183]
	v_pk_fma_f32 v[182:183], v[6:7], v[6:7], v[182:183]
	v_pk_fma_f32 v[182:183], v[0:1], v[0:1], v[182:183]
	v_pk_fma_f32 v[182:183], v[2:3], v[2:3], v[182:183]
	global_store_dwordx4 v[186:187], v[178:181], off offset:256
	v_add_f32_e32 v184, v182, v183
	v_mov_b32_e32 v185, v184
	s_nop 1
	v_permlane16_swap_b32_e32 v185, v184
	v_add_f32_e32 v184, v184, v185
	v_mov_b32_e32 v185, v184
	s_nop 1
	v_permlane32_swap_b32_e32 v185, v184
	v_add_f32_e32 v184, v184, v185
	s_and_saveexec_b64 s[40:41], s[4:5]
	global_store_dword v[236:237], v184, off offset:3072
	s_or_b64 exec, exec, s[40:41]
	s_andn2_b64 vcc, exec, s[6:7]
	s_mov_b64 s[6:7], -1
	s_cbranch_vccnz .LBB0_961
	s_andn2_b64 vcc, exec, s[8:9]
	s_cbranch_vccnz .LBB0_960
	s_nop 0
	s_branch .LBB0_960

.LBB0_1148:
	v_lshl_add_u32 v150, s12, 8, v131
	v_ashrrev_i32_e32 v151, 31, v150
	v_lshl_or_b32 v148, s8, 8, v153
	v_lshlrev_b64 v[160:161], 11, v[150:151]
	v_ashrrev_i32_e32 v149, 31, v148
	v_lshl_add_u64 v[160:161], s[14:15], 0, v[160:161]
	v_lshl_add_u64 v[164:165], v[148:149], 1, v[160:161]
	v_mov_b32_e32 v232, v164
	v_mov_b32_e32 v233, v165
	global_load_dwordx4 v[188:191], v[232:233], off
	global_load_dwordx4 v[192:195], v[232:233], off offset:256
	s_mov_b64 s[100:101], 0x8000
	v_lshl_add_u64 v[230:231], v[232:233], 0, s[100:101]
	global_load_dwordx4 v[196:199], v[230:231], off
	global_load_dwordx4 v[200:203], v[230:231], off offset:256
	s_mov_b64 s[100:101], 0x10000
	v_lshl_add_u64 v[230:231], v[232:233], 0, s[100:101]
	global_load_dwordx4 v[204:207], v[230:231], off
	global_load_dwordx4 v[208:211], v[230:231], off offset:256
	s_mov_b64 s[100:101], 0x18000
	v_lshl_add_u64 v[230:231], v[232:233], 0, s[100:101]
	global_load_dwordx4 v[212:215], v[230:231], off
	global_load_dwordx4 v[216:219], v[230:231], off offset:256
	s_lshl_b32 s30, s8, 2
	s_ashr_i32 s31, s30, 31
	v_lshlrev_b64 v[234:235], 6, v[150:151]
	v_lshl_add_u64 v[234:235], s[18:19], 0, v[234:235]
	v_lshl_add_u64 v[234:235], s[30:31], 2, v[234:235]
	s_lshl_b32 s100, s50, 2
	s_mov_b32 s101, 0
	v_lshl_add_u64 v[234:235], v[234:235], 0, s[100:101]
	s_mov_b64 s[100:101], 0x2000
	v_lshl_add_u64 v[236:237], v[234:235], 0, s[100:101]
	s_waitcnt vmcnt(7)
	v_lshlrev_b32_e32 v166, 16, v188
	v_and_b32_e32 v167, 0xffff0000, v188
	v_lshlrev_b32_e32 v168, 16, v189
	v_and_b32_e32 v169, 0xffff0000, v189
	v_lshlrev_b32_e32 v170, 16, v190
	v_and_b32_e32 v171, 0xffff0000, v190
	v_lshlrev_b32_e32 v172, 16, v191
	v_and_b32_e32 v173, 0xffff0000, v191
	v_pk_add_f32 v[124:125], v[124:125], v[166:167]
	v_pk_add_f32 v[126:127], v[126:127], v[168:169]
	v_pk_add_f32 v[120:121], v[120:121], v[170:171]
	v_pk_add_f32 v[122:123], v[122:123], v[172:173]
	v_cvt_pk_bf16_f32 v174, v124, v125
	v_cvt_pk_bf16_f32 v175, v126, v127
	v_cvt_pk_bf16_f32 v176, v120, v121
	v_cvt_pk_bf16_f32 v177, v122, v123
	v_pk_mul_f32 v[182:183], v[124:125], v[124:125]
	v_pk_fma_f32 v[182:183], v[126:127], v[126:127], v[182:183]
	v_pk_fma_f32 v[182:183], v[120:121], v[120:121], v[182:183]
	v_pk_fma_f32 v[182:183], v[122:123], v[122:123], v[182:183]
	global_store_dwordx4 v[232:233], v[174:177], off
	s_waitcnt vmcnt(7)
	v_lshlrev_b32_e32 v166, 16, v192
	v_and_b32_e32 v167, 0xffff0000, v192
	v_lshlrev_b32_e32 v168, 16, v193
	v_and_b32_e32 v169, 0xffff0000, v193
	v_lshlrev_b32_e32 v170, 16, v194
	v_and_b32_e32 v171, 0xffff0000, v194
	v_lshlrev_b32_e32 v172, 16, v195
	v_and_b32_e32 v173, 0xffff0000, v195
	v_pk_add_f32 v[116:117], v[116:117], v[166:167]
	v_pk_add_f32 v[118:119], v[118:119], v[168:169]
	v_pk_add_f32 v[112:113], v[112:113], v[170:171]
	v_pk_add_f32 v[114:115], v[114:115], v[172:173]
	v_cvt_pk_bf16_f32 v178, v116, v117
	v_cvt_pk_bf16_f32 v179, v118, v119
	v_cvt_pk_bf16_f32 v180, v112, v113
	v_cvt_pk_bf16_f32 v181, v114, v115
	v_pk_fma_f32 v[182:183], v[116:117], v[116:117], v[182:183]
	v_pk_fma_f32 v[182:183], v[118:119], v[118:119], v[182:183]
	v_pk_fma_f32 v[182:183], v[112:113], v[112:113], v[182:183]
	v_pk_fma_f32 v[182:183], v[114:115], v[114:115], v[182:183]
	global_store_dwordx4 v[232:233], v[178:181], off offset:256
	v_add_f32_e32 v184, v182, v183
	v_mov_b32_e32 v185, v184
	s_nop 1
	v_permlane16_swap_b32_e32 v185, v184
	v_add_f32_e32 v184, v184, v185
	v_mov_b32_e32 v185, v184
	s_nop 1
	v_permlane32_swap_b32_e32 v185, v184
	v_add_f32_e32 v184, v184, v185
	s_and_saveexec_b64 s[36:37], s[4:5]
	global_store_dword v[234:235], v184, off
	s_or_b64 exec, exec, s[36:37]
	s_mov_b64 s[100:101], 0x40000
	v_lshl_add_u64 v[230:231], v[232:233], 0, s[100:101]
	global_load_dwordx4 v[188:191], v[230:231], off
	global_load_dwordx4 v[192:195], v[230:231], off offset:256
	s_mov_b64 s[100:101], 0x8000
	v_lshl_add_u64 v[186:187], v[232:233], 0, s[100:101]
	s_waitcnt vmcnt(10)
	v_lshlrev_b32_e32 v166, 16, v196
	v_and_b32_e32 v167, 0xffff0000, v196
	v_lshlrev_b32_e32 v168, 16, v197
	v_and_b32_e32 v169, 0xffff0000, v197
	v_lshlrev_b32_e32 v170, 16, v198
	v_and_b32_e32 v171, 0xffff0000, v198
	v_lshlrev_b32_e32 v172, 16, v199
	v_and_b32_e32 v173, 0xffff0000, v199
	v_pk_add_f32 v[108:109], v[108:109], v[166:167]
	v_pk_add_f32 v[110:111], v[110:111], v[168:169]
	v_pk_add_f32 v[104:105], v[104:105], v[170:171]
	v_pk_add_f32 v[106:107], v[106:107], v[172:173]
	v_cvt_pk_bf16_f32 v174, v108, v109
	v_cvt_pk_bf16_f32 v175, v110, v111
	v_cvt_pk_bf16_f32 v176, v104, v105
	v_cvt_pk_bf16_f32 v177, v106, v107
	v_pk_mul_f32 v[182:183], v[108:109], v[108:109]
	v_pk_fma_f32 v[182:183], v[110:111], v[110:111], v[182:183]
	v_pk_fma_f32 v[182:183], v[104:105], v[104:105], v[182:183]
	v_pk_fma_f32 v[182:183], v[106:107], v[106:107], v[182:183]
	global_store_dwordx4 v[186:187], v[174:177], off
	s_waitcnt vmcnt(10)
	v_lshlrev_b32_e32 v166, 16, v200
	v_and_b32_e32 v167, 0xffff0000, v200
	v_lshlrev_b32_e32 v168, 16, v201
	v_and_b32_e32 v169, 0xffff0000, v201
	v_lshlrev_b32_e32 v170, 16, v202
	v_and_b32_e32 v171, 0xffff0000, v202
	v_lshlrev_b32_e32 v172, 16, v203
	v_and_b32_e32 v173, 0xffff0000, v203
	v_pk_add_f32 v[100:101], v[100:101], v[166:167]
	v_pk_add_f32 v[102:103], v[102:103], v[168:169]
	v_pk_add_f32 v[96:97], v[96:97], v[170:171]
	v_pk_add_f32 v[98:99], v[98:99], v[172:173]
	v_cvt_pk_bf16_f32 v178, v100, v101
	v_cvt_pk_bf16_f32 v179, v102, v103
	v_cvt_pk_bf16_f32 v180, v96, v97
	v_cvt_pk_bf16_f32 v181, v98, v99
	v_pk_fma_f32 v[182:183], v[100:101], v[100:101], v[182:183]
	v_pk_fma_f32 v[182:183], v[102:103], v[102:103], v[182:183]
	v_pk_fma_f32 v[182:183], v[96:97], v[96:97], v[182:183]
	v_pk_fma_f32 v[182:183], v[98:99], v[98:99], v[182:183]
	global_store_dwordx4 v[186:187], v[178:181], off offset:256
	v_add_f32_e32 v184, v182, v183
	v_mov_b32_e32 v185, v184
	s_nop 1
	v_permlane16_swap_b32_e32 v185, v184
	v_add_f32_e32 v184, v184, v185
	v_mov_b32_e32 v185, v184
	s_nop 1
	v_permlane32_swap_b32_e32 v185, v184
	v_add_f32_e32 v184, v184, v185
	s_and_saveexec_b64 s[36:37], s[4:5]
	global_store_dword v[234:235], v184, off offset:1024
	s_or_b64 exec, exec, s[36:37]
	s_mov_b64 s[100:101], 0x48000
	v_lshl_add_u64 v[230:231], v[232:233], 0, s[100:101]
	global_load_dwordx4 v[196:199], v[230:231], off
	global_load_dwordx4 v[200:203], v[230:231], off offset:256
	s_mov_b64 s[100:101], 0x10000
	v_lshl_add_u64 v[186:187], v[232:233], 0, s[100:101]
	s_waitcnt vmcnt(13)
	v_lshlrev_b32_e32 v166, 16, v204
	v_and_b32_e32 v167, 0xffff0000, v204
	v_lshlrev_b32_e32 v168, 16, v205
	v_and_b32_e32 v169, 0xffff0000, v205
	v_lshlrev_b32_e32 v170, 16, v206
	v_and_b32_e32 v171, 0xffff0000, v206
	v_lshlrev_b32_e32 v172, 16, v207
	v_and_b32_e32 v173, 0xffff0000, v207
	v_pk_add_f32 v[92:93], v[92:93], v[166:167]
	v_pk_add_f32 v[94:95], v[94:95], v[168:169]
	v_pk_add_f32 v[88:89], v[88:89], v[170:171]
	v_pk_add_f32 v[90:91], v[90:91], v[172:173]
	v_cvt_pk_bf16_f32 v174, v92, v93
	v_cvt_pk_bf16_f32 v175, v94, v95
	v_cvt_pk_bf16_f32 v176, v88, v89
	v_cvt_pk_bf16_f32 v177, v90, v91
	v_pk_mul_f32 v[182:183], v[92:93], v[92:93]
	v_pk_fma_f32 v[182:183], v[94:95], v[94:95], v[182:183]
	v_pk_fma_f32 v[182:183], v[88:89], v[88:89], v[182:183]
	v_pk_fma_f32 v[182:183], v[90:91], v[90:91], v[182:183]
	global_store_dwordx4 v[186:187], v[174:177], off
	s_waitcnt vmcnt(13)
	v_lshlrev_b32_e32 v166, 16, v208
	v_and_b32_e32 v167, 0xffff0000, v208
	v_lshlrev_b32_e32 v168, 16, v209
	v_and_b32_e32 v169, 0xffff0000, v209
	v_lshlrev_b32_e32 v170, 16, v210
	v_and_b32_e32 v171, 0xffff0000, v210
	v_lshlrev_b32_e32 v172, 16, v211
	v_and_b32_e32 v173, 0xffff0000, v211
	v_pk_add_f32 v[84:85], v[84:85], v[166:167]
	v_pk_add_f32 v[86:87], v[86:87], v[168:169]
	v_pk_add_f32 v[80:81], v[80:81], v[170:171]
	v_pk_add_f32 v[82:83], v[82:83], v[172:173]
	v_cvt_pk_bf16_f32 v178, v84, v85
	v_cvt_pk_bf16_f32 v179, v86, v87
	v_cvt_pk_bf16_f32 v180, v80, v81
	v_cvt_pk_bf16_f32 v181, v82, v83
	v_pk_fma_f32 v[182:183], v[84:85], v[84:85], v[182:183]
	v_pk_fma_f32 v[182:183], v[86:87], v[86:87], v[182:183]
	v_pk_fma_f32 v[182:183], v[80:81], v[80:81], v[182:183]
	v_pk_fma_f32 v[182:183], v[82:83], v[82:83], v[182:183]
	global_store_dwordx4 v[186:187], v[178:181], off offset:256
	v_add_f32_e32 v184, v182, v183
	v_mov_b32_e32 v185, v184
	s_nop 1
	v_permlane16_swap_b32_e32 v185, v184
	v_add_f32_e32 v184, v184, v185
	v_mov_b32_e32 v185, v184
	s_nop 1
	v_permlane32_swap_b32_e32 v185, v184
	v_add_f32_e32 v184, v184, v185
	s_and_saveexec_b64 s[36:37], s[4:5]
	global_store_dword v[234:235], v184, off offset:2048
	s_or_b64 exec, exec, s[36:37]
	s_mov_b64 s[100:101], 0x50000
	v_lshl_add_u64 v[230:231], v[232:233], 0, s[100:101]
	global_load_dwordx4 v[204:207], v[230:231], off
	global_load_dwordx4 v[208:211], v[230:231], off offset:256
	s_mov_b64 s[100:101], 0x18000
	v_lshl_add_u64 v[186:187], v[232:233], 0, s[100:101]
	s_waitcnt vmcnt(16)
	v_lshlrev_b32_e32 v166, 16, v212
	v_and_b32_e32 v167, 0xffff0000, v212
	v_lshlrev_b32_e32 v168, 16, v213
	v_and_b32_e32 v169, 0xffff0000, v213
	v_lshlrev_b32_e32 v170, 16, v214
	v_and_b32_e32 v171, 0xffff0000, v214
	v_lshlrev_b32_e32 v172, 16, v215
	v_and_b32_e32 v173, 0xffff0000, v215
	v_pk_add_f32 v[76:77], v[76:77], v[166:167]
	v_pk_add_f32 v[78:79], v[78:79], v[168:169]
	v_pk_add_f32 v[72:73], v[72:73], v[170:171]
	v_pk_add_f32 v[74:75], v[74:75], v[172:173]
	v_cvt_pk_bf16_f32 v174, v76, v77
	v_cvt_pk_bf16_f32 v175, v78, v79
	v_cvt_pk_bf16_f32 v176, v72, v73
	v_cvt_pk_bf16_f32 v177, v74, v75
	v_pk_mul_f32 v[182:183], v[76:77], v[76:77]
	v_pk_fma_f32 v[182:183], v[78:79], v[78:79], v[182:183]
	v_pk_fma_f32 v[182:183], v[72:73], v[72:73], v[182:183]
	v_pk_fma_f32 v[182:183], v[74:75], v[74:75], v[182:183]
	global_store_dwordx4 v[186:187], v[174:177], off
	s_waitcnt vmcnt(16)
	v_lshlrev_b32_e32 v166, 16, v216
	v_and_b32_e32 v167, 0xffff0000, v216
	v_lshlrev_b32_e32 v168, 16, v217
	v_and_b32_e32 v169, 0xffff0000, v217
	v_lshlrev_b32_e32 v170, 16, v218
	v_and_b32_e32 v171, 0xffff0000, v218
	v_lshlrev_b32_e32 v172, 16, v219
	v_and_b32_e32 v173, 0xffff0000, v219
	v_pk_add_f32 v[68:69], v[68:69], v[166:167]
	v_pk_add_f32 v[70:71], v[70:71], v[168:169]
	v_pk_add_f32 v[64:65], v[64:65], v[170:171]
	v_pk_add_f32 v[66:67], v[66:67], v[172:173]
	v_cvt_pk_bf16_f32 v178, v68, v69
	v_cvt_pk_bf16_f32 v179, v70, v71
	v_cvt_pk_bf16_f32 v180, v64, v65
	v_cvt_pk_bf16_f32 v181, v66, v67
	v_pk_fma_f32 v[182:183], v[68:69], v[68:69], v[182:183]
	v_pk_fma_f32 v[182:183], v[70:71], v[70:71], v[182:183]
	v_pk_fma_f32 v[182:183], v[64:65], v[64:65], v[182:183]
	v_pk_fma_f32 v[182:183], v[66:67], v[66:67], v[182:183]
	global_store_dwordx4 v[186:187], v[178:181], off offset:256
	v_add_f32_e32 v184, v182, v183
	v_mov_b32_e32 v185, v184
	s_nop 1
	v_permlane16_swap_b32_e32 v185, v184
	v_add_f32_e32 v184, v184, v185
	v_mov_b32_e32 v185, v184
	s_nop 1
	v_permlane32_swap_b32_e32 v185, v184
	v_add_f32_e32 v184, v184, v185
	s_and_saveexec_b64 s[36:37], s[4:5]
	global_store_dword v[234:235], v184, off offset:3072
	s_or_b64 exec, exec, s[36:37]
	s_mov_b64 s[100:101], 0x58000
	v_lshl_add_u64 v[230:231], v[232:233], 0, s[100:101]
	global_load_dwordx4 v[212:215], v[230:231], off
	global_load_dwordx4 v[216:219], v[230:231], off offset:256
	s_mov_b64 s[100:101], 0x40000
	v_lshl_add_u64 v[186:187], v[232:233], 0, s[100:101]
	s_waitcnt vmcnt(16)
	v_lshlrev_b32_e32 v166, 16, v188
	v_and_b32_e32 v167, 0xffff0000, v188
	v_lshlrev_b32_e32 v168, 16, v189
	v_and_b32_e32 v169, 0xffff0000, v189
	v_lshlrev_b32_e32 v170, 16, v190
	v_and_b32_e32 v171, 0xffff0000, v190
	v_lshlrev_b32_e32 v172, 16, v191
	v_and_b32_e32 v173, 0xffff0000, v191
	v_pk_add_f32 v[60:61], v[60:61], v[166:167]
	v_pk_add_f32 v[62:63], v[62:63], v[168:169]
	v_pk_add_f32 v[56:57], v[56:57], v[170:171]
	v_pk_add_f32 v[58:59], v[58:59], v[172:173]
	v_cvt_pk_bf16_f32 v174, v60, v61
	v_cvt_pk_bf16_f32 v175, v62, v63
	v_cvt_pk_bf16_f32 v176, v56, v57
	v_cvt_pk_bf16_f32 v177, v58, v59
	v_pk_mul_f32 v[182:183], v[60:61], v[60:61]
	v_pk_fma_f32 v[182:183], v[62:63], v[62:63], v[182:183]
	v_pk_fma_f32 v[182:183], v[56:57], v[56:57], v[182:183]
	v_pk_fma_f32 v[182:183], v[58:59], v[58:59], v[182:183]
	global_store_dwordx4 v[186:187], v[174:177], off
	s_waitcnt vmcnt(16)
	v_lshlrev_b32_e32 v166, 16, v192
	v_and_b32_e32 v167, 0xffff0000, v192
	v_lshlrev_b32_e32 v168, 16, v193
	v_and_b32_e32 v169, 0xffff0000, v193
	v_lshlrev_b32_e32 v170, 16, v194
	v_and_b32_e32 v171, 0xffff0000, v194
	v_lshlrev_b32_e32 v172, 16, v195
	v_and_b32_e32 v173, 0xffff0000, v195
	v_pk_add_f32 v[52:53], v[52:53], v[166:167]
	v_pk_add_f32 v[54:55], v[54:55], v[168:169]
	v_pk_add_f32 v[48:49], v[48:49], v[170:171]
	v_pk_add_f32 v[50:51], v[50:51], v[172:173]
	v_cvt_pk_bf16_f32 v178, v52, v53
	v_cvt_pk_bf16_f32 v179, v54, v55
	v_cvt_pk_bf16_f32 v180, v48, v49
	v_cvt_pk_bf16_f32 v181, v50, v51
	v_pk_fma_f32 v[182:183], v[52:53], v[52:53], v[182:183]
	v_pk_fma_f32 v[182:183], v[54:55], v[54:55], v[182:183]
	v_pk_fma_f32 v[182:183], v[48:49], v[48:49], v[182:183]
	v_pk_fma_f32 v[182:183], v[50:51], v[50:51], v[182:183]
	global_store_dwordx4 v[186:187], v[178:181], off offset:256
	v_add_f32_e32 v184, v182, v183
	v_mov_b32_e32 v185, v184
	s_nop 1
	v_permlane16_swap_b32_e32 v185, v184
	v_add_f32_e32 v184, v184, v185
	v_mov_b32_e32 v185, v184
	s_nop 1
	v_permlane32_swap_b32_e32 v185, v184
	v_add_f32_e32 v184, v184, v185
	s_and_saveexec_b64 s[36:37], s[4:5]
	global_store_dword v[236:237], v184, off
	s_or_b64 exec, exec, s[36:37]
	s_mov_b64 s[100:101], 0x48000
	v_lshl_add_u64 v[186:187], v[232:233], 0, s[100:101]
	s_waitcnt vmcnt(14)
	v_lshlrev_b32_e32 v166, 16, v196
	v_and_b32_e32 v167, 0xffff0000, v196
	v_lshlrev_b32_e32 v168, 16, v197
	v_and_b32_e32 v169, 0xffff0000, v197
	v_lshlrev_b32_e32 v170, 16, v198
	v_and_b32_e32 v171, 0xffff0000, v198
	v_lshlrev_b32_e32 v172, 16, v199
	v_and_b32_e32 v173, 0xffff0000, v199
	v_pk_add_f32 v[44:45], v[44:45], v[166:167]
	v_pk_add_f32 v[46:47], v[46:47], v[168:169]
	v_pk_add_f32 v[40:41], v[40:41], v[170:171]
	v_pk_add_f32 v[42:43], v[42:43], v[172:173]
	v_cvt_pk_bf16_f32 v174, v44, v45
	v_cvt_pk_bf16_f32 v175, v46, v47
	v_cvt_pk_bf16_f32 v176, v40, v41
	v_cvt_pk_bf16_f32 v177, v42, v43
	v_pk_mul_f32 v[182:183], v[44:45], v[44:45]
	v_pk_fma_f32 v[182:183], v[46:47], v[46:47], v[182:183]
	v_pk_fma_f32 v[182:183], v[40:41], v[40:41], v[182:183]
	v_pk_fma_f32 v[182:183], v[42:43], v[42:43], v[182:183]
	global_store_dwordx4 v[186:187], v[174:177], off
	s_waitcnt vmcnt(14)
	v_lshlrev_b32_e32 v166, 16, v200
	v_and_b32_e32 v167, 0xffff0000, v200
	v_lshlrev_b32_e32 v168, 16, v201
	v_and_b32_e32 v169, 0xffff0000, v201
	v_lshlrev_b32_e32 v170, 16, v202
	v_and_b32_e32 v171, 0xffff0000, v202
	v_lshlrev_b32_e32 v172, 16, v203
	v_and_b32_e32 v173, 0xffff0000, v203
	v_pk_add_f32 v[36:37], v[36:37], v[166:167]
	v_pk_add_f32 v[38:39], v[38:39], v[168:169]
	v_pk_add_f32 v[32:33], v[32:33], v[170:171]
	v_pk_add_f32 v[34:35], v[34:35], v[172:173]
	v_cvt_pk_bf16_f32 v178, v36, v37
	v_cvt_pk_bf16_f32 v179, v38, v39
	v_cvt_pk_bf16_f32 v180, v32, v33
	v_cvt_pk_bf16_f32 v181, v34, v35
	v_pk_fma_f32 v[182:183], v[36:37], v[36:37], v[182:183]
	v_pk_fma_f32 v[182:183], v[38:39], v[38:39], v[182:183]
	v_pk_fma_f32 v[182:183], v[32:33], v[32:33], v[182:183]
	v_pk_fma_f32 v[182:183], v[34:35], v[34:35], v[182:183]
	global_store_dwordx4 v[186:187], v[178:181], off offset:256
	v_add_f32_e32 v184, v182, v183
	v_mov_b32_e32 v185, v184
	s_nop 1
	v_permlane16_swap_b32_e32 v185, v184
	v_add_f32_e32 v184, v184, v185
	v_mov_b32_e32 v185, v184
	s_nop 1
	v_permlane32_swap_b32_e32 v185, v184
	v_add_f32_e32 v184, v184, v185
	s_and_saveexec_b64 s[36:37], s[4:5]
	global_store_dword v[236:237], v184, off offset:1024
	s_or_b64 exec, exec, s[36:37]
	s_mov_b64 s[100:101], 0x50000
	v_lshl_add_u64 v[186:187], v[232:233], 0, s[100:101]
	s_waitcnt vmcnt(12)
	v_lshlrev_b32_e32 v166, 16, v204
	v_and_b32_e32 v167, 0xffff0000, v204
	v_lshlrev_b32_e32 v168, 16, v205
	v_and_b32_e32 v169, 0xffff0000, v205
	v_lshlrev_b32_e32 v170, 16, v206
	v_and_b32_e32 v171, 0xffff0000, v206
	v_lshlrev_b32_e32 v172, 16, v207
	v_and_b32_e32 v173, 0xffff0000, v207
	v_pk_add_f32 v[28:29], v[28:29], v[166:167]
	v_pk_add_f32 v[30:31], v[30:31], v[168:169]
	v_pk_add_f32 v[24:25], v[24:25], v[170:171]
	v_pk_add_f32 v[26:27], v[26:27], v[172:173]
	v_cvt_pk_bf16_f32 v174, v28, v29
	v_cvt_pk_bf16_f32 v175, v30, v31
	v_cvt_pk_bf16_f32 v176, v24, v25
	v_cvt_pk_bf16_f32 v177, v26, v27
	v_pk_mul_f32 v[182:183], v[28:29], v[28:29]
	v_pk_fma_f32 v[182:183], v[30:31], v[30:31], v[182:183]
	v_pk_fma_f32 v[182:183], v[24:25], v[24:25], v[182:183]
	v_pk_fma_f32 v[182:183], v[26:27], v[26:27], v[182:183]
	global_store_dwordx4 v[186:187], v[174:177], off
	s_waitcnt vmcnt(12)
	v_lshlrev_b32_e32 v166, 16, v208
	v_and_b32_e32 v167, 0xffff0000, v208
	v_lshlrev_b32_e32 v168, 16, v209
	v_and_b32_e32 v169, 0xffff0000, v209
	v_lshlrev_b32_e32 v170, 16, v210
	v_and_b32_e32 v171, 0xffff0000, v210
	v_lshlrev_b32_e32 v172, 16, v211
	v_and_b32_e32 v173, 0xffff0000, v211
	v_pk_add_f32 v[20:21], v[20:21], v[166:167]
	v_pk_add_f32 v[22:23], v[22:23], v[168:169]
	v_pk_add_f32 v[16:17], v[16:17], v[170:171]
	v_pk_add_f32 v[18:19], v[18:19], v[172:173]
	v_cvt_pk_bf16_f32 v178, v20, v21
	v_cvt_pk_bf16_f32 v179, v22, v23
	v_cvt_pk_bf16_f32 v180, v16, v17
	v_cvt_pk_bf16_f32 v181, v18, v19
	v_pk_fma_f32 v[182:183], v[20:21], v[20:21], v[182:183]
	v_pk_fma_f32 v[182:183], v[22:23], v[22:23], v[182:183]
	v_pk_fma_f32 v[182:183], v[16:17], v[16:17], v[182:183]
	v_pk_fma_f32 v[182:183], v[18:19], v[18:19], v[182:183]
	global_store_dwordx4 v[186:187], v[178:181], off offset:256
	v_add_f32_e32 v184, v182, v183
	v_mov_b32_e32 v185, v184
	s_nop 1
	v_permlane16_swap_b32_e32 v185, v184
	v_add_f32_e32 v184, v184, v185
	v_mov_b32_e32 v185, v184
	s_nop 1
	v_permlane32_swap_b32_e32 v185, v184
	v_add_f32_e32 v184, v184, v185
	s_and_saveexec_b64 s[36:37], s[4:5]
	global_store_dword v[236:237], v184, off offset:2048
	s_or_b64 exec, exec, s[36:37]
	s_mov_b64 s[100:101], 0x58000
	v_lshl_add_u64 v[186:187], v[232:233], 0, s[100:101]
	s_waitcnt vmcnt(10)
	v_lshlrev_b32_e32 v166, 16, v212
	v_and_b32_e32 v167, 0xffff0000, v212
	v_lshlrev_b32_e32 v168, 16, v213
	v_and_b32_e32 v169, 0xffff0000, v213
	v_lshlrev_b32_e32 v170, 16, v214
	v_and_b32_e32 v171, 0xffff0000, v214
	v_lshlrev_b32_e32 v172, 16, v215
	v_and_b32_e32 v173, 0xffff0000, v215
	v_pk_add_f32 v[12:13], v[12:13], v[166:167]
	v_pk_add_f32 v[14:15], v[14:15], v[168:169]
	v_pk_add_f32 v[8:9], v[8:9], v[170:171]
	v_pk_add_f32 v[10:11], v[10:11], v[172:173]
	v_cvt_pk_bf16_f32 v174, v12, v13
	v_cvt_pk_bf16_f32 v175, v14, v15
	v_cvt_pk_bf16_f32 v176, v8, v9
	v_cvt_pk_bf16_f32 v177, v10, v11
	v_pk_mul_f32 v[182:183], v[12:13], v[12:13]
	v_pk_fma_f32 v[182:183], v[14:15], v[14:15], v[182:183]
	v_pk_fma_f32 v[182:183], v[8:9], v[8:9], v[182:183]
	v_pk_fma_f32 v[182:183], v[10:11], v[10:11], v[182:183]
	global_store_dwordx4 v[186:187], v[174:177], off
	s_waitcnt vmcnt(10)
	v_lshlrev_b32_e32 v166, 16, v216
	v_and_b32_e32 v167, 0xffff0000, v216
	v_lshlrev_b32_e32 v168, 16, v217
	v_and_b32_e32 v169, 0xffff0000, v217
	v_lshlrev_b32_e32 v170, 16, v218
	v_and_b32_e32 v171, 0xffff0000, v218
	v_lshlrev_b32_e32 v172, 16, v219
	v_and_b32_e32 v173, 0xffff0000, v219
	v_pk_add_f32 v[4:5], v[4:5], v[166:167]
	v_pk_add_f32 v[6:7], v[6:7], v[168:169]
	v_pk_add_f32 v[0:1], v[0:1], v[170:171]
	v_pk_add_f32 v[2:3], v[2:3], v[172:173]
	v_cvt_pk_bf16_f32 v178, v4, v5
	v_cvt_pk_bf16_f32 v179, v6, v7
	v_cvt_pk_bf16_f32 v180, v0, v1
	v_cvt_pk_bf16_f32 v181, v2, v3
	v_pk_fma_f32 v[182:183], v[4:5], v[4:5], v[182:183]
	v_pk_fma_f32 v[182:183], v[6:7], v[6:7], v[182:183]
	v_pk_fma_f32 v[182:183], v[0:1], v[0:1], v[182:183]
	v_pk_fma_f32 v[182:183], v[2:3], v[2:3], v[182:183]
	global_store_dwordx4 v[186:187], v[178:181], off offset:256
	v_add_f32_e32 v184, v182, v183
	v_mov_b32_e32 v185, v184
	s_nop 1
	v_permlane16_swap_b32_e32 v185, v184
	v_add_f32_e32 v184, v184, v185
	v_mov_b32_e32 v185, v184
	s_nop 1
	v_permlane32_swap_b32_e32 v185, v184
	v_add_f32_e32 v184, v184, v185
	s_and_saveexec_b64 s[36:37], s[4:5]
	global_store_dword v[236:237], v184, off offset:3072
	s_or_b64 exec, exec, s[36:37]
	s_and_b64 vcc, exec, s[6:7]
	s_mov_b64 s[6:7], -1
	s_cbranch_vccnz .LBB0_1133
	s_andn2_b64 vcc, exec, s[10:11]
	s_cbranch_vccnz .LBB0_1132
	s_nop 0
	s_branch .LBB0_1132

.LBB0_1560:
	v_lshl_add_u32 v148, s38, 8, v150
	v_ashrrev_i32_e32 v149, 31, v148
	v_lshl_or_b32 v146, s0, 8, v152
	v_lshlrev_b64 v[158:159], 11, v[148:149]
	v_ashrrev_i32_e32 v147, 31, v146
	v_lshl_add_u64 v[158:159], s[14:15], 0, v[158:159]
	v_lshl_add_u64 v[162:163], v[146:147], 1, v[158:159]
	v_mov_b32_e32 v232, v162
	v_mov_b32_e32 v233, v163
	global_load_dwordx4 v[188:191], v[232:233], off
	global_load_dwordx4 v[192:195], v[232:233], off offset:256
	s_mov_b64 s[100:101], 0x8000
	v_lshl_add_u64 v[230:231], v[232:233], 0, s[100:101]
	global_load_dwordx4 v[196:199], v[230:231], off
	global_load_dwordx4 v[200:203], v[230:231], off offset:256
	s_mov_b64 s[100:101], 0x10000
	v_lshl_add_u64 v[230:231], v[232:233], 0, s[100:101]
	global_load_dwordx4 v[204:207], v[230:231], off
	global_load_dwordx4 v[208:211], v[230:231], off offset:256
	s_mov_b64 s[100:101], 0x18000
	v_lshl_add_u64 v[230:231], v[232:233], 0, s[100:101]
	global_load_dwordx4 v[212:215], v[230:231], off
	global_load_dwordx4 v[216:219], v[230:231], off offset:256
	s_lshl_b32 s38, s0, 2
	s_ashr_i32 s39, s38, 31
	v_lshlrev_b64 v[234:235], 6, v[148:149]
	v_lshl_add_u64 v[234:235], s[18:19], 0, v[234:235]
	v_lshl_add_u64 v[234:235], s[38:39], 2, v[234:235]
	s_lshl_b32 s100, s52, 2
	s_mov_b32 s101, 0
	v_lshl_add_u64 v[234:235], v[234:235], 0, s[100:101]
	s_mov_b64 s[100:101], 0x2000
	v_lshl_add_u64 v[236:237], v[234:235], 0, s[100:101]
	s_waitcnt vmcnt(7)
	v_lshlrev_b32_e32 v166, 16, v188
	v_and_b32_e32 v167, 0xffff0000, v188
	v_lshlrev_b32_e32 v168, 16, v189
	v_and_b32_e32 v169, 0xffff0000, v189
	v_lshlrev_b32_e32 v170, 16, v190
	v_and_b32_e32 v171, 0xffff0000, v190
	v_lshlrev_b32_e32 v172, 16, v191
	v_and_b32_e32 v173, 0xffff0000, v191
	v_pk_add_f32 v[124:125], v[124:125], v[166:167]
	v_pk_add_f32 v[126:127], v[126:127], v[168:169]
	v_pk_add_f32 v[120:121], v[120:121], v[170:171]
	v_pk_add_f32 v[122:123], v[122:123], v[172:173]
	v_cvt_pk_bf16_f32 v174, v124, v125
	v_cvt_pk_bf16_f32 v175, v126, v127
	v_cvt_pk_bf16_f32 v176, v120, v121
	v_cvt_pk_bf16_f32 v177, v122, v123
	v_pk_mul_f32 v[182:183], v[124:125], v[124:125]
	v_pk_fma_f32 v[182:183], v[126:127], v[126:127], v[182:183]
	v_pk_fma_f32 v[182:183], v[120:121], v[120:121], v[182:183]
	v_pk_fma_f32 v[182:183], v[122:123], v[122:123], v[182:183]
	global_store_dwordx4 v[232:233], v[174:177], off
	s_waitcnt vmcnt(7)
	v_lshlrev_b32_e32 v166, 16, v192
	v_and_b32_e32 v167, 0xffff0000, v192
	v_lshlrev_b32_e32 v168, 16, v193
	v_and_b32_e32 v169, 0xffff0000, v193
	v_lshlrev_b32_e32 v170, 16, v194
	v_and_b32_e32 v171, 0xffff0000, v194
	v_lshlrev_b32_e32 v172, 16, v195
	v_and_b32_e32 v173, 0xffff0000, v195
	v_pk_add_f32 v[116:117], v[116:117], v[166:167]
	v_pk_add_f32 v[118:119], v[118:119], v[168:169]
	v_pk_add_f32 v[112:113], v[112:113], v[170:171]
	v_pk_add_f32 v[114:115], v[114:115], v[172:173]
	v_cvt_pk_bf16_f32 v178, v116, v117
	v_cvt_pk_bf16_f32 v179, v118, v119
	v_cvt_pk_bf16_f32 v180, v112, v113
	v_cvt_pk_bf16_f32 v181, v114, v115
	v_pk_fma_f32 v[182:183], v[116:117], v[116:117], v[182:183]
	v_pk_fma_f32 v[182:183], v[118:119], v[118:119], v[182:183]
	v_pk_fma_f32 v[182:183], v[112:113], v[112:113], v[182:183]
	v_pk_fma_f32 v[182:183], v[114:115], v[114:115], v[182:183]
	global_store_dwordx4 v[232:233], v[178:181], off offset:256
	v_add_f32_e32 v184, v182, v183
	v_mov_b32_e32 v185, v184
	s_nop 1
	v_permlane16_swap_b32_e32 v185, v184
	v_add_f32_e32 v184, v184, v185
	v_mov_b32_e32 v185, v184
	s_nop 1
	v_permlane32_swap_b32_e32 v185, v184
	v_add_f32_e32 v184, v184, v185
	s_and_saveexec_b64 s[40:41], s[4:5]
	global_store_dword v[234:235], v184, off
	s_or_b64 exec, exec, s[40:41]
	s_mov_b64 s[100:101], 0x40000
	v_lshl_add_u64 v[230:231], v[232:233], 0, s[100:101]
	global_load_dwordx4 v[188:191], v[230:231], off
	global_load_dwordx4 v[192:195], v[230:231], off offset:256
	s_mov_b64 s[100:101], 0x8000
	v_lshl_add_u64 v[186:187], v[232:233], 0, s[100:101]
	s_waitcnt vmcnt(10)
	v_lshlrev_b32_e32 v166, 16, v196
	v_and_b32_e32 v167, 0xffff0000, v196
	v_lshlrev_b32_e32 v168, 16, v197
	v_and_b32_e32 v169, 0xffff0000, v197
	v_lshlrev_b32_e32 v170, 16, v198
	v_and_b32_e32 v171, 0xffff0000, v198
	v_lshlrev_b32_e32 v172, 16, v199
	v_and_b32_e32 v173, 0xffff0000, v199
	v_pk_add_f32 v[108:109], v[108:109], v[166:167]
	v_pk_add_f32 v[110:111], v[110:111], v[168:169]
	v_pk_add_f32 v[104:105], v[104:105], v[170:171]
	v_pk_add_f32 v[106:107], v[106:107], v[172:173]
	v_cvt_pk_bf16_f32 v174, v108, v109
	v_cvt_pk_bf16_f32 v175, v110, v111
	v_cvt_pk_bf16_f32 v176, v104, v105
	v_cvt_pk_bf16_f32 v177, v106, v107
	v_pk_mul_f32 v[182:183], v[108:109], v[108:109]
	v_pk_fma_f32 v[182:183], v[110:111], v[110:111], v[182:183]
	v_pk_fma_f32 v[182:183], v[104:105], v[104:105], v[182:183]
	v_pk_fma_f32 v[182:183], v[106:107], v[106:107], v[182:183]
	global_store_dwordx4 v[186:187], v[174:177], off
	s_waitcnt vmcnt(10)
	v_lshlrev_b32_e32 v166, 16, v200
	v_and_b32_e32 v167, 0xffff0000, v200
	v_lshlrev_b32_e32 v168, 16, v201
	v_and_b32_e32 v169, 0xffff0000, v201
	v_lshlrev_b32_e32 v170, 16, v202
	v_and_b32_e32 v171, 0xffff0000, v202
	v_lshlrev_b32_e32 v172, 16, v203
	v_and_b32_e32 v173, 0xffff0000, v203
	v_pk_add_f32 v[100:101], v[100:101], v[166:167]
	v_pk_add_f32 v[102:103], v[102:103], v[168:169]
	v_pk_add_f32 v[96:97], v[96:97], v[170:171]
	v_pk_add_f32 v[98:99], v[98:99], v[172:173]
	v_cvt_pk_bf16_f32 v178, v100, v101
	v_cvt_pk_bf16_f32 v179, v102, v103
	v_cvt_pk_bf16_f32 v180, v96, v97
	v_cvt_pk_bf16_f32 v181, v98, v99
	v_pk_fma_f32 v[182:183], v[100:101], v[100:101], v[182:183]
	v_pk_fma_f32 v[182:183], v[102:103], v[102:103], v[182:183]
	v_pk_fma_f32 v[182:183], v[96:97], v[96:97], v[182:183]
	v_pk_fma_f32 v[182:183], v[98:99], v[98:99], v[182:183]
	global_store_dwordx4 v[186:187], v[178:181], off offset:256
	v_add_f32_e32 v184, v182, v183
	v_mov_b32_e32 v185, v184
	s_nop 1
	v_permlane16_swap_b32_e32 v185, v184
	v_add_f32_e32 v184, v184, v185
	v_mov_b32_e32 v185, v184
	s_nop 1
	v_permlane32_swap_b32_e32 v185, v184
	v_add_f32_e32 v184, v184, v185
	s_and_saveexec_b64 s[40:41], s[4:5]
	global_store_dword v[234:235], v184, off offset:1024
	s_or_b64 exec, exec, s[40:41]
	s_mov_b64 s[100:101], 0x48000
	v_lshl_add_u64 v[230:231], v[232:233], 0, s[100:101]
	global_load_dwordx4 v[196:199], v[230:231], off
	global_load_dwordx4 v[200:203], v[230:231], off offset:256
	s_mov_b64 s[100:101], 0x10000
	v_lshl_add_u64 v[186:187], v[232:233], 0, s[100:101]
	s_waitcnt vmcnt(13)
	v_lshlrev_b32_e32 v166, 16, v204
	v_and_b32_e32 v167, 0xffff0000, v204
	v_lshlrev_b32_e32 v168, 16, v205
	v_and_b32_e32 v169, 0xffff0000, v205
	v_lshlrev_b32_e32 v170, 16, v206
	v_and_b32_e32 v171, 0xffff0000, v206
	v_lshlrev_b32_e32 v172, 16, v207
	v_and_b32_e32 v173, 0xffff0000, v207
	v_pk_add_f32 v[92:93], v[92:93], v[166:167]
	v_pk_add_f32 v[94:95], v[94:95], v[168:169]
	v_pk_add_f32 v[88:89], v[88:89], v[170:171]
	v_pk_add_f32 v[90:91], v[90:91], v[172:173]
	v_cvt_pk_bf16_f32 v174, v92, v93
	v_cvt_pk_bf16_f32 v175, v94, v95
	v_cvt_pk_bf16_f32 v176, v88, v89
	v_cvt_pk_bf16_f32 v177, v90, v91
	v_pk_mul_f32 v[182:183], v[92:93], v[92:93]
	v_pk_fma_f32 v[182:183], v[94:95], v[94:95], v[182:183]
	v_pk_fma_f32 v[182:183], v[88:89], v[88:89], v[182:183]
	v_pk_fma_f32 v[182:183], v[90:91], v[90:91], v[182:183]
	global_store_dwordx4 v[186:187], v[174:177], off
	s_waitcnt vmcnt(13)
	v_lshlrev_b32_e32 v166, 16, v208
	v_and_b32_e32 v167, 0xffff0000, v208
	v_lshlrev_b32_e32 v168, 16, v209
	v_and_b32_e32 v169, 0xffff0000, v209
	v_lshlrev_b32_e32 v170, 16, v210
	v_and_b32_e32 v171, 0xffff0000, v210
	v_lshlrev_b32_e32 v172, 16, v211
	v_and_b32_e32 v173, 0xffff0000, v211
	v_pk_add_f32 v[84:85], v[84:85], v[166:167]
	v_pk_add_f32 v[86:87], v[86:87], v[168:169]
	v_pk_add_f32 v[80:81], v[80:81], v[170:171]
	v_pk_add_f32 v[82:83], v[82:83], v[172:173]
	v_cvt_pk_bf16_f32 v178, v84, v85
	v_cvt_pk_bf16_f32 v179, v86, v87
	v_cvt_pk_bf16_f32 v180, v80, v81
	v_cvt_pk_bf16_f32 v181, v82, v83
	v_pk_fma_f32 v[182:183], v[84:85], v[84:85], v[182:183]
	v_pk_fma_f32 v[182:183], v[86:87], v[86:87], v[182:183]
	v_pk_fma_f32 v[182:183], v[80:81], v[80:81], v[182:183]
	v_pk_fma_f32 v[182:183], v[82:83], v[82:83], v[182:183]
	global_store_dwordx4 v[186:187], v[178:181], off offset:256
	v_add_f32_e32 v184, v182, v183
	v_mov_b32_e32 v185, v184
	s_nop 1
	v_permlane16_swap_b32_e32 v185, v184
	v_add_f32_e32 v184, v184, v185
	v_mov_b32_e32 v185, v184
	s_nop 1
	v_permlane32_swap_b32_e32 v185, v184
	v_add_f32_e32 v184, v184, v185
	s_and_saveexec_b64 s[40:41], s[4:5]
	global_store_dword v[234:235], v184, off offset:2048
	s_or_b64 exec, exec, s[40:41]
	s_mov_b64 s[100:101], 0x50000
	v_lshl_add_u64 v[230:231], v[232:233], 0, s[100:101]
	global_load_dwordx4 v[204:207], v[230:231], off
	global_load_dwordx4 v[208:211], v[230:231], off offset:256
	s_mov_b64 s[100:101], 0x18000
	v_lshl_add_u64 v[186:187], v[232:233], 0, s[100:101]
	s_waitcnt vmcnt(16)
	v_lshlrev_b32_e32 v166, 16, v212
	v_and_b32_e32 v167, 0xffff0000, v212
	v_lshlrev_b32_e32 v168, 16, v213
	v_and_b32_e32 v169, 0xffff0000, v213
	v_lshlrev_b32_e32 v170, 16, v214
	v_and_b32_e32 v171, 0xffff0000, v214
	v_lshlrev_b32_e32 v172, 16, v215
	v_and_b32_e32 v173, 0xffff0000, v215
	v_pk_add_f32 v[76:77], v[76:77], v[166:167]
	v_pk_add_f32 v[78:79], v[78:79], v[168:169]
	v_pk_add_f32 v[72:73], v[72:73], v[170:171]
	v_pk_add_f32 v[74:75], v[74:75], v[172:173]
	v_cvt_pk_bf16_f32 v174, v76, v77
	v_cvt_pk_bf16_f32 v175, v78, v79
	v_cvt_pk_bf16_f32 v176, v72, v73
	v_cvt_pk_bf16_f32 v177, v74, v75
	v_pk_mul_f32 v[182:183], v[76:77], v[76:77]
	v_pk_fma_f32 v[182:183], v[78:79], v[78:79], v[182:183]
	v_pk_fma_f32 v[182:183], v[72:73], v[72:73], v[182:183]
	v_pk_fma_f32 v[182:183], v[74:75], v[74:75], v[182:183]
	global_store_dwordx4 v[186:187], v[174:177], off
	s_waitcnt vmcnt(16)
	v_lshlrev_b32_e32 v166, 16, v216
	v_and_b32_e32 v167, 0xffff0000, v216
	v_lshlrev_b32_e32 v168, 16, v217
	v_and_b32_e32 v169, 0xffff0000, v217
	v_lshlrev_b32_e32 v170, 16, v218
	v_and_b32_e32 v171, 0xffff0000, v218
	v_lshlrev_b32_e32 v172, 16, v219
	v_and_b32_e32 v173, 0xffff0000, v219
	v_pk_add_f32 v[68:69], v[68:69], v[166:167]
	v_pk_add_f32 v[70:71], v[70:71], v[168:169]
	v_pk_add_f32 v[64:65], v[64:65], v[170:171]
	v_pk_add_f32 v[66:67], v[66:67], v[172:173]
	v_cvt_pk_bf16_f32 v178, v68, v69
	v_cvt_pk_bf16_f32 v179, v70, v71
	v_cvt_pk_bf16_f32 v180, v64, v65
	v_cvt_pk_bf16_f32 v181, v66, v67
	v_pk_fma_f32 v[182:183], v[68:69], v[68:69], v[182:183]
	v_pk_fma_f32 v[182:183], v[70:71], v[70:71], v[182:183]
	v_pk_fma_f32 v[182:183], v[64:65], v[64:65], v[182:183]
	v_pk_fma_f32 v[182:183], v[66:67], v[66:67], v[182:183]
	global_store_dwordx4 v[186:187], v[178:181], off offset:256
	v_add_f32_e32 v184, v182, v183
	v_mov_b32_e32 v185, v184
	s_nop 1
	v_permlane16_swap_b32_e32 v185, v184
	v_add_f32_e32 v184, v184, v185
	v_mov_b32_e32 v185, v184
	s_nop 1
	v_permlane32_swap_b32_e32 v185, v184
	v_add_f32_e32 v184, v184, v185
	s_and_saveexec_b64 s[40:41], s[4:5]
	global_store_dword v[234:235], v184, off offset:3072
	s_or_b64 exec, exec, s[40:41]
	s_mov_b64 s[100:101], 0x58000
	v_lshl_add_u64 v[230:231], v[232:233], 0, s[100:101]
	global_load_dwordx4 v[212:215], v[230:231], off
	global_load_dwordx4 v[216:219], v[230:231], off offset:256
	s_mov_b64 s[100:101], 0x40000
	v_lshl_add_u64 v[186:187], v[232:233], 0, s[100:101]
	s_waitcnt vmcnt(16)
	v_lshlrev_b32_e32 v166, 16, v188
	v_and_b32_e32 v167, 0xffff0000, v188
	v_lshlrev_b32_e32 v168, 16, v189
	v_and_b32_e32 v169, 0xffff0000, v189
	v_lshlrev_b32_e32 v170, 16, v190
	v_and_b32_e32 v171, 0xffff0000, v190
	v_lshlrev_b32_e32 v172, 16, v191
	v_and_b32_e32 v173, 0xffff0000, v191
	v_pk_add_f32 v[60:61], v[60:61], v[166:167]
	v_pk_add_f32 v[62:63], v[62:63], v[168:169]
	v_pk_add_f32 v[56:57], v[56:57], v[170:171]
	v_pk_add_f32 v[58:59], v[58:59], v[172:173]
	v_cvt_pk_bf16_f32 v174, v60, v61
	v_cvt_pk_bf16_f32 v175, v62, v63
	v_cvt_pk_bf16_f32 v176, v56, v57
	v_cvt_pk_bf16_f32 v177, v58, v59
	v_pk_mul_f32 v[182:183], v[60:61], v[60:61]
	v_pk_fma_f32 v[182:183], v[62:63], v[62:63], v[182:183]
	v_pk_fma_f32 v[182:183], v[56:57], v[56:57], v[182:183]
	v_pk_fma_f32 v[182:183], v[58:59], v[58:59], v[182:183]
	global_store_dwordx4 v[186:187], v[174:177], off
	s_waitcnt vmcnt(16)
	v_lshlrev_b32_e32 v166, 16, v192
	v_and_b32_e32 v167, 0xffff0000, v192
	v_lshlrev_b32_e32 v168, 16, v193
	v_and_b32_e32 v169, 0xffff0000, v193
	v_lshlrev_b32_e32 v170, 16, v194
	v_and_b32_e32 v171, 0xffff0000, v194
	v_lshlrev_b32_e32 v172, 16, v195
	v_and_b32_e32 v173, 0xffff0000, v195
	v_pk_add_f32 v[52:53], v[52:53], v[166:167]
	v_pk_add_f32 v[54:55], v[54:55], v[168:169]
	v_pk_add_f32 v[48:49], v[48:49], v[170:171]
	v_pk_add_f32 v[50:51], v[50:51], v[172:173]
	v_cvt_pk_bf16_f32 v178, v52, v53
	v_cvt_pk_bf16_f32 v179, v54, v55
	v_cvt_pk_bf16_f32 v180, v48, v49
	v_cvt_pk_bf16_f32 v181, v50, v51
	v_pk_fma_f32 v[182:183], v[52:53], v[52:53], v[182:183]
	v_pk_fma_f32 v[182:183], v[54:55], v[54:55], v[182:183]
	v_pk_fma_f32 v[182:183], v[48:49], v[48:49], v[182:183]
	v_pk_fma_f32 v[182:183], v[50:51], v[50:51], v[182:183]
	global_store_dwordx4 v[186:187], v[178:181], off offset:256
	v_add_f32_e32 v184, v182, v183
	v_mov_b32_e32 v185, v184
	s_nop 1
	v_permlane16_swap_b32_e32 v185, v184
	v_add_f32_e32 v184, v184, v185
	v_mov_b32_e32 v185, v184
	s_nop 1
	v_permlane32_swap_b32_e32 v185, v184
	v_add_f32_e32 v184, v184, v185
	s_and_saveexec_b64 s[40:41], s[4:5]
	global_store_dword v[236:237], v184, off
	s_or_b64 exec, exec, s[40:41]
	s_mov_b64 s[100:101], 0x48000
	v_lshl_add_u64 v[186:187], v[232:233], 0, s[100:101]
	s_waitcnt vmcnt(14)
	v_lshlrev_b32_e32 v166, 16, v196
	v_and_b32_e32 v167, 0xffff0000, v196
	v_lshlrev_b32_e32 v168, 16, v197
	v_and_b32_e32 v169, 0xffff0000, v197
	v_lshlrev_b32_e32 v170, 16, v198
	v_and_b32_e32 v171, 0xffff0000, v198
	v_lshlrev_b32_e32 v172, 16, v199
	v_and_b32_e32 v173, 0xffff0000, v199
	v_pk_add_f32 v[44:45], v[44:45], v[166:167]
	v_pk_add_f32 v[46:47], v[46:47], v[168:169]
	v_pk_add_f32 v[40:41], v[40:41], v[170:171]
	v_pk_add_f32 v[42:43], v[42:43], v[172:173]
	v_cvt_pk_bf16_f32 v174, v44, v45
	v_cvt_pk_bf16_f32 v175, v46, v47
	v_cvt_pk_bf16_f32 v176, v40, v41
	v_cvt_pk_bf16_f32 v177, v42, v43
	v_pk_mul_f32 v[182:183], v[44:45], v[44:45]
	v_pk_fma_f32 v[182:183], v[46:47], v[46:47], v[182:183]
	v_pk_fma_f32 v[182:183], v[40:41], v[40:41], v[182:183]
	v_pk_fma_f32 v[182:183], v[42:43], v[42:43], v[182:183]
	global_store_dwordx4 v[186:187], v[174:177], off
	s_waitcnt vmcnt(14)
	v_lshlrev_b32_e32 v166, 16, v200
	v_and_b32_e32 v167, 0xffff0000, v200
	v_lshlrev_b32_e32 v168, 16, v201
	v_and_b32_e32 v169, 0xffff0000, v201
	v_lshlrev_b32_e32 v170, 16, v202
	v_and_b32_e32 v171, 0xffff0000, v202
	v_lshlrev_b32_e32 v172, 16, v203
	v_and_b32_e32 v173, 0xffff0000, v203
	v_pk_add_f32 v[36:37], v[36:37], v[166:167]
	v_pk_add_f32 v[38:39], v[38:39], v[168:169]
	v_pk_add_f32 v[32:33], v[32:33], v[170:171]
	v_pk_add_f32 v[34:35], v[34:35], v[172:173]
	v_cvt_pk_bf16_f32 v178, v36, v37
	v_cvt_pk_bf16_f32 v179, v38, v39
	v_cvt_pk_bf16_f32 v180, v32, v33
	v_cvt_pk_bf16_f32 v181, v34, v35
	v_pk_fma_f32 v[182:183], v[36:37], v[36:37], v[182:183]
	v_pk_fma_f32 v[182:183], v[38:39], v[38:39], v[182:183]
	v_pk_fma_f32 v[182:183], v[32:33], v[32:33], v[182:183]
	v_pk_fma_f32 v[182:183], v[34:35], v[34:35], v[182:183]
	global_store_dwordx4 v[186:187], v[178:181], off offset:256
	v_add_f32_e32 v184, v182, v183
	v_mov_b32_e32 v185, v184
	s_nop 1
	v_permlane16_swap_b32_e32 v185, v184
	v_add_f32_e32 v184, v184, v185
	v_mov_b32_e32 v185, v184
	s_nop 1
	v_permlane32_swap_b32_e32 v185, v184
	v_add_f32_e32 v184, v184, v185
	s_and_saveexec_b64 s[40:41], s[4:5]
	global_store_dword v[236:237], v184, off offset:1024
	s_or_b64 exec, exec, s[40:41]
	s_mov_b64 s[100:101], 0x50000
	v_lshl_add_u64 v[186:187], v[232:233], 0, s[100:101]
	s_waitcnt vmcnt(12)
	v_lshlrev_b32_e32 v166, 16, v204
	v_and_b32_e32 v167, 0xffff0000, v204
	v_lshlrev_b32_e32 v168, 16, v205
	v_and_b32_e32 v169, 0xffff0000, v205
	v_lshlrev_b32_e32 v170, 16, v206
	v_and_b32_e32 v171, 0xffff0000, v206
	v_lshlrev_b32_e32 v172, 16, v207
	v_and_b32_e32 v173, 0xffff0000, v207
	v_pk_add_f32 v[28:29], v[28:29], v[166:167]
	v_pk_add_f32 v[30:31], v[30:31], v[168:169]
	v_pk_add_f32 v[24:25], v[24:25], v[170:171]
	v_pk_add_f32 v[26:27], v[26:27], v[172:173]
	v_cvt_pk_bf16_f32 v174, v28, v29
	v_cvt_pk_bf16_f32 v175, v30, v31
	v_cvt_pk_bf16_f32 v176, v24, v25
	v_cvt_pk_bf16_f32 v177, v26, v27
	v_pk_mul_f32 v[182:183], v[28:29], v[28:29]
	v_pk_fma_f32 v[182:183], v[30:31], v[30:31], v[182:183]
	v_pk_fma_f32 v[182:183], v[24:25], v[24:25], v[182:183]
	v_pk_fma_f32 v[182:183], v[26:27], v[26:27], v[182:183]
	global_store_dwordx4 v[186:187], v[174:177], off
	s_waitcnt vmcnt(12)
	v_lshlrev_b32_e32 v166, 16, v208
	v_and_b32_e32 v167, 0xffff0000, v208
	v_lshlrev_b32_e32 v168, 16, v209
	v_and_b32_e32 v169, 0xffff0000, v209
	v_lshlrev_b32_e32 v170, 16, v210
	v_and_b32_e32 v171, 0xffff0000, v210
	v_lshlrev_b32_e32 v172, 16, v211
	v_and_b32_e32 v173, 0xffff0000, v211
	v_pk_add_f32 v[20:21], v[20:21], v[166:167]
	v_pk_add_f32 v[22:23], v[22:23], v[168:169]
	v_pk_add_f32 v[16:17], v[16:17], v[170:171]
	v_pk_add_f32 v[18:19], v[18:19], v[172:173]
	v_cvt_pk_bf16_f32 v178, v20, v21
	v_cvt_pk_bf16_f32 v179, v22, v23
	v_cvt_pk_bf16_f32 v180, v16, v17
	v_cvt_pk_bf16_f32 v181, v18, v19
	v_pk_fma_f32 v[182:183], v[20:21], v[20:21], v[182:183]
	v_pk_fma_f32 v[182:183], v[22:23], v[22:23], v[182:183]
	v_pk_fma_f32 v[182:183], v[16:17], v[16:17], v[182:183]
	v_pk_fma_f32 v[182:183], v[18:19], v[18:19], v[182:183]
	global_store_dwordx4 v[186:187], v[178:181], off offset:256
	v_add_f32_e32 v184, v182, v183
	v_mov_b32_e32 v185, v184
	s_nop 1
	v_permlane16_swap_b32_e32 v185, v184
	v_add_f32_e32 v184, v184, v185
	v_mov_b32_e32 v185, v184
	s_nop 1
	v_permlane32_swap_b32_e32 v185, v184
	v_add_f32_e32 v184, v184, v185
	s_and_saveexec_b64 s[40:41], s[4:5]
	global_store_dword v[236:237], v184, off offset:2048
	s_or_b64 exec, exec, s[40:41]
	s_mov_b64 s[100:101], 0x58000
	v_lshl_add_u64 v[186:187], v[232:233], 0, s[100:101]
	s_waitcnt vmcnt(10)
	v_lshlrev_b32_e32 v166, 16, v212
	v_and_b32_e32 v167, 0xffff0000, v212
	v_lshlrev_b32_e32 v168, 16, v213
	v_and_b32_e32 v169, 0xffff0000, v213
	v_lshlrev_b32_e32 v170, 16, v214
	v_and_b32_e32 v171, 0xffff0000, v214
	v_lshlrev_b32_e32 v172, 16, v215
	v_and_b32_e32 v173, 0xffff0000, v215
	v_pk_add_f32 v[12:13], v[12:13], v[166:167]
	v_pk_add_f32 v[14:15], v[14:15], v[168:169]
	v_pk_add_f32 v[8:9], v[8:9], v[170:171]
	v_pk_add_f32 v[10:11], v[10:11], v[172:173]
	v_cvt_pk_bf16_f32 v174, v12, v13
	v_cvt_pk_bf16_f32 v175, v14, v15
	v_cvt_pk_bf16_f32 v176, v8, v9
	v_cvt_pk_bf16_f32 v177, v10, v11
	v_pk_mul_f32 v[182:183], v[12:13], v[12:13]
	v_pk_fma_f32 v[182:183], v[14:15], v[14:15], v[182:183]
	v_pk_fma_f32 v[182:183], v[8:9], v[8:9], v[182:183]
	v_pk_fma_f32 v[182:183], v[10:11], v[10:11], v[182:183]
	global_store_dwordx4 v[186:187], v[174:177], off
	s_waitcnt vmcnt(10)
	v_lshlrev_b32_e32 v166, 16, v216
	v_and_b32_e32 v167, 0xffff0000, v216
	v_lshlrev_b32_e32 v168, 16, v217
	v_and_b32_e32 v169, 0xffff0000, v217
	v_lshlrev_b32_e32 v170, 16, v218
	v_and_b32_e32 v171, 0xffff0000, v218
	v_lshlrev_b32_e32 v172, 16, v219
	v_and_b32_e32 v173, 0xffff0000, v219
	v_pk_add_f32 v[4:5], v[4:5], v[166:167]
	v_pk_add_f32 v[6:7], v[6:7], v[168:169]
	v_pk_add_f32 v[0:1], v[0:1], v[170:171]
	v_pk_add_f32 v[2:3], v[2:3], v[172:173]
	v_cvt_pk_bf16_f32 v178, v4, v5
	v_cvt_pk_bf16_f32 v179, v6, v7
	v_cvt_pk_bf16_f32 v180, v0, v1
	v_cvt_pk_bf16_f32 v181, v2, v3
	v_pk_fma_f32 v[182:183], v[4:5], v[4:5], v[182:183]
	v_pk_fma_f32 v[182:183], v[6:7], v[6:7], v[182:183]
	v_pk_fma_f32 v[182:183], v[0:1], v[0:1], v[182:183]
	v_pk_fma_f32 v[182:183], v[2:3], v[2:3], v[182:183]
	global_store_dwordx4 v[186:187], v[178:181], off offset:256
	v_add_f32_e32 v184, v182, v183
	v_mov_b32_e32 v185, v184
	s_nop 1
	v_permlane16_swap_b32_e32 v185, v184
	v_add_f32_e32 v184, v184, v185
	v_mov_b32_e32 v185, v184
	s_nop 1
	v_permlane32_swap_b32_e32 v185, v184
	v_add_f32_e32 v184, v184, v185
	s_and_saveexec_b64 s[40:41], s[4:5]
	global_store_dword v[236:237], v184, off offset:3072
	s_or_b64 exec, exec, s[40:41]
	s_andn2_b64 vcc, exec, s[6:7]
	s_mov_b64 s[6:7], -1
	s_cbranch_vccnz .LBB0_1549
	s_andn2_b64 vcc, exec, s[8:9]
	s_cbranch_vccnz .LBB0_1548
	s_nop 0
	s_branch .LBB0_1548

.LBB0_1736:
	v_lshl_add_u32 v148, s12, 8, v150
	v_ashrrev_i32_e32 v149, 31, v148
	v_lshl_or_b32 v146, s8, 8, v152
	v_lshlrev_b64 v[158:159], 11, v[148:149]
	v_ashrrev_i32_e32 v147, 31, v146
	v_lshl_add_u64 v[158:159], s[14:15], 0, v[158:159]
	v_lshl_add_u64 v[162:163], v[146:147], 1, v[158:159]
	v_mov_b32_e32 v232, v162
	v_mov_b32_e32 v233, v163
	global_load_dwordx4 v[188:191], v[232:233], off
	global_load_dwordx4 v[192:195], v[232:233], off offset:256
	s_mov_b64 s[100:101], 0x8000
	v_lshl_add_u64 v[230:231], v[232:233], 0, s[100:101]
	global_load_dwordx4 v[196:199], v[230:231], off
	global_load_dwordx4 v[200:203], v[230:231], off offset:256
	s_mov_b64 s[100:101], 0x10000
	v_lshl_add_u64 v[230:231], v[232:233], 0, s[100:101]
	global_load_dwordx4 v[204:207], v[230:231], off
	global_load_dwordx4 v[208:211], v[230:231], off offset:256
	s_mov_b64 s[100:101], 0x18000
	v_lshl_add_u64 v[230:231], v[232:233], 0, s[100:101]
	global_load_dwordx4 v[212:215], v[230:231], off
	global_load_dwordx4 v[216:219], v[230:231], off offset:256
	s_lshl_b32 s30, s8, 2
	s_ashr_i32 s31, s30, 31
	v_lshlrev_b64 v[234:235], 6, v[148:149]
	v_lshl_add_u64 v[234:235], s[18:19], 0, v[234:235]
	v_lshl_add_u64 v[234:235], s[30:31], 2, v[234:235]
	s_lshl_b32 s100, s46, 2
	s_mov_b32 s101, 0
	v_lshl_add_u64 v[234:235], v[234:235], 0, s[100:101]
	s_mov_b64 s[100:101], 0x2000
	v_lshl_add_u64 v[236:237], v[234:235], 0, s[100:101]
	s_waitcnt vmcnt(7)
	v_lshlrev_b32_e32 v166, 16, v188
	v_and_b32_e32 v167, 0xffff0000, v188
	v_lshlrev_b32_e32 v168, 16, v189
	v_and_b32_e32 v169, 0xffff0000, v189
	v_lshlrev_b32_e32 v170, 16, v190
	v_and_b32_e32 v171, 0xffff0000, v190
	v_lshlrev_b32_e32 v172, 16, v191
	v_and_b32_e32 v173, 0xffff0000, v191
	v_pk_add_f32 v[124:125], v[124:125], v[166:167]
	v_pk_add_f32 v[126:127], v[126:127], v[168:169]
	v_pk_add_f32 v[120:121], v[120:121], v[170:171]
	v_pk_add_f32 v[122:123], v[122:123], v[172:173]
	v_cvt_pk_bf16_f32 v174, v124, v125
	v_cvt_pk_bf16_f32 v175, v126, v127
	v_cvt_pk_bf16_f32 v176, v120, v121
	v_cvt_pk_bf16_f32 v177, v122, v123
	v_pk_mul_f32 v[182:183], v[124:125], v[124:125]
	v_pk_fma_f32 v[182:183], v[126:127], v[126:127], v[182:183]
	v_pk_fma_f32 v[182:183], v[120:121], v[120:121], v[182:183]
	v_pk_fma_f32 v[182:183], v[122:123], v[122:123], v[182:183]
	global_store_dwordx4 v[232:233], v[174:177], off
	s_waitcnt vmcnt(7)
	v_lshlrev_b32_e32 v166, 16, v192
	v_and_b32_e32 v167, 0xffff0000, v192
	v_lshlrev_b32_e32 v168, 16, v193
	v_and_b32_e32 v169, 0xffff0000, v193
	v_lshlrev_b32_e32 v170, 16, v194
	v_and_b32_e32 v171, 0xffff0000, v194
	v_lshlrev_b32_e32 v172, 16, v195
	v_and_b32_e32 v173, 0xffff0000, v195
	v_pk_add_f32 v[116:117], v[116:117], v[166:167]
	v_pk_add_f32 v[118:119], v[118:119], v[168:169]
	v_pk_add_f32 v[112:113], v[112:113], v[170:171]
	v_pk_add_f32 v[114:115], v[114:115], v[172:173]
	v_cvt_pk_bf16_f32 v178, v116, v117
	v_cvt_pk_bf16_f32 v179, v118, v119
	v_cvt_pk_bf16_f32 v180, v112, v113
	v_cvt_pk_bf16_f32 v181, v114, v115
	v_pk_fma_f32 v[182:183], v[116:117], v[116:117], v[182:183]
	v_pk_fma_f32 v[182:183], v[118:119], v[118:119], v[182:183]
	v_pk_fma_f32 v[182:183], v[112:113], v[112:113], v[182:183]
	v_pk_fma_f32 v[182:183], v[114:115], v[114:115], v[182:183]
	global_store_dwordx4 v[232:233], v[178:181], off offset:256
	v_add_f32_e32 v184, v182, v183
	v_mov_b32_e32 v185, v184
	s_nop 1
	v_permlane16_swap_b32_e32 v185, v184
	v_add_f32_e32 v184, v184, v185
	v_mov_b32_e32 v185, v184
	s_nop 1
	v_permlane32_swap_b32_e32 v185, v184
	v_add_f32_e32 v184, v184, v185
	s_and_saveexec_b64 s[36:37], s[4:5]
	global_store_dword v[234:235], v184, off
	s_or_b64 exec, exec, s[36:37]
	s_mov_b64 s[100:101], 0x40000
	v_lshl_add_u64 v[230:231], v[232:233], 0, s[100:101]
	global_load_dwordx4 v[188:191], v[230:231], off
	global_load_dwordx4 v[192:195], v[230:231], off offset:256
	s_mov_b64 s[100:101], 0x8000
	v_lshl_add_u64 v[186:187], v[232:233], 0, s[100:101]
	s_waitcnt vmcnt(10)
	v_lshlrev_b32_e32 v166, 16, v196
	v_and_b32_e32 v167, 0xffff0000, v196
	v_lshlrev_b32_e32 v168, 16, v197
	v_and_b32_e32 v169, 0xffff0000, v197
	v_lshlrev_b32_e32 v170, 16, v198
	v_and_b32_e32 v171, 0xffff0000, v198
	v_lshlrev_b32_e32 v172, 16, v199
	v_and_b32_e32 v173, 0xffff0000, v199
	v_pk_add_f32 v[108:109], v[108:109], v[166:167]
	v_pk_add_f32 v[110:111], v[110:111], v[168:169]
	v_pk_add_f32 v[104:105], v[104:105], v[170:171]
	v_pk_add_f32 v[106:107], v[106:107], v[172:173]
	v_cvt_pk_bf16_f32 v174, v108, v109
	v_cvt_pk_bf16_f32 v175, v110, v111
	v_cvt_pk_bf16_f32 v176, v104, v105
	v_cvt_pk_bf16_f32 v177, v106, v107
	v_pk_mul_f32 v[182:183], v[108:109], v[108:109]
	v_pk_fma_f32 v[182:183], v[110:111], v[110:111], v[182:183]
	v_pk_fma_f32 v[182:183], v[104:105], v[104:105], v[182:183]
	v_pk_fma_f32 v[182:183], v[106:107], v[106:107], v[182:183]
	global_store_dwordx4 v[186:187], v[174:177], off
	s_waitcnt vmcnt(10)
	v_lshlrev_b32_e32 v166, 16, v200
	v_and_b32_e32 v167, 0xffff0000, v200
	v_lshlrev_b32_e32 v168, 16, v201
	v_and_b32_e32 v169, 0xffff0000, v201
	v_lshlrev_b32_e32 v170, 16, v202
	v_and_b32_e32 v171, 0xffff0000, v202
	v_lshlrev_b32_e32 v172, 16, v203
	v_and_b32_e32 v173, 0xffff0000, v203
	v_pk_add_f32 v[100:101], v[100:101], v[166:167]
	v_pk_add_f32 v[102:103], v[102:103], v[168:169]
	v_pk_add_f32 v[96:97], v[96:97], v[170:171]
	v_pk_add_f32 v[98:99], v[98:99], v[172:173]
	v_cvt_pk_bf16_f32 v178, v100, v101
	v_cvt_pk_bf16_f32 v179, v102, v103
	v_cvt_pk_bf16_f32 v180, v96, v97
	v_cvt_pk_bf16_f32 v181, v98, v99
	v_pk_fma_f32 v[182:183], v[100:101], v[100:101], v[182:183]
	v_pk_fma_f32 v[182:183], v[102:103], v[102:103], v[182:183]
	v_pk_fma_f32 v[182:183], v[96:97], v[96:97], v[182:183]
	v_pk_fma_f32 v[182:183], v[98:99], v[98:99], v[182:183]
	global_store_dwordx4 v[186:187], v[178:181], off offset:256
	v_add_f32_e32 v184, v182, v183
	v_mov_b32_e32 v185, v184
	s_nop 1
	v_permlane16_swap_b32_e32 v185, v184
	v_add_f32_e32 v184, v184, v185
	v_mov_b32_e32 v185, v184
	s_nop 1
	v_permlane32_swap_b32_e32 v185, v184
	v_add_f32_e32 v184, v184, v185
	s_and_saveexec_b64 s[36:37], s[4:5]
	global_store_dword v[234:235], v184, off offset:1024
	s_or_b64 exec, exec, s[36:37]
	s_mov_b64 s[100:101], 0x48000
	v_lshl_add_u64 v[230:231], v[232:233], 0, s[100:101]
	global_load_dwordx4 v[196:199], v[230:231], off
	global_load_dwordx4 v[200:203], v[230:231], off offset:256
	s_mov_b64 s[100:101], 0x10000
	v_lshl_add_u64 v[186:187], v[232:233], 0, s[100:101]
	s_waitcnt vmcnt(13)
	v_lshlrev_b32_e32 v166, 16, v204
	v_and_b32_e32 v167, 0xffff0000, v204
	v_lshlrev_b32_e32 v168, 16, v205
	v_and_b32_e32 v169, 0xffff0000, v205
	v_lshlrev_b32_e32 v170, 16, v206
	v_and_b32_e32 v171, 0xffff0000, v206
	v_lshlrev_b32_e32 v172, 16, v207
	v_and_b32_e32 v173, 0xffff0000, v207
	v_pk_add_f32 v[92:93], v[92:93], v[166:167]
	v_pk_add_f32 v[94:95], v[94:95], v[168:169]
	v_pk_add_f32 v[88:89], v[88:89], v[170:171]
	v_pk_add_f32 v[90:91], v[90:91], v[172:173]
	v_cvt_pk_bf16_f32 v174, v92, v93
	v_cvt_pk_bf16_f32 v175, v94, v95
	v_cvt_pk_bf16_f32 v176, v88, v89
	v_cvt_pk_bf16_f32 v177, v90, v91
	v_pk_mul_f32 v[182:183], v[92:93], v[92:93]
	v_pk_fma_f32 v[182:183], v[94:95], v[94:95], v[182:183]
	v_pk_fma_f32 v[182:183], v[88:89], v[88:89], v[182:183]
	v_pk_fma_f32 v[182:183], v[90:91], v[90:91], v[182:183]
	global_store_dwordx4 v[186:187], v[174:177], off
	s_waitcnt vmcnt(13)
	v_lshlrev_b32_e32 v166, 16, v208
	v_and_b32_e32 v167, 0xffff0000, v208
	v_lshlrev_b32_e32 v168, 16, v209
	v_and_b32_e32 v169, 0xffff0000, v209
	v_lshlrev_b32_e32 v170, 16, v210
	v_and_b32_e32 v171, 0xffff0000, v210
	v_lshlrev_b32_e32 v172, 16, v211
	v_and_b32_e32 v173, 0xffff0000, v211
	v_pk_add_f32 v[84:85], v[84:85], v[166:167]
	v_pk_add_f32 v[86:87], v[86:87], v[168:169]
	v_pk_add_f32 v[80:81], v[80:81], v[170:171]
	v_pk_add_f32 v[82:83], v[82:83], v[172:173]
	v_cvt_pk_bf16_f32 v178, v84, v85
	v_cvt_pk_bf16_f32 v179, v86, v87
	v_cvt_pk_bf16_f32 v180, v80, v81
	v_cvt_pk_bf16_f32 v181, v82, v83
	v_pk_fma_f32 v[182:183], v[84:85], v[84:85], v[182:183]
	v_pk_fma_f32 v[182:183], v[86:87], v[86:87], v[182:183]
	v_pk_fma_f32 v[182:183], v[80:81], v[80:81], v[182:183]
	v_pk_fma_f32 v[182:183], v[82:83], v[82:83], v[182:183]
	global_store_dwordx4 v[186:187], v[178:181], off offset:256
	v_add_f32_e32 v184, v182, v183
	v_mov_b32_e32 v185, v184
	s_nop 1
	v_permlane16_swap_b32_e32 v185, v184
	v_add_f32_e32 v184, v184, v185
	v_mov_b32_e32 v185, v184
	s_nop 1
	v_permlane32_swap_b32_e32 v185, v184
	v_add_f32_e32 v184, v184, v185
	s_and_saveexec_b64 s[36:37], s[4:5]
	global_store_dword v[234:235], v184, off offset:2048
	s_or_b64 exec, exec, s[36:37]
	s_mov_b64 s[100:101], 0x50000
	v_lshl_add_u64 v[230:231], v[232:233], 0, s[100:101]
	global_load_dwordx4 v[204:207], v[230:231], off
	global_load_dwordx4 v[208:211], v[230:231], off offset:256
	s_mov_b64 s[100:101], 0x18000
	v_lshl_add_u64 v[186:187], v[232:233], 0, s[100:101]
	s_waitcnt vmcnt(16)
	v_lshlrev_b32_e32 v166, 16, v212
	v_and_b32_e32 v167, 0xffff0000, v212
	v_lshlrev_b32_e32 v168, 16, v213
	v_and_b32_e32 v169, 0xffff0000, v213
	v_lshlrev_b32_e32 v170, 16, v214
	v_and_b32_e32 v171, 0xffff0000, v214
	v_lshlrev_b32_e32 v172, 16, v215
	v_and_b32_e32 v173, 0xffff0000, v215
	v_pk_add_f32 v[76:77], v[76:77], v[166:167]
	v_pk_add_f32 v[78:79], v[78:79], v[168:169]
	v_pk_add_f32 v[72:73], v[72:73], v[170:171]
	v_pk_add_f32 v[74:75], v[74:75], v[172:173]
	v_cvt_pk_bf16_f32 v174, v76, v77
	v_cvt_pk_bf16_f32 v175, v78, v79
	v_cvt_pk_bf16_f32 v176, v72, v73
	v_cvt_pk_bf16_f32 v177, v74, v75
	v_pk_mul_f32 v[182:183], v[76:77], v[76:77]
	v_pk_fma_f32 v[182:183], v[78:79], v[78:79], v[182:183]
	v_pk_fma_f32 v[182:183], v[72:73], v[72:73], v[182:183]
	v_pk_fma_f32 v[182:183], v[74:75], v[74:75], v[182:183]
	global_store_dwordx4 v[186:187], v[174:177], off
	s_waitcnt vmcnt(16)
	v_lshlrev_b32_e32 v166, 16, v216
	v_and_b32_e32 v167, 0xffff0000, v216
	v_lshlrev_b32_e32 v168, 16, v217
	v_and_b32_e32 v169, 0xffff0000, v217
	v_lshlrev_b32_e32 v170, 16, v218
	v_and_b32_e32 v171, 0xffff0000, v218
	v_lshlrev_b32_e32 v172, 16, v219
	v_and_b32_e32 v173, 0xffff0000, v219
	v_pk_add_f32 v[68:69], v[68:69], v[166:167]
	v_pk_add_f32 v[70:71], v[70:71], v[168:169]
	v_pk_add_f32 v[64:65], v[64:65], v[170:171]
	v_pk_add_f32 v[66:67], v[66:67], v[172:173]
	v_cvt_pk_bf16_f32 v178, v68, v69
	v_cvt_pk_bf16_f32 v179, v70, v71
	v_cvt_pk_bf16_f32 v180, v64, v65
	v_cvt_pk_bf16_f32 v181, v66, v67
	v_pk_fma_f32 v[182:183], v[68:69], v[68:69], v[182:183]
	v_pk_fma_f32 v[182:183], v[70:71], v[70:71], v[182:183]
	v_pk_fma_f32 v[182:183], v[64:65], v[64:65], v[182:183]
	v_pk_fma_f32 v[182:183], v[66:67], v[66:67], v[182:183]
	global_store_dwordx4 v[186:187], v[178:181], off offset:256
	v_add_f32_e32 v184, v182, v183
	v_mov_b32_e32 v185, v184
	s_nop 1
	v_permlane16_swap_b32_e32 v185, v184
	v_add_f32_e32 v184, v184, v185
	v_mov_b32_e32 v185, v184
	s_nop 1
	v_permlane32_swap_b32_e32 v185, v184
	v_add_f32_e32 v184, v184, v185
	s_and_saveexec_b64 s[36:37], s[4:5]
	global_store_dword v[234:235], v184, off offset:3072
	s_or_b64 exec, exec, s[36:37]
	s_mov_b64 s[100:101], 0x58000
	v_lshl_add_u64 v[230:231], v[232:233], 0, s[100:101]
	global_load_dwordx4 v[212:215], v[230:231], off
	global_load_dwordx4 v[216:219], v[230:231], off offset:256
	s_mov_b64 s[100:101], 0x40000
	v_lshl_add_u64 v[186:187], v[232:233], 0, s[100:101]
	s_waitcnt vmcnt(16)
	v_lshlrev_b32_e32 v166, 16, v188
	v_and_b32_e32 v167, 0xffff0000, v188
	v_lshlrev_b32_e32 v168, 16, v189
	v_and_b32_e32 v169, 0xffff0000, v189
	v_lshlrev_b32_e32 v170, 16, v190
	v_and_b32_e32 v171, 0xffff0000, v190
	v_lshlrev_b32_e32 v172, 16, v191
	v_and_b32_e32 v173, 0xffff0000, v191
	v_pk_add_f32 v[60:61], v[60:61], v[166:167]
	v_pk_add_f32 v[62:63], v[62:63], v[168:169]
	v_pk_add_f32 v[56:57], v[56:57], v[170:171]
	v_pk_add_f32 v[58:59], v[58:59], v[172:173]
	v_cvt_pk_bf16_f32 v174, v60, v61
	v_cvt_pk_bf16_f32 v175, v62, v63
	v_cvt_pk_bf16_f32 v176, v56, v57
	v_cvt_pk_bf16_f32 v177, v58, v59
	v_pk_mul_f32 v[182:183], v[60:61], v[60:61]
	v_pk_fma_f32 v[182:183], v[62:63], v[62:63], v[182:183]
	v_pk_fma_f32 v[182:183], v[56:57], v[56:57], v[182:183]
	v_pk_fma_f32 v[182:183], v[58:59], v[58:59], v[182:183]
	global_store_dwordx4 v[186:187], v[174:177], off
	s_waitcnt vmcnt(16)
	v_lshlrev_b32_e32 v166, 16, v192
	v_and_b32_e32 v167, 0xffff0000, v192
	v_lshlrev_b32_e32 v168, 16, v193
	v_and_b32_e32 v169, 0xffff0000, v193
	v_lshlrev_b32_e32 v170, 16, v194
	v_and_b32_e32 v171, 0xffff0000, v194
	v_lshlrev_b32_e32 v172, 16, v195
	v_and_b32_e32 v173, 0xffff0000, v195
	v_pk_add_f32 v[52:53], v[52:53], v[166:167]
	v_pk_add_f32 v[54:55], v[54:55], v[168:169]
	v_pk_add_f32 v[48:49], v[48:49], v[170:171]
	v_pk_add_f32 v[50:51], v[50:51], v[172:173]
	v_cvt_pk_bf16_f32 v178, v52, v53
	v_cvt_pk_bf16_f32 v179, v54, v55
	v_cvt_pk_bf16_f32 v180, v48, v49
	v_cvt_pk_bf16_f32 v181, v50, v51
	v_pk_fma_f32 v[182:183], v[52:53], v[52:53], v[182:183]
	v_pk_fma_f32 v[182:183], v[54:55], v[54:55], v[182:183]
	v_pk_fma_f32 v[182:183], v[48:49], v[48:49], v[182:183]
	v_pk_fma_f32 v[182:183], v[50:51], v[50:51], v[182:183]
	global_store_dwordx4 v[186:187], v[178:181], off offset:256
	v_add_f32_e32 v184, v182, v183
	v_mov_b32_e32 v185, v184
	s_nop 1
	v_permlane16_swap_b32_e32 v185, v184
	v_add_f32_e32 v184, v184, v185
	v_mov_b32_e32 v185, v184
	s_nop 1
	v_permlane32_swap_b32_e32 v185, v184
	v_add_f32_e32 v184, v184, v185
	s_and_saveexec_b64 s[36:37], s[4:5]
	global_store_dword v[236:237], v184, off
	s_or_b64 exec, exec, s[36:37]
	s_mov_b64 s[100:101], 0x48000
	v_lshl_add_u64 v[186:187], v[232:233], 0, s[100:101]
	s_waitcnt vmcnt(14)
	v_lshlrev_b32_e32 v166, 16, v196
	v_and_b32_e32 v167, 0xffff0000, v196
	v_lshlrev_b32_e32 v168, 16, v197
	v_and_b32_e32 v169, 0xffff0000, v197
	v_lshlrev_b32_e32 v170, 16, v198
	v_and_b32_e32 v171, 0xffff0000, v198
	v_lshlrev_b32_e32 v172, 16, v199
	v_and_b32_e32 v173, 0xffff0000, v199
	v_pk_add_f32 v[44:45], v[44:45], v[166:167]
	v_pk_add_f32 v[46:47], v[46:47], v[168:169]
	v_pk_add_f32 v[40:41], v[40:41], v[170:171]
	v_pk_add_f32 v[42:43], v[42:43], v[172:173]
	v_cvt_pk_bf16_f32 v174, v44, v45
	v_cvt_pk_bf16_f32 v175, v46, v47
	v_cvt_pk_bf16_f32 v176, v40, v41
	v_cvt_pk_bf16_f32 v177, v42, v43
	v_pk_mul_f32 v[182:183], v[44:45], v[44:45]
	v_pk_fma_f32 v[182:183], v[46:47], v[46:47], v[182:183]
	v_pk_fma_f32 v[182:183], v[40:41], v[40:41], v[182:183]
	v_pk_fma_f32 v[182:183], v[42:43], v[42:43], v[182:183]
	global_store_dwordx4 v[186:187], v[174:177], off
	s_waitcnt vmcnt(14)
	v_lshlrev_b32_e32 v166, 16, v200
	v_and_b32_e32 v167, 0xffff0000, v200
	v_lshlrev_b32_e32 v168, 16, v201
	v_and_b32_e32 v169, 0xffff0000, v201
	v_lshlrev_b32_e32 v170, 16, v202
	v_and_b32_e32 v171, 0xffff0000, v202
	v_lshlrev_b32_e32 v172, 16, v203
	v_and_b32_e32 v173, 0xffff0000, v203
	v_pk_add_f32 v[36:37], v[36:37], v[166:167]
	v_pk_add_f32 v[38:39], v[38:39], v[168:169]
	v_pk_add_f32 v[32:33], v[32:33], v[170:171]
	v_pk_add_f32 v[34:35], v[34:35], v[172:173]
	v_cvt_pk_bf16_f32 v178, v36, v37
	v_cvt_pk_bf16_f32 v179, v38, v39
	v_cvt_pk_bf16_f32 v180, v32, v33
	v_cvt_pk_bf16_f32 v181, v34, v35
	v_pk_fma_f32 v[182:183], v[36:37], v[36:37], v[182:183]
	v_pk_fma_f32 v[182:183], v[38:39], v[38:39], v[182:183]
	v_pk_fma_f32 v[182:183], v[32:33], v[32:33], v[182:183]
	v_pk_fma_f32 v[182:183], v[34:35], v[34:35], v[182:183]
	global_store_dwordx4 v[186:187], v[178:181], off offset:256
	v_add_f32_e32 v184, v182, v183
	v_mov_b32_e32 v185, v184
	s_nop 1
	v_permlane16_swap_b32_e32 v185, v184
	v_add_f32_e32 v184, v184, v185
	v_mov_b32_e32 v185, v184
	s_nop 1
	v_permlane32_swap_b32_e32 v185, v184
	v_add_f32_e32 v184, v184, v185
	s_and_saveexec_b64 s[36:37], s[4:5]
	global_store_dword v[236:237], v184, off offset:1024
	s_or_b64 exec, exec, s[36:37]
	s_mov_b64 s[100:101], 0x50000
	v_lshl_add_u64 v[186:187], v[232:233], 0, s[100:101]
	s_waitcnt vmcnt(12)
	v_lshlrev_b32_e32 v166, 16, v204
	v_and_b32_e32 v167, 0xffff0000, v204
	v_lshlrev_b32_e32 v168, 16, v205
	v_and_b32_e32 v169, 0xffff0000, v205
	v_lshlrev_b32_e32 v170, 16, v206
	v_and_b32_e32 v171, 0xffff0000, v206
	v_lshlrev_b32_e32 v172, 16, v207
	v_and_b32_e32 v173, 0xffff0000, v207
	v_pk_add_f32 v[28:29], v[28:29], v[166:167]
	v_pk_add_f32 v[30:31], v[30:31], v[168:169]
	v_pk_add_f32 v[24:25], v[24:25], v[170:171]
	v_pk_add_f32 v[26:27], v[26:27], v[172:173]
	v_cvt_pk_bf16_f32 v174, v28, v29
	v_cvt_pk_bf16_f32 v175, v30, v31
	v_cvt_pk_bf16_f32 v176, v24, v25
	v_cvt_pk_bf16_f32 v177, v26, v27
	v_pk_mul_f32 v[182:183], v[28:29], v[28:29]
	v_pk_fma_f32 v[182:183], v[30:31], v[30:31], v[182:183]
	v_pk_fma_f32 v[182:183], v[24:25], v[24:25], v[182:183]
	v_pk_fma_f32 v[182:183], v[26:27], v[26:27], v[182:183]
	global_store_dwordx4 v[186:187], v[174:177], off
	s_waitcnt vmcnt(12)
	v_lshlrev_b32_e32 v166, 16, v208
	v_and_b32_e32 v167, 0xffff0000, v208
	v_lshlrev_b32_e32 v168, 16, v209
	v_and_b32_e32 v169, 0xffff0000, v209
	v_lshlrev_b32_e32 v170, 16, v210
	v_and_b32_e32 v171, 0xffff0000, v210
	v_lshlrev_b32_e32 v172, 16, v211
	v_and_b32_e32 v173, 0xffff0000, v211
	v_pk_add_f32 v[20:21], v[20:21], v[166:167]
	v_pk_add_f32 v[22:23], v[22:23], v[168:169]
	v_pk_add_f32 v[16:17], v[16:17], v[170:171]
	v_pk_add_f32 v[18:19], v[18:19], v[172:173]
	v_cvt_pk_bf16_f32 v178, v20, v21
	v_cvt_pk_bf16_f32 v179, v22, v23
	v_cvt_pk_bf16_f32 v180, v16, v17
	v_cvt_pk_bf16_f32 v181, v18, v19
	v_pk_fma_f32 v[182:183], v[20:21], v[20:21], v[182:183]
	v_pk_fma_f32 v[182:183], v[22:23], v[22:23], v[182:183]
	v_pk_fma_f32 v[182:183], v[16:17], v[16:17], v[182:183]
	v_pk_fma_f32 v[182:183], v[18:19], v[18:19], v[182:183]
	global_store_dwordx4 v[186:187], v[178:181], off offset:256
	v_add_f32_e32 v184, v182, v183
	v_mov_b32_e32 v185, v184
	s_nop 1
	v_permlane16_swap_b32_e32 v185, v184
	v_add_f32_e32 v184, v184, v185
	v_mov_b32_e32 v185, v184
	s_nop 1
	v_permlane32_swap_b32_e32 v185, v184
	v_add_f32_e32 v184, v184, v185
	s_and_saveexec_b64 s[36:37], s[4:5]
	global_store_dword v[236:237], v184, off offset:2048
	s_or_b64 exec, exec, s[36:37]
	s_mov_b64 s[100:101], 0x58000
	v_lshl_add_u64 v[186:187], v[232:233], 0, s[100:101]
	s_waitcnt vmcnt(10)
	v_lshlrev_b32_e32 v166, 16, v212
	v_and_b32_e32 v167, 0xffff0000, v212
	v_lshlrev_b32_e32 v168, 16, v213
	v_and_b32_e32 v169, 0xffff0000, v213
	v_lshlrev_b32_e32 v170, 16, v214
	v_and_b32_e32 v171, 0xffff0000, v214
	v_lshlrev_b32_e32 v172, 16, v215
	v_and_b32_e32 v173, 0xffff0000, v215
	v_pk_add_f32 v[12:13], v[12:13], v[166:167]
	v_pk_add_f32 v[14:15], v[14:15], v[168:169]
	v_pk_add_f32 v[8:9], v[8:9], v[170:171]
	v_pk_add_f32 v[10:11], v[10:11], v[172:173]
	v_cvt_pk_bf16_f32 v174, v12, v13
	v_cvt_pk_bf16_f32 v175, v14, v15
	v_cvt_pk_bf16_f32 v176, v8, v9
	v_cvt_pk_bf16_f32 v177, v10, v11
	v_pk_mul_f32 v[182:183], v[12:13], v[12:13]
	v_pk_fma_f32 v[182:183], v[14:15], v[14:15], v[182:183]
	v_pk_fma_f32 v[182:183], v[8:9], v[8:9], v[182:183]
	v_pk_fma_f32 v[182:183], v[10:11], v[10:11], v[182:183]
	global_store_dwordx4 v[186:187], v[174:177], off
	s_waitcnt vmcnt(10)
	v_lshlrev_b32_e32 v166, 16, v216
	v_and_b32_e32 v167, 0xffff0000, v216
	v_lshlrev_b32_e32 v168, 16, v217
	v_and_b32_e32 v169, 0xffff0000, v217
	v_lshlrev_b32_e32 v170, 16, v218
	v_and_b32_e32 v171, 0xffff0000, v218
	v_lshlrev_b32_e32 v172, 16, v219
	v_and_b32_e32 v173, 0xffff0000, v219
	v_pk_add_f32 v[4:5], v[4:5], v[166:167]
	v_pk_add_f32 v[6:7], v[6:7], v[168:169]
	v_pk_add_f32 v[0:1], v[0:1], v[170:171]
	v_pk_add_f32 v[2:3], v[2:3], v[172:173]
	v_cvt_pk_bf16_f32 v178, v4, v5
	v_cvt_pk_bf16_f32 v179, v6, v7
	v_cvt_pk_bf16_f32 v180, v0, v1
	v_cvt_pk_bf16_f32 v181, v2, v3
	v_pk_fma_f32 v[182:183], v[4:5], v[4:5], v[182:183]
	v_pk_fma_f32 v[182:183], v[6:7], v[6:7], v[182:183]
	v_pk_fma_f32 v[182:183], v[0:1], v[0:1], v[182:183]
	v_pk_fma_f32 v[182:183], v[2:3], v[2:3], v[182:183]
	global_store_dwordx4 v[186:187], v[178:181], off offset:256
	v_add_f32_e32 v184, v182, v183
	v_mov_b32_e32 v185, v184
	s_nop 1
	v_permlane16_swap_b32_e32 v185, v184
	v_add_f32_e32 v184, v184, v185
	v_mov_b32_e32 v185, v184
	s_nop 1
	v_permlane32_swap_b32_e32 v185, v184
	v_add_f32_e32 v184, v184, v185
	s_and_saveexec_b64 s[36:37], s[4:5]
	global_store_dword v[236:237], v184, off offset:3072
	s_or_b64 exec, exec, s[36:37]
	s_and_b64 vcc, exec, s[6:7]
	s_mov_b64 s[6:7], -1
	s_cbranch_vccnz .LBB0_1721
	s_andn2_b64 vcc, exec, s[10:11]
	s_cbranch_vccnz .LBB0_1720
	s_nop 0
	s_branch .LBB0_1720

.LBB0_2004:
	v_lshl_add_u32 v148, s36, 8, v150
	v_ashrrev_i32_e32 v149, 31, v148
	v_lshl_or_b32 v146, s0, 8, v152
	v_lshlrev_b64 v[158:159], 11, v[148:149]
	v_ashrrev_i32_e32 v147, 31, v146
	v_lshl_add_u64 v[158:159], s[14:15], 0, v[158:159]
	v_lshl_add_u64 v[162:163], v[146:147], 1, v[158:159]
	v_mov_b32_e32 v232, v162
	v_mov_b32_e32 v233, v163
	global_load_dwordx4 v[188:191], v[232:233], off
	global_load_dwordx4 v[192:195], v[232:233], off offset:256
	s_mov_b64 s[100:101], 0x8000
	v_lshl_add_u64 v[230:231], v[232:233], 0, s[100:101]
	global_load_dwordx4 v[196:199], v[230:231], off
	global_load_dwordx4 v[200:203], v[230:231], off offset:256
	s_mov_b64 s[100:101], 0x10000
	v_lshl_add_u64 v[230:231], v[232:233], 0, s[100:101]
	global_load_dwordx4 v[204:207], v[230:231], off
	global_load_dwordx4 v[208:211], v[230:231], off offset:256
	s_mov_b64 s[100:101], 0x18000
	v_lshl_add_u64 v[230:231], v[232:233], 0, s[100:101]
	global_load_dwordx4 v[212:215], v[230:231], off
	global_load_dwordx4 v[216:219], v[230:231], off offset:256
	s_lshl_b32 s36, s0, 2
	s_ashr_i32 s37, s36, 31
	v_lshlrev_b64 v[234:235], 6, v[148:149]
	v_lshl_add_u64 v[234:235], s[18:19], 0, v[234:235]
	v_lshl_add_u64 v[234:235], s[36:37], 2, v[234:235]
	s_lshl_b32 s100, s50, 2
	s_mov_b32 s101, 0
	v_lshl_add_u64 v[234:235], v[234:235], 0, s[100:101]
	s_mov_b64 s[100:101], 0x2000
	v_lshl_add_u64 v[236:237], v[234:235], 0, s[100:101]
	s_waitcnt vmcnt(7)
	v_lshlrev_b32_e32 v166, 16, v188
	v_and_b32_e32 v167, 0xffff0000, v188
	v_lshlrev_b32_e32 v168, 16, v189
	v_and_b32_e32 v169, 0xffff0000, v189
	v_lshlrev_b32_e32 v170, 16, v190
	v_and_b32_e32 v171, 0xffff0000, v190
	v_lshlrev_b32_e32 v172, 16, v191
	v_and_b32_e32 v173, 0xffff0000, v191
	v_pk_add_f32 v[124:125], v[124:125], v[166:167]
	v_pk_add_f32 v[126:127], v[126:127], v[168:169]
	v_pk_add_f32 v[120:121], v[120:121], v[170:171]
	v_pk_add_f32 v[122:123], v[122:123], v[172:173]
	v_cvt_pk_bf16_f32 v174, v124, v125
	v_cvt_pk_bf16_f32 v175, v126, v127
	v_cvt_pk_bf16_f32 v176, v120, v121
	v_cvt_pk_bf16_f32 v177, v122, v123
	v_pk_mul_f32 v[182:183], v[124:125], v[124:125]
	v_pk_fma_f32 v[182:183], v[126:127], v[126:127], v[182:183]
	v_pk_fma_f32 v[182:183], v[120:121], v[120:121], v[182:183]
	v_pk_fma_f32 v[182:183], v[122:123], v[122:123], v[182:183]
	global_store_dwordx4 v[232:233], v[174:177], off
	s_waitcnt vmcnt(7)
	v_lshlrev_b32_e32 v166, 16, v192
	v_and_b32_e32 v167, 0xffff0000, v192
	v_lshlrev_b32_e32 v168, 16, v193
	v_and_b32_e32 v169, 0xffff0000, v193
	v_lshlrev_b32_e32 v170, 16, v194
	v_and_b32_e32 v171, 0xffff0000, v194
	v_lshlrev_b32_e32 v172, 16, v195
	v_and_b32_e32 v173, 0xffff0000, v195
	v_pk_add_f32 v[116:117], v[116:117], v[166:167]
	v_pk_add_f32 v[118:119], v[118:119], v[168:169]
	v_pk_add_f32 v[112:113], v[112:113], v[170:171]
	v_pk_add_f32 v[114:115], v[114:115], v[172:173]
	v_cvt_pk_bf16_f32 v178, v116, v117
	v_cvt_pk_bf16_f32 v179, v118, v119
	v_cvt_pk_bf16_f32 v180, v112, v113
	v_cvt_pk_bf16_f32 v181, v114, v115
	v_pk_fma_f32 v[182:183], v[116:117], v[116:117], v[182:183]
	v_pk_fma_f32 v[182:183], v[118:119], v[118:119], v[182:183]
	v_pk_fma_f32 v[182:183], v[112:113], v[112:113], v[182:183]
	v_pk_fma_f32 v[182:183], v[114:115], v[114:115], v[182:183]
	global_store_dwordx4 v[232:233], v[178:181], off offset:256
	v_add_f32_e32 v184, v182, v183
	v_mov_b32_e32 v185, v184
	s_nop 1
	v_permlane16_swap_b32_e32 v185, v184
	v_add_f32_e32 v184, v184, v185
	v_mov_b32_e32 v185, v184
	s_nop 1
	v_permlane32_swap_b32_e32 v185, v184
	v_add_f32_e32 v184, v184, v185
	s_and_saveexec_b64 s[38:39], s[4:5]
	global_store_dword v[234:235], v184, off
	s_or_b64 exec, exec, s[38:39]
	s_mov_b64 s[100:101], 0x40000
	v_lshl_add_u64 v[230:231], v[232:233], 0, s[100:101]
	global_load_dwordx4 v[188:191], v[230:231], off
	global_load_dwordx4 v[192:195], v[230:231], off offset:256
	s_mov_b64 s[100:101], 0x8000
	v_lshl_add_u64 v[186:187], v[232:233], 0, s[100:101]
	s_waitcnt vmcnt(10)
	v_lshlrev_b32_e32 v166, 16, v196
	v_and_b32_e32 v167, 0xffff0000, v196
	v_lshlrev_b32_e32 v168, 16, v197
	v_and_b32_e32 v169, 0xffff0000, v197
	v_lshlrev_b32_e32 v170, 16, v198
	v_and_b32_e32 v171, 0xffff0000, v198
	v_lshlrev_b32_e32 v172, 16, v199
	v_and_b32_e32 v173, 0xffff0000, v199
	v_pk_add_f32 v[108:109], v[108:109], v[166:167]
	v_pk_add_f32 v[110:111], v[110:111], v[168:169]
	v_pk_add_f32 v[104:105], v[104:105], v[170:171]
	v_pk_add_f32 v[106:107], v[106:107], v[172:173]
	v_cvt_pk_bf16_f32 v174, v108, v109
	v_cvt_pk_bf16_f32 v175, v110, v111
	v_cvt_pk_bf16_f32 v176, v104, v105
	v_cvt_pk_bf16_f32 v177, v106, v107
	v_pk_mul_f32 v[182:183], v[108:109], v[108:109]
	v_pk_fma_f32 v[182:183], v[110:111], v[110:111], v[182:183]
	v_pk_fma_f32 v[182:183], v[104:105], v[104:105], v[182:183]
	v_pk_fma_f32 v[182:183], v[106:107], v[106:107], v[182:183]
	global_store_dwordx4 v[186:187], v[174:177], off
	s_waitcnt vmcnt(10)
	v_lshlrev_b32_e32 v166, 16, v200
	v_and_b32_e32 v167, 0xffff0000, v200
	v_lshlrev_b32_e32 v168, 16, v201
	v_and_b32_e32 v169, 0xffff0000, v201
	v_lshlrev_b32_e32 v170, 16, v202
	v_and_b32_e32 v171, 0xffff0000, v202
	v_lshlrev_b32_e32 v172, 16, v203
	v_and_b32_e32 v173, 0xffff0000, v203
	v_pk_add_f32 v[100:101], v[100:101], v[166:167]
	v_pk_add_f32 v[102:103], v[102:103], v[168:169]
	v_pk_add_f32 v[96:97], v[96:97], v[170:171]
	v_pk_add_f32 v[98:99], v[98:99], v[172:173]
	v_cvt_pk_bf16_f32 v178, v100, v101
	v_cvt_pk_bf16_f32 v179, v102, v103
	v_cvt_pk_bf16_f32 v180, v96, v97
	v_cvt_pk_bf16_f32 v181, v98, v99
	v_pk_fma_f32 v[182:183], v[100:101], v[100:101], v[182:183]
	v_pk_fma_f32 v[182:183], v[102:103], v[102:103], v[182:183]
	v_pk_fma_f32 v[182:183], v[96:97], v[96:97], v[182:183]
	v_pk_fma_f32 v[182:183], v[98:99], v[98:99], v[182:183]
	global_store_dwordx4 v[186:187], v[178:181], off offset:256
	v_add_f32_e32 v184, v182, v183
	v_mov_b32_e32 v185, v184
	s_nop 1
	v_permlane16_swap_b32_e32 v185, v184
	v_add_f32_e32 v184, v184, v185
	v_mov_b32_e32 v185, v184
	s_nop 1
	v_permlane32_swap_b32_e32 v185, v184
	v_add_f32_e32 v184, v184, v185
	s_and_saveexec_b64 s[38:39], s[4:5]
	global_store_dword v[234:235], v184, off offset:1024
	s_or_b64 exec, exec, s[38:39]
	s_mov_b64 s[100:101], 0x48000
	v_lshl_add_u64 v[230:231], v[232:233], 0, s[100:101]
	global_load_dwordx4 v[196:199], v[230:231], off
	global_load_dwordx4 v[200:203], v[230:231], off offset:256
	s_mov_b64 s[100:101], 0x10000
	v_lshl_add_u64 v[186:187], v[232:233], 0, s[100:101]
	s_waitcnt vmcnt(13)
	v_lshlrev_b32_e32 v166, 16, v204
	v_and_b32_e32 v167, 0xffff0000, v204
	v_lshlrev_b32_e32 v168, 16, v205
	v_and_b32_e32 v169, 0xffff0000, v205
	v_lshlrev_b32_e32 v170, 16, v206
	v_and_b32_e32 v171, 0xffff0000, v206
	v_lshlrev_b32_e32 v172, 16, v207
	v_and_b32_e32 v173, 0xffff0000, v207
	v_pk_add_f32 v[92:93], v[92:93], v[166:167]
	v_pk_add_f32 v[94:95], v[94:95], v[168:169]
	v_pk_add_f32 v[88:89], v[88:89], v[170:171]
	v_pk_add_f32 v[90:91], v[90:91], v[172:173]
	v_cvt_pk_bf16_f32 v174, v92, v93
	v_cvt_pk_bf16_f32 v175, v94, v95
	v_cvt_pk_bf16_f32 v176, v88, v89
	v_cvt_pk_bf16_f32 v177, v90, v91
	v_pk_mul_f32 v[182:183], v[92:93], v[92:93]
	v_pk_fma_f32 v[182:183], v[94:95], v[94:95], v[182:183]
	v_pk_fma_f32 v[182:183], v[88:89], v[88:89], v[182:183]
	v_pk_fma_f32 v[182:183], v[90:91], v[90:91], v[182:183]
	global_store_dwordx4 v[186:187], v[174:177], off
	s_waitcnt vmcnt(13)
	v_lshlrev_b32_e32 v166, 16, v208
	v_and_b32_e32 v167, 0xffff0000, v208
	v_lshlrev_b32_e32 v168, 16, v209
	v_and_b32_e32 v169, 0xffff0000, v209
	v_lshlrev_b32_e32 v170, 16, v210
	v_and_b32_e32 v171, 0xffff0000, v210
	v_lshlrev_b32_e32 v172, 16, v211
	v_and_b32_e32 v173, 0xffff0000, v211
	v_pk_add_f32 v[84:85], v[84:85], v[166:167]
	v_pk_add_f32 v[86:87], v[86:87], v[168:169]
	v_pk_add_f32 v[80:81], v[80:81], v[170:171]
	v_pk_add_f32 v[82:83], v[82:83], v[172:173]
	v_cvt_pk_bf16_f32 v178, v84, v85
	v_cvt_pk_bf16_f32 v179, v86, v87
	v_cvt_pk_bf16_f32 v180, v80, v81
	v_cvt_pk_bf16_f32 v181, v82, v83
	v_pk_fma_f32 v[182:183], v[84:85], v[84:85], v[182:183]
	v_pk_fma_f32 v[182:183], v[86:87], v[86:87], v[182:183]
	v_pk_fma_f32 v[182:183], v[80:81], v[80:81], v[182:183]
	v_pk_fma_f32 v[182:183], v[82:83], v[82:83], v[182:183]
	global_store_dwordx4 v[186:187], v[178:181], off offset:256
	v_add_f32_e32 v184, v182, v183
	v_mov_b32_e32 v185, v184
	s_nop 1
	v_permlane16_swap_b32_e32 v185, v184
	v_add_f32_e32 v184, v184, v185
	v_mov_b32_e32 v185, v184
	s_nop 1
	v_permlane32_swap_b32_e32 v185, v184
	v_add_f32_e32 v184, v184, v185
	s_and_saveexec_b64 s[38:39], s[4:5]
	global_store_dword v[234:235], v184, off offset:2048
	s_or_b64 exec, exec, s[38:39]
	s_mov_b64 s[100:101], 0x50000
	v_lshl_add_u64 v[230:231], v[232:233], 0, s[100:101]
	global_load_dwordx4 v[204:207], v[230:231], off
	global_load_dwordx4 v[208:211], v[230:231], off offset:256
	s_mov_b64 s[100:101], 0x18000
	v_lshl_add_u64 v[186:187], v[232:233], 0, s[100:101]
	s_waitcnt vmcnt(16)
	v_lshlrev_b32_e32 v166, 16, v212
	v_and_b32_e32 v167, 0xffff0000, v212
	v_lshlrev_b32_e32 v168, 16, v213
	v_and_b32_e32 v169, 0xffff0000, v213
	v_lshlrev_b32_e32 v170, 16, v214
	v_and_b32_e32 v171, 0xffff0000, v214
	v_lshlrev_b32_e32 v172, 16, v215
	v_and_b32_e32 v173, 0xffff0000, v215
	v_pk_add_f32 v[76:77], v[76:77], v[166:167]
	v_pk_add_f32 v[78:79], v[78:79], v[168:169]
	v_pk_add_f32 v[72:73], v[72:73], v[170:171]
	v_pk_add_f32 v[74:75], v[74:75], v[172:173]
	v_cvt_pk_bf16_f32 v174, v76, v77
	v_cvt_pk_bf16_f32 v175, v78, v79
	v_cvt_pk_bf16_f32 v176, v72, v73
	v_cvt_pk_bf16_f32 v177, v74, v75
	v_pk_mul_f32 v[182:183], v[76:77], v[76:77]
	v_pk_fma_f32 v[182:183], v[78:79], v[78:79], v[182:183]
	v_pk_fma_f32 v[182:183], v[72:73], v[72:73], v[182:183]
	v_pk_fma_f32 v[182:183], v[74:75], v[74:75], v[182:183]
	global_store_dwordx4 v[186:187], v[174:177], off
	s_waitcnt vmcnt(16)
	v_lshlrev_b32_e32 v166, 16, v216
	v_and_b32_e32 v167, 0xffff0000, v216
	v_lshlrev_b32_e32 v168, 16, v217
	v_and_b32_e32 v169, 0xffff0000, v217
	v_lshlrev_b32_e32 v170, 16, v218
	v_and_b32_e32 v171, 0xffff0000, v218
	v_lshlrev_b32_e32 v172, 16, v219
	v_and_b32_e32 v173, 0xffff0000, v219
	v_pk_add_f32 v[68:69], v[68:69], v[166:167]
	v_pk_add_f32 v[70:71], v[70:71], v[168:169]
	v_pk_add_f32 v[64:65], v[64:65], v[170:171]
	v_pk_add_f32 v[66:67], v[66:67], v[172:173]
	v_cvt_pk_bf16_f32 v178, v68, v69
	v_cvt_pk_bf16_f32 v179, v70, v71
	v_cvt_pk_bf16_f32 v180, v64, v65
	v_cvt_pk_bf16_f32 v181, v66, v67
	v_pk_fma_f32 v[182:183], v[68:69], v[68:69], v[182:183]
	v_pk_fma_f32 v[182:183], v[70:71], v[70:71], v[182:183]
	v_pk_fma_f32 v[182:183], v[64:65], v[64:65], v[182:183]
	v_pk_fma_f32 v[182:183], v[66:67], v[66:67], v[182:183]
	global_store_dwordx4 v[186:187], v[178:181], off offset:256
	v_add_f32_e32 v184, v182, v183
	v_mov_b32_e32 v185, v184
	s_nop 1
	v_permlane16_swap_b32_e32 v185, v184
	v_add_f32_e32 v184, v184, v185
	v_mov_b32_e32 v185, v184
	s_nop 1
	v_permlane32_swap_b32_e32 v185, v184
	v_add_f32_e32 v184, v184, v185
	s_and_saveexec_b64 s[38:39], s[4:5]
	global_store_dword v[234:235], v184, off offset:3072
	s_or_b64 exec, exec, s[38:39]
	s_mov_b64 s[100:101], 0x58000
	v_lshl_add_u64 v[230:231], v[232:233], 0, s[100:101]
	global_load_dwordx4 v[212:215], v[230:231], off
	global_load_dwordx4 v[216:219], v[230:231], off offset:256
	s_mov_b64 s[100:101], 0x40000
	v_lshl_add_u64 v[186:187], v[232:233], 0, s[100:101]
	s_waitcnt vmcnt(16)
	v_lshlrev_b32_e32 v166, 16, v188
	v_and_b32_e32 v167, 0xffff0000, v188
	v_lshlrev_b32_e32 v168, 16, v189
	v_and_b32_e32 v169, 0xffff0000, v189
	v_lshlrev_b32_e32 v170, 16, v190
	v_and_b32_e32 v171, 0xffff0000, v190
	v_lshlrev_b32_e32 v172, 16, v191
	v_and_b32_e32 v173, 0xffff0000, v191
	v_pk_add_f32 v[60:61], v[60:61], v[166:167]
	v_pk_add_f32 v[62:63], v[62:63], v[168:169]
	v_pk_add_f32 v[56:57], v[56:57], v[170:171]
	v_pk_add_f32 v[58:59], v[58:59], v[172:173]
	v_cvt_pk_bf16_f32 v174, v60, v61
	v_cvt_pk_bf16_f32 v175, v62, v63
	v_cvt_pk_bf16_f32 v176, v56, v57
	v_cvt_pk_bf16_f32 v177, v58, v59
	v_pk_mul_f32 v[182:183], v[60:61], v[60:61]
	v_pk_fma_f32 v[182:183], v[62:63], v[62:63], v[182:183]
	v_pk_fma_f32 v[182:183], v[56:57], v[56:57], v[182:183]
	v_pk_fma_f32 v[182:183], v[58:59], v[58:59], v[182:183]
	global_store_dwordx4 v[186:187], v[174:177], off
	s_waitcnt vmcnt(16)
	v_lshlrev_b32_e32 v166, 16, v192
	v_and_b32_e32 v167, 0xffff0000, v192
	v_lshlrev_b32_e32 v168, 16, v193
	v_and_b32_e32 v169, 0xffff0000, v193
	v_lshlrev_b32_e32 v170, 16, v194
	v_and_b32_e32 v171, 0xffff0000, v194
	v_lshlrev_b32_e32 v172, 16, v195
	v_and_b32_e32 v173, 0xffff0000, v195
	v_pk_add_f32 v[52:53], v[52:53], v[166:167]
	v_pk_add_f32 v[54:55], v[54:55], v[168:169]
	v_pk_add_f32 v[48:49], v[48:49], v[170:171]
	v_pk_add_f32 v[50:51], v[50:51], v[172:173]
	v_cvt_pk_bf16_f32 v178, v52, v53
	v_cvt_pk_bf16_f32 v179, v54, v55
	v_cvt_pk_bf16_f32 v180, v48, v49
	v_cvt_pk_bf16_f32 v181, v50, v51
	v_pk_fma_f32 v[182:183], v[52:53], v[52:53], v[182:183]
	v_pk_fma_f32 v[182:183], v[54:55], v[54:55], v[182:183]
	v_pk_fma_f32 v[182:183], v[48:49], v[48:49], v[182:183]
	v_pk_fma_f32 v[182:183], v[50:51], v[50:51], v[182:183]
	global_store_dwordx4 v[186:187], v[178:181], off offset:256
	v_add_f32_e32 v184, v182, v183
	v_mov_b32_e32 v185, v184
	s_nop 1
	v_permlane16_swap_b32_e32 v185, v184
	v_add_f32_e32 v184, v184, v185
	v_mov_b32_e32 v185, v184
	s_nop 1
	v_permlane32_swap_b32_e32 v185, v184
	v_add_f32_e32 v184, v184, v185
	s_and_saveexec_b64 s[38:39], s[4:5]
	global_store_dword v[236:237], v184, off
	s_or_b64 exec, exec, s[38:39]
	s_mov_b64 s[100:101], 0x48000
	v_lshl_add_u64 v[186:187], v[232:233], 0, s[100:101]
	s_waitcnt vmcnt(14)
	v_lshlrev_b32_e32 v166, 16, v196
	v_and_b32_e32 v167, 0xffff0000, v196
	v_lshlrev_b32_e32 v168, 16, v197
	v_and_b32_e32 v169, 0xffff0000, v197
	v_lshlrev_b32_e32 v170, 16, v198
	v_and_b32_e32 v171, 0xffff0000, v198
	v_lshlrev_b32_e32 v172, 16, v199
	v_and_b32_e32 v173, 0xffff0000, v199
	v_pk_add_f32 v[44:45], v[44:45], v[166:167]
	v_pk_add_f32 v[46:47], v[46:47], v[168:169]
	v_pk_add_f32 v[40:41], v[40:41], v[170:171]
	v_pk_add_f32 v[42:43], v[42:43], v[172:173]
	v_cvt_pk_bf16_f32 v174, v44, v45
	v_cvt_pk_bf16_f32 v175, v46, v47
	v_cvt_pk_bf16_f32 v176, v40, v41
	v_cvt_pk_bf16_f32 v177, v42, v43
	v_pk_mul_f32 v[182:183], v[44:45], v[44:45]
	v_pk_fma_f32 v[182:183], v[46:47], v[46:47], v[182:183]
	v_pk_fma_f32 v[182:183], v[40:41], v[40:41], v[182:183]
	v_pk_fma_f32 v[182:183], v[42:43], v[42:43], v[182:183]
	global_store_dwordx4 v[186:187], v[174:177], off
	s_waitcnt vmcnt(14)
	v_lshlrev_b32_e32 v166, 16, v200
	v_and_b32_e32 v167, 0xffff0000, v200
	v_lshlrev_b32_e32 v168, 16, v201
	v_and_b32_e32 v169, 0xffff0000, v201
	v_lshlrev_b32_e32 v170, 16, v202
	v_and_b32_e32 v171, 0xffff0000, v202
	v_lshlrev_b32_e32 v172, 16, v203
	v_and_b32_e32 v173, 0xffff0000, v203
	v_pk_add_f32 v[36:37], v[36:37], v[166:167]
	v_pk_add_f32 v[38:39], v[38:39], v[168:169]
	v_pk_add_f32 v[32:33], v[32:33], v[170:171]
	v_pk_add_f32 v[34:35], v[34:35], v[172:173]
	v_cvt_pk_bf16_f32 v178, v36, v37
	v_cvt_pk_bf16_f32 v179, v38, v39
	v_cvt_pk_bf16_f32 v180, v32, v33
	v_cvt_pk_bf16_f32 v181, v34, v35
	v_pk_fma_f32 v[182:183], v[36:37], v[36:37], v[182:183]
	v_pk_fma_f32 v[182:183], v[38:39], v[38:39], v[182:183]
	v_pk_fma_f32 v[182:183], v[32:33], v[32:33], v[182:183]
	v_pk_fma_f32 v[182:183], v[34:35], v[34:35], v[182:183]
	global_store_dwordx4 v[186:187], v[178:181], off offset:256
	v_add_f32_e32 v184, v182, v183
	v_mov_b32_e32 v185, v184
	s_nop 1
	v_permlane16_swap_b32_e32 v185, v184
	v_add_f32_e32 v184, v184, v185
	v_mov_b32_e32 v185, v184
	s_nop 1
	v_permlane32_swap_b32_e32 v185, v184
	v_add_f32_e32 v184, v184, v185
	s_and_saveexec_b64 s[38:39], s[4:5]
	global_store_dword v[236:237], v184, off offset:1024
	s_or_b64 exec, exec, s[38:39]
	s_mov_b64 s[100:101], 0x50000
	v_lshl_add_u64 v[186:187], v[232:233], 0, s[100:101]
	s_waitcnt vmcnt(12)
	v_lshlrev_b32_e32 v166, 16, v204
	v_and_b32_e32 v167, 0xffff0000, v204
	v_lshlrev_b32_e32 v168, 16, v205
	v_and_b32_e32 v169, 0xffff0000, v205
	v_lshlrev_b32_e32 v170, 16, v206
	v_and_b32_e32 v171, 0xffff0000, v206
	v_lshlrev_b32_e32 v172, 16, v207
	v_and_b32_e32 v173, 0xffff0000, v207
	v_pk_add_f32 v[28:29], v[28:29], v[166:167]
	v_pk_add_f32 v[30:31], v[30:31], v[168:169]
	v_pk_add_f32 v[24:25], v[24:25], v[170:171]
	v_pk_add_f32 v[26:27], v[26:27], v[172:173]
	v_cvt_pk_bf16_f32 v174, v28, v29
	v_cvt_pk_bf16_f32 v175, v30, v31
	v_cvt_pk_bf16_f32 v176, v24, v25
	v_cvt_pk_bf16_f32 v177, v26, v27
	v_pk_mul_f32 v[182:183], v[28:29], v[28:29]
	v_pk_fma_f32 v[182:183], v[30:31], v[30:31], v[182:183]
	v_pk_fma_f32 v[182:183], v[24:25], v[24:25], v[182:183]
	v_pk_fma_f32 v[182:183], v[26:27], v[26:27], v[182:183]
	global_store_dwordx4 v[186:187], v[174:177], off
	s_waitcnt vmcnt(12)
	v_lshlrev_b32_e32 v166, 16, v208
	v_and_b32_e32 v167, 0xffff0000, v208
	v_lshlrev_b32_e32 v168, 16, v209
	v_and_b32_e32 v169, 0xffff0000, v209
	v_lshlrev_b32_e32 v170, 16, v210
	v_and_b32_e32 v171, 0xffff0000, v210
	v_lshlrev_b32_e32 v172, 16, v211
	v_and_b32_e32 v173, 0xffff0000, v211
	v_pk_add_f32 v[20:21], v[20:21], v[166:167]
	v_pk_add_f32 v[22:23], v[22:23], v[168:169]
	v_pk_add_f32 v[16:17], v[16:17], v[170:171]
	v_pk_add_f32 v[18:19], v[18:19], v[172:173]
	v_cvt_pk_bf16_f32 v178, v20, v21
	v_cvt_pk_bf16_f32 v179, v22, v23
	v_cvt_pk_bf16_f32 v180, v16, v17
	v_cvt_pk_bf16_f32 v181, v18, v19
	v_pk_fma_f32 v[182:183], v[20:21], v[20:21], v[182:183]
	v_pk_fma_f32 v[182:183], v[22:23], v[22:23], v[182:183]
	v_pk_fma_f32 v[182:183], v[16:17], v[16:17], v[182:183]
	v_pk_fma_f32 v[182:183], v[18:19], v[18:19], v[182:183]
	global_store_dwordx4 v[186:187], v[178:181], off offset:256
	v_add_f32_e32 v184, v182, v183
	v_mov_b32_e32 v185, v184
	s_nop 1
	v_permlane16_swap_b32_e32 v185, v184
	v_add_f32_e32 v184, v184, v185
	v_mov_b32_e32 v185, v184
	s_nop 1
	v_permlane32_swap_b32_e32 v185, v184
	v_add_f32_e32 v184, v184, v185
	s_and_saveexec_b64 s[38:39], s[4:5]
	global_store_dword v[236:237], v184, off offset:2048
	s_or_b64 exec, exec, s[38:39]
	s_mov_b64 s[100:101], 0x58000
	v_lshl_add_u64 v[186:187], v[232:233], 0, s[100:101]
	s_waitcnt vmcnt(10)
	v_lshlrev_b32_e32 v166, 16, v212
	v_and_b32_e32 v167, 0xffff0000, v212
	v_lshlrev_b32_e32 v168, 16, v213
	v_and_b32_e32 v169, 0xffff0000, v213
	v_lshlrev_b32_e32 v170, 16, v214
	v_and_b32_e32 v171, 0xffff0000, v214
	v_lshlrev_b32_e32 v172, 16, v215
	v_and_b32_e32 v173, 0xffff0000, v215
	v_pk_add_f32 v[12:13], v[12:13], v[166:167]
	v_pk_add_f32 v[14:15], v[14:15], v[168:169]
	v_pk_add_f32 v[8:9], v[8:9], v[170:171]
	v_pk_add_f32 v[10:11], v[10:11], v[172:173]
	v_cvt_pk_bf16_f32 v174, v12, v13
	v_cvt_pk_bf16_f32 v175, v14, v15
	v_cvt_pk_bf16_f32 v176, v8, v9
	v_cvt_pk_bf16_f32 v177, v10, v11
	v_pk_mul_f32 v[182:183], v[12:13], v[12:13]
	v_pk_fma_f32 v[182:183], v[14:15], v[14:15], v[182:183]
	v_pk_fma_f32 v[182:183], v[8:9], v[8:9], v[182:183]
	v_pk_fma_f32 v[182:183], v[10:11], v[10:11], v[182:183]
	global_store_dwordx4 v[186:187], v[174:177], off
	s_waitcnt vmcnt(10)
	v_lshlrev_b32_e32 v166, 16, v216
	v_and_b32_e32 v167, 0xffff0000, v216
	v_lshlrev_b32_e32 v168, 16, v217
	v_and_b32_e32 v169, 0xffff0000, v217
	v_lshlrev_b32_e32 v170, 16, v218
	v_and_b32_e32 v171, 0xffff0000, v218
	v_lshlrev_b32_e32 v172, 16, v219
	v_and_b32_e32 v173, 0xffff0000, v219
	v_pk_add_f32 v[4:5], v[4:5], v[166:167]
	v_pk_add_f32 v[6:7], v[6:7], v[168:169]
	v_pk_add_f32 v[0:1], v[0:1], v[170:171]
	v_pk_add_f32 v[2:3], v[2:3], v[172:173]
	v_cvt_pk_bf16_f32 v178, v4, v5
	v_cvt_pk_bf16_f32 v179, v6, v7
	v_cvt_pk_bf16_f32 v180, v0, v1
	v_cvt_pk_bf16_f32 v181, v2, v3
	v_pk_fma_f32 v[182:183], v[4:5], v[4:5], v[182:183]
	v_pk_fma_f32 v[182:183], v[6:7], v[6:7], v[182:183]
	v_pk_fma_f32 v[182:183], v[0:1], v[0:1], v[182:183]
	v_pk_fma_f32 v[182:183], v[2:3], v[2:3], v[182:183]
	global_store_dwordx4 v[186:187], v[178:181], off offset:256
	v_add_f32_e32 v184, v182, v183
	v_mov_b32_e32 v185, v184
	s_nop 1
	v_permlane16_swap_b32_e32 v185, v184
	v_add_f32_e32 v184, v184, v185
	v_mov_b32_e32 v185, v184
	s_nop 1
	v_permlane32_swap_b32_e32 v185, v184
	v_add_f32_e32 v184, v184, v185
	s_and_saveexec_b64 s[38:39], s[4:5]
	global_store_dword v[236:237], v184, off offset:3072
	s_or_b64 exec, exec, s[38:39]
	s_andn2_b64 vcc, exec, s[6:7]
	s_mov_b64 s[6:7], -1
	s_cbranch_vccnz .LBB0_1993
	s_andn2_b64 vcc, exec, s[8:9]
	s_cbranch_vccnz .LBB0_1992
	s_nop 0
	s_branch .LBB0_1992
